# static priority: waves 4-7 (role B) raised to 1 for the whole P8/P9 K-loop, per-slot s_setprio toggles removed
# speedup vs baseline: 1.0032x; 1.0032x over previous
;     __host__ __device__ bool next(int i, Unit& u) const { const int L = i * G + c; if (L >= n) return false; u.pm = L; u.pn = L >> 2; return true; }
; #define PG8_STAGE(bufoff, gbase, voff) do { _Pragma("unroll") for (int _i = 0; _i < 2; ++_i) \
;         __builtin_amdgcn_global_load_lds((const unsigned*)((const char*)(gbase) + (voff)[_i]), (PG8_LAS unsigned*)(lds + (bufoff) + ldsw + _i * 8192), 16, 0, 0); } while (0)
; #define PG8_LDA(dst, b, h) do { _Pragma("unroll") for (int m = 0; m < 4; ++m) _Pragma("unroll") for (int k = 0; k < 2; ++k) dst[m][k] = *(const PG8_LAS bf16x8*)(lds + PG8_SA(b, h) + aoff + m * 2048 + k * 1024); } while (0)
; #define PG8_LDB(dst, b, h) do { _Pragma("unroll") for (int n = 0; n < 2; ++n) _Pragma("unroll") for (int k = 0; k < 2; ++k) dst[n][k] = *(const PG8_LAS bf16x8*)(lds + PG8_SB(b, h) + boff + n * 2048 + k * 1024); } while (0)
; #define PG8_SCHED __builtin_amdgcn_sched_barrier(0)
; template <class Epi, class Sched, bool ALIGN_EPI>
; __device__ __forceinline__ void gemm_phase(PG8_LAS unsigned char* lds, const Gemm g, const Sched& S, const Epi& E) {
;     ...
;         const bool has_next = S.next(ui + 1, nxt);
;         const size_t tail_ = has_next ? 0 : tailoff; const char* nA = (has_next ? (const char*)g.A + (size_t)nxt.pm * tstepA : cA) + (has_next ? 0 : tailoffA); const char* nB = (has_next ? (const char*)g.Bt + (size_t)nxt.pn * tstepB : cB) + tail_;
;         for (int t = 0; t < nt; t += 2) {
;             if constexpr (Epi::MIDK) { if (t == (nt >> 1)) E.midk(acc, cur, wr, fr); }
;             const bool last = (t == nt - 2);
;             const char* a1 = cA + (size_t)(t + 1) * kstepA;
;             const char* a2 = last ? nA : cA + (size_t)(t + 2) * kstepA; const char* b2 = last ? nB : cB + (size_t)(t + 2) * kstep;
;             const char* a3 = a2 + kstepA; const char* b3 = b2 + kstep;
;             PG8_LDB(B0, 0, 0); PG8_LDB(B1, 0, 1); PG8_SCHED; PG8_LDA(At, 0, 0); PG8_STAGE(PG8_SA(1, 1), a1 + hstepA, voffA);
.LBB0_900:
	s_ashr_i32 s21, s20, 31
	s_lshl_b64 s[22:23], s[20:21], 20
	s_add_u32 s2, s68, s22
	s_addc_u32 s19, s69, s23
	s_and_b64 s[22:23], s[0:1], exec
	s_cselect_b32 s2, s2, s28
	s_cselect_b32 s19, s19, s29
	s_add_u32 s22, s2, s24
	s_addc_u32 s23, s19, s25
	s_ashr_i32 s19, s18, 31
	s_lshl_b64 s[34:35], s[18:19], 20
	s_add_u32 s2, s78, s34
	s_addc_u32 s19, s79, s35
	s_and_b64 s[34:35], s[0:1], exec
	s_cselect_b32 s2, s2, s30
	s_cselect_b32 s19, s19, s31
	s_add_u32 s24, s2, s24
	s_addc_u32 s25, s19, s25
	s_add_u32 s28, s28, 0x80080
	s_addc_u32 s29, s29, 0
	s_add_u32 s19, s30, 0x100
	s_addc_u32 s21, s31, 0
	s_mov_b32 s49, -2
	s_and_b32 s2, s3, 0xfff
	s_mov_b32 s49, 0
	s_cmp_lt_u32 s3, 0x1000
	s_cbranch_scc0 .Lp8k_B_init
	s_setprio 0
	s_mov_b64 s[50:51], s[24:25]
	s_cmp_eq_u32 s42, 1
	s_cbranch_scc1 .Lp8k_A_first
	s_add_u32 s28, s30, 0x100
	s_addc_u32 s29, s31, 0
	ds_read_b128 v[156:159], v153 offset:0
	ds_read_b128 v[160:163], v153 offset:1024
	s_branch .Lp8k_A_entry

; #define PG8_STAGE(bufoff, gbase, voff) do { _Pragma("unroll") for (int _i = 0; _i < 2; ++_i) \
;         __builtin_amdgcn_global_load_lds((const unsigned*)((const char*)(gbase) + (voff)[_i]), (PG8_LAS unsigned*)(lds + (bufoff) + ldsw + _i * 8192), 16, 0, 0); } while (0)
; #define PG8_LDA(dst, b, h) do { _Pragma("unroll") for (int m = 0; m < 4; ++m) _Pragma("unroll") for (int k = 0; k < 2; ++k) dst[m][k] = *(const PG8_LAS bf16x8*)(lds + PG8_SA(b, h) + aoff + m * 2048 + k * 1024); } while (0)
; #define PG8_LDB(dst, b, h) do { _Pragma("unroll") for (int n = 0; n < 2; ++n) _Pragma("unroll") for (int k = 0; k < 2; ++k) dst[n][k] = *(const PG8_LAS bf16x8*)(lds + PG8_SB(b, h) + boff + n * 2048 + k * 1024); } while (0)
; #define PG8_MMA(ai, bj, At, Bt) do { __builtin_amdgcn_s_setprio(1); _Pragma("unroll") for (int m = 0; m < 4; ++m) _Pragma("unroll") for (int n = 0; n < 2; ++n) _Pragma("unroll") for (int k = 0; k < 2; ++k) \
;         acc[ai][bj][m][n] = __builtin_amdgcn_mfma_f32_16x16x32_bf16(Bt[n][k], At[m][k], acc[ai][bj][m][n], 0, 0, 0); __builtin_amdgcn_s_setprio(0); } while (0)
; #define PG8_WAIT_V(n) asm volatile("s_waitcnt vmcnt(" #n ")" ::: "memory")
; template <class Epi, class Sched, bool ALIGN_EPI>
; __device__ __forceinline__ void gemm_phase(PG8_LAS unsigned char* lds, const Gemm g, const Sched& S, const Epi& E) {
;     ...
;             PG8_LDB(B0, 0, 0); PG8_LDB(B1, 0, 1); PG8_SCHED; PG8_LDA(At, 0, 0); PG8_STAGE(PG8_SA(1, 1), a1 + hstepA, voffA);
;             PG8_WAIT_V(8); PG8_WAIT_L(0); PG8_BAR; PG8_MMA(0, 0, At, B0); PG8_MMA(0, 1, At, B1); PG8_BAR; PG8_SCHED;
;             PG8_LDA(At, 0, 1); PG8_STAGE(PG8_SB(0, 0), b2, voffB); PG8_STAGE(PG8_SB(0, 1), b2 + hstepB, voffB); PG8_STAGE(PG8_SA(0, 0), a2, voffA);
;             PG8_WAIT_V(8); PG8_WAIT_L(0); PG8_BAR; PG8_MMA(1, 0, At, B0); PG8_MMA(1, 1, At, B1); PG8_BAR; PG8_SCHED;
;             PG8_LDB(B0, 1, 0); PG8_LDB(B1, 1, 1); PG8_SCHED; PG8_LDA(At, 1, 0); PG8_STAGE(PG8_SA(0, 1), a2 + hstepA, voffA);
;             PG8_WAIT_V(8); PG8_WAIT_L(0); PG8_BAR; PG8_MMA(0, 0, At, B0); PG8_MMA(0, 1, At, B1); PG8_BAR; PG8_SCHED;
;             PG8_LDA(At, 1, 1); PG8_STAGE(PG8_SB(1, 0), b3, voffB); PG8_STAGE(PG8_SB(1, 1), b3 + hstepB, voffB); PG8_STAGE(PG8_SA(1, 0), a3, voffA);
;             PG8_WAIT_V(8); PG8_WAIT_L(0); PG8_BAR; PG8_MMA(1, 0, At, B0); PG8_MMA(1, 1, At, B1); PG8_BAR; PG8_SCHED;
.Lp8k_A_entry:
	s_waitcnt vmcnt(8) lgkmcnt(0)
	s_barrier
	v_mfma_f32_16x16x32_bf16 v[126:129], v[156:159], v[190:193], 0
	v_mfma_f32_16x16x32_bf16 v[126:129], v[160:163], v[194:197], v[126:129]
	v_mfma_f32_16x16x32_bf16 v[122:125], v[168:171], v[194:197], 0
	v_mfma_f32_16x16x32_bf16 v[122:125], v[164:167], v[190:193], v[122:125]
	v_mfma_f32_16x16x32_bf16 v[118:121], v[174:177], v[190:193], 0
	v_mfma_f32_16x16x32_bf16 v[118:121], v[178:181], v[194:197], v[118:121]
	v_mfma_f32_16x16x32_bf16 v[114:117], v[186:189], v[194:197], 0
	v_mfma_f32_16x16x32_bf16 v[114:117], v[182:185], v[190:193], v[114:117]
	v_mfma_f32_16x16x32_bf16 v[98:101], v[182:185], v[198:201], 0
	v_mfma_f32_16x16x32_bf16 v[98:101], v[186:189], v[202:205], v[98:101]
	v_mfma_f32_16x16x32_bf16 v[102:105], v[178:181], v[202:205], 0
	v_mfma_f32_16x16x32_bf16 v[102:105], v[174:177], v[198:201], v[102:105]
	v_mfma_f32_16x16x32_bf16 v[106:109], v[164:167], v[198:201], 0
	v_mfma_f32_16x16x32_bf16 v[106:109], v[168:171], v[202:205], v[106:109]
	v_mfma_f32_16x16x32_bf16 v[110:113], v[160:163], v[202:205], 0
	v_mfma_f32_16x16x32_bf16 v[110:113], v[156:159], v[198:201], v[110:113]
	v_mfma_f32_16x16x32_bf16 v[94:97], v[156:159], v[206:209], 0
	v_mfma_f32_16x16x32_bf16 v[94:97], v[160:163], v[210:213], v[94:97]
	v_mfma_f32_16x16x32_bf16 v[90:93], v[168:171], v[210:213], 0
	v_mfma_f32_16x16x32_bf16 v[90:93], v[164:167], v[206:209], v[90:93]
	v_mfma_f32_16x16x32_bf16 v[86:89], v[174:177], v[206:209], 0
	v_mfma_f32_16x16x32_bf16 v[86:89], v[178:181], v[210:213], v[86:89]
	v_mfma_f32_16x16x32_bf16 v[82:85], v[186:189], v[210:213], 0
	v_mfma_f32_16x16x32_bf16 v[82:85], v[182:185], v[206:209], v[82:85]
	v_mfma_f32_16x16x32_bf16 v[66:69], v[182:185], v[214:217], 0
	v_mfma_f32_16x16x32_bf16 v[66:69], v[186:189], v[218:221], v[66:69]
	v_mfma_f32_16x16x32_bf16 v[70:73], v[178:181], v[218:221], 0
	v_mfma_f32_16x16x32_bf16 v[70:73], v[174:177], v[214:217], v[70:73]
	v_mfma_f32_16x16x32_bf16 v[74:77], v[164:167], v[214:217], 0
	v_mfma_f32_16x16x32_bf16 v[74:77], v[168:171], v[218:221], v[74:77]
	v_mfma_f32_16x16x32_bf16 v[78:81], v[160:163], v[218:221], 0
	v_mfma_f32_16x16x32_bf16 v[78:81], v[156:159], v[214:217], v[78:81]
	v_mfma_f32_16x16x32_bf16 v[62:65], v[156:159], v[222:225], 0
	v_mfma_f32_16x16x32_bf16 v[62:65], v[160:163], v[226:229], v[62:65]
	v_mfma_f32_16x16x32_bf16 v[58:61], v[168:171], v[226:229], 0
	v_mfma_f32_16x16x32_bf16 v[58:61], v[164:167], v[222:225], v[58:61]
	v_mfma_f32_16x16x32_bf16 v[54:57], v[174:177], v[222:225], 0
	v_mfma_f32_16x16x32_bf16 v[54:57], v[178:181], v[226:229], v[54:57]
	v_mfma_f32_16x16x32_bf16 v[50:53], v[186:189], v[226:229], 0
	v_mfma_f32_16x16x32_bf16 v[50:53], v[182:185], v[222:225], v[50:53]
	v_mfma_f32_16x16x32_bf16 v[34:37], v[182:185], v[230:233], 0
	v_mfma_f32_16x16x32_bf16 v[34:37], v[186:189], v[234:237], v[34:37]
	v_mfma_f32_16x16x32_bf16 v[38:41], v[178:181], v[234:237], 0
	v_mfma_f32_16x16x32_bf16 v[38:41], v[174:177], v[230:233], v[38:41]
	v_mfma_f32_16x16x32_bf16 v[42:45], v[164:167], v[230:233], 0
	v_mfma_f32_16x16x32_bf16 v[42:45], v[168:171], v[234:237], v[42:45]
	v_mfma_f32_16x16x32_bf16 v[46:49], v[160:163], v[234:237], 0
	v_mfma_f32_16x16x32_bf16 v[46:49], v[156:159], v[230:233], v[46:49]
	v_mfma_f32_16x16x32_bf16 v[30:33], v[156:159], v[238:241], 0
	v_mfma_f32_16x16x32_bf16 v[30:33], v[160:163], v[242:245], v[30:33]
	v_mfma_f32_16x16x32_bf16 v[26:29], v[168:171], v[242:245], 0
	v_mfma_f32_16x16x32_bf16 v[26:29], v[164:167], v[238:241], v[26:29]
	v_mfma_f32_16x16x32_bf16 v[22:25], v[174:177], v[238:241], 0
	v_mfma_f32_16x16x32_bf16 v[22:25], v[178:181], v[242:245], v[22:25]
	v_mfma_f32_16x16x32_bf16 v[18:21], v[186:189], v[242:245], 0
	v_mfma_f32_16x16x32_bf16 v[18:21], v[182:185], v[238:241], v[18:21]
	v_mfma_f32_16x16x32_bf16 v[2:5], v[182:185], v[246:249], 0
	v_mfma_f32_16x16x32_bf16 v[2:5], v[186:189], v[250:253], v[2:5]
	v_mfma_f32_16x16x32_bf16 v[6:9], v[178:181], v[250:253], 0
	v_mfma_f32_16x16x32_bf16 v[6:9], v[174:177], v[246:249], v[6:9]
	v_mfma_f32_16x16x32_bf16 v[10:13], v[164:167], v[246:249], 0
	v_mfma_f32_16x16x32_bf16 v[10:13], v[168:171], v[250:253], v[10:13]
	v_mfma_f32_16x16x32_bf16 v[14:17], v[160:163], v[250:253], 0
	v_mfma_f32_16x16x32_bf16 v[14:17], v[156:159], v[246:249], v[14:17]
	s_waitcnt vmcnt(0)
	s_barrier
	ds_read_b128 v[190:193], v155 offset:32768
	ds_read_b128 v[194:197], v155 offset:33792
	ds_read_b128 v[198:201], v155 offset:34816
	s_cmp_eq_u32 s49, 15
	s_cselect_b32 s28, s50, s28
	s_cselect_b32 s29, s51, s29
	s_add_i32 m0, s2, 0x10000
	s_nop 0
	global_load_lds_dwordx4 v134, s[28:29]
	ds_read_b128 v[202:205], v155 offset:35840
	ds_read_b128 v[206:209], v155 offset:36864
	ds_read_b128 v[210:213], v155 offset:37888
	s_add_i32 m0, s2, 0x12000
	s_nop 0
	global_load_lds_dwordx4 v130, s[28:29]
	ds_read_b128 v[214:217], v155 offset:38912
	ds_read_b128 v[218:221], v155 offset:39936
	ds_read_b128 v[156:159], v153 offset:32768
	s_add_u32 s30, s28, 0x20000
	s_addc_u32 s31, s29, 0
	s_add_i32 m0, s2, 0x11000
	s_nop 0
	global_load_lds_dwordx4 v134, s[30:31]
	ds_read_b128 v[160:163], v153 offset:33792
	ds_read_b128 v[164:167], v153 offset:34816
	ds_read_b128 v[168:171], v153 offset:35840
	s_add_i32 m0, s2, 0x13000
	s_nop 0
	global_load_lds_dwordx4 v130, s[30:31]
	ds_read_b128 v[174:177], v153 offset:49152
	ds_read_b128 v[178:181], v153 offset:50176
	ds_read_b128 v[182:185], v153 offset:51200
	s_add_u32 s30, s28, 0x80000
	s_addc_u32 s31, s29, 0
	s_add_i32 m0, s2, 0x14000
	s_nop 0
	global_load_lds_dwordx4 v134, s[30:31]
	ds_read_b128 v[186:189], v153 offset:52224
	ds_read_b128 v[222:225], v155 offset:49152
	ds_read_b128 v[226:229], v155 offset:50176
	s_add_i32 m0, s2, 0x16000
	s_nop 0
	global_load_lds_dwordx4 v130, s[30:31]
	ds_read_b128 v[230:233], v155 offset:51200
	ds_read_b128 v[234:237], v155 offset:52224
	ds_read_b128 v[238:241], v155 offset:53248
	s_add_u32 s30, s28, 0xa0000
	s_addc_u32 s31, s29, 0
	s_add_i32 m0, s2, 0x15000
	s_nop 0
	global_load_lds_dwordx4 v134, s[30:31]
	ds_read_b128 v[242:245], v155 offset:54272
	ds_read_b128 v[246:249], v155 offset:55296
	ds_read_b128 v[250:253], v155 offset:56320
	s_add_i32 m0, s2, 0x17000
	s_nop 0
	global_load_lds_dwordx4 v130, s[30:31]
	s_add_u32 s28, s28, 0x80
	s_addc_u32 s29, s29, 0
	s_waitcnt vmcnt(8) lgkmcnt(0)
	s_barrier
; #define PG8_STAGE(bufoff, gbase, voff) do { _Pragma("unroll") for (int _i = 0; _i < 2; ++_i) \
;         __builtin_amdgcn_global_load_lds((const unsigned*)((const char*)(gbase) + (voff)[_i]), (PG8_LAS unsigned*)(lds + (bufoff) + ldsw + _i * 8192), 16, 0, 0); } while (0)
; #define PG8_LDA(dst, b, h) do { _Pragma("unroll") for (int m = 0; m < 4; ++m) _Pragma("unroll") for (int k = 0; k < 2; ++k) dst[m][k] = *(const PG8_LAS bf16x8*)(lds + PG8_SA(b, h) + aoff + m * 2048 + k * 1024); } while (0)
; #define PG8_LDB(dst, b, h) do { _Pragma("unroll") for (int n = 0; n < 2; ++n) _Pragma("unroll") for (int k = 0; k < 2; ++k) dst[n][k] = *(const PG8_LAS bf16x8*)(lds + PG8_SB(b, h) + boff + n * 2048 + k * 1024); } while (0)
; #define PG8_MMA(ai, bj, At, Bt) do { __builtin_amdgcn_s_setprio(1); _Pragma("unroll") for (int m = 0; m < 4; ++m) _Pragma("unroll") for (int n = 0; n < 2; ++n) _Pragma("unroll") for (int k = 0; k < 2; ++k) \
;         acc[ai][bj][m][n] = __builtin_amdgcn_mfma_f32_16x16x32_bf16(Bt[n][k], At[m][k], acc[ai][bj][m][n], 0, 0, 0); __builtin_amdgcn_s_setprio(0); } while (0)
; #define PG8_WAIT_V(n) asm volatile("s_waitcnt vmcnt(" #n ")" ::: "memory")
; #define PG8_WAIT_L(n) asm volatile("s_waitcnt lgkmcnt(" #n ")" ::: "memory")
; #define PG8_BAR __builtin_amdgcn_s_barrier()
; #define PG8_SCHED __builtin_amdgcn_sched_barrier(0)
; template <class Epi, class Sched, bool ALIGN_EPI>
; __device__ __forceinline__ void gemm_phase(PG8_LAS unsigned char* lds, const Gemm g, const Sched& S, const Epi& E) {
;     ...
;             PG8_LDB(B0, 1, 0); PG8_LDB(B1, 1, 1); PG8_SCHED; PG8_LDA(At, 1, 0); PG8_STAGE(PG8_SA(0, 1), a2 + hstepA, voffA);
;             PG8_WAIT_V(8); PG8_WAIT_L(0); PG8_BAR; PG8_MMA(0, 0, At, B0); PG8_MMA(0, 1, At, B1); PG8_BAR; PG8_SCHED;
;             PG8_LDA(At, 1, 1); PG8_STAGE(PG8_SB(1, 0), b3, voffB); PG8_STAGE(PG8_SB(1, 1), b3 + hstepB, voffB); PG8_STAGE(PG8_SA(1, 0), a3, voffA);
;             PG8_WAIT_V(8); PG8_WAIT_L(0); PG8_BAR; PG8_MMA(1, 0, At, B0); PG8_MMA(1, 1, At, B1); PG8_BAR; PG8_SCHED;
	v_mfma_f32_16x16x32_bf16 v[126:129], v[156:159], v[190:193], v[126:129]
	v_mfma_f32_16x16x32_bf16 v[126:129], v[160:163], v[194:197], v[126:129]
	v_mfma_f32_16x16x32_bf16 v[122:125], v[168:171], v[194:197], v[122:125]
	v_mfma_f32_16x16x32_bf16 v[122:125], v[164:167], v[190:193], v[122:125]
	v_mfma_f32_16x16x32_bf16 v[118:121], v[174:177], v[190:193], v[118:121]
	v_mfma_f32_16x16x32_bf16 v[118:121], v[178:181], v[194:197], v[118:121]
	v_mfma_f32_16x16x32_bf16 v[114:117], v[186:189], v[194:197], v[114:117]
	v_mfma_f32_16x16x32_bf16 v[114:117], v[182:185], v[190:193], v[114:117]
	v_mfma_f32_16x16x32_bf16 v[98:101], v[182:185], v[198:201], v[98:101]
	v_mfma_f32_16x16x32_bf16 v[98:101], v[186:189], v[202:205], v[98:101]
	v_mfma_f32_16x16x32_bf16 v[102:105], v[178:181], v[202:205], v[102:105]
	v_mfma_f32_16x16x32_bf16 v[102:105], v[174:177], v[198:201], v[102:105]
	v_mfma_f32_16x16x32_bf16 v[106:109], v[164:167], v[198:201], v[106:109]
	v_mfma_f32_16x16x32_bf16 v[106:109], v[168:171], v[202:205], v[106:109]
	v_mfma_f32_16x16x32_bf16 v[110:113], v[160:163], v[202:205], v[110:113]
	v_mfma_f32_16x16x32_bf16 v[110:113], v[156:159], v[198:201], v[110:113]
	v_mfma_f32_16x16x32_bf16 v[94:97], v[156:159], v[206:209], v[94:97]
	v_mfma_f32_16x16x32_bf16 v[94:97], v[160:163], v[210:213], v[94:97]
	v_mfma_f32_16x16x32_bf16 v[90:93], v[168:171], v[210:213], v[90:93]
	v_mfma_f32_16x16x32_bf16 v[90:93], v[164:167], v[206:209], v[90:93]
	v_mfma_f32_16x16x32_bf16 v[86:89], v[174:177], v[206:209], v[86:89]
	v_mfma_f32_16x16x32_bf16 v[86:89], v[178:181], v[210:213], v[86:89]
	v_mfma_f32_16x16x32_bf16 v[82:85], v[186:189], v[210:213], v[82:85]
	v_mfma_f32_16x16x32_bf16 v[82:85], v[182:185], v[206:209], v[82:85]
	v_mfma_f32_16x16x32_bf16 v[66:69], v[182:185], v[214:217], v[66:69]
	v_mfma_f32_16x16x32_bf16 v[66:69], v[186:189], v[218:221], v[66:69]
	v_mfma_f32_16x16x32_bf16 v[70:73], v[178:181], v[218:221], v[70:73]
	v_mfma_f32_16x16x32_bf16 v[70:73], v[174:177], v[214:217], v[70:73]
	v_mfma_f32_16x16x32_bf16 v[74:77], v[164:167], v[214:217], v[74:77]
	v_mfma_f32_16x16x32_bf16 v[74:77], v[168:171], v[218:221], v[74:77]
	v_mfma_f32_16x16x32_bf16 v[78:81], v[160:163], v[218:221], v[78:81]
	v_mfma_f32_16x16x32_bf16 v[78:81], v[156:159], v[214:217], v[78:81]
	v_mfma_f32_16x16x32_bf16 v[62:65], v[156:159], v[222:225], v[62:65]
	v_mfma_f32_16x16x32_bf16 v[62:65], v[160:163], v[226:229], v[62:65]
	v_mfma_f32_16x16x32_bf16 v[58:61], v[168:171], v[226:229], v[58:61]
	v_mfma_f32_16x16x32_bf16 v[58:61], v[164:167], v[222:225], v[58:61]
	v_mfma_f32_16x16x32_bf16 v[54:57], v[174:177], v[222:225], v[54:57]
	v_mfma_f32_16x16x32_bf16 v[54:57], v[178:181], v[226:229], v[54:57]
	v_mfma_f32_16x16x32_bf16 v[50:53], v[186:189], v[226:229], v[50:53]
	v_mfma_f32_16x16x32_bf16 v[50:53], v[182:185], v[222:225], v[50:53]
	v_mfma_f32_16x16x32_bf16 v[34:37], v[182:185], v[230:233], v[34:37]
	v_mfma_f32_16x16x32_bf16 v[34:37], v[186:189], v[234:237], v[34:37]
	v_mfma_f32_16x16x32_bf16 v[38:41], v[178:181], v[234:237], v[38:41]
	v_mfma_f32_16x16x32_bf16 v[38:41], v[174:177], v[230:233], v[38:41]
	v_mfma_f32_16x16x32_bf16 v[42:45], v[164:167], v[230:233], v[42:45]
	v_mfma_f32_16x16x32_bf16 v[42:45], v[168:171], v[234:237], v[42:45]
	v_mfma_f32_16x16x32_bf16 v[46:49], v[160:163], v[234:237], v[46:49]
	v_mfma_f32_16x16x32_bf16 v[46:49], v[156:159], v[230:233], v[46:49]
	v_mfma_f32_16x16x32_bf16 v[30:33], v[156:159], v[238:241], v[30:33]
	v_mfma_f32_16x16x32_bf16 v[30:33], v[160:163], v[242:245], v[30:33]
	v_mfma_f32_16x16x32_bf16 v[26:29], v[168:171], v[242:245], v[26:29]
	v_mfma_f32_16x16x32_bf16 v[26:29], v[164:167], v[238:241], v[26:29]
	v_mfma_f32_16x16x32_bf16 v[22:25], v[174:177], v[238:241], v[22:25]
	v_mfma_f32_16x16x32_bf16 v[22:25], v[178:181], v[242:245], v[22:25]
	v_mfma_f32_16x16x32_bf16 v[18:21], v[186:189], v[242:245], v[18:21]
	v_mfma_f32_16x16x32_bf16 v[18:21], v[182:185], v[238:241], v[18:21]
	v_mfma_f32_16x16x32_bf16 v[2:5], v[182:185], v[246:249], v[2:5]
	v_mfma_f32_16x16x32_bf16 v[2:5], v[186:189], v[250:253], v[2:5]
	v_mfma_f32_16x16x32_bf16 v[6:9], v[178:181], v[250:253], v[6:9]
	v_mfma_f32_16x16x32_bf16 v[6:9], v[174:177], v[246:249], v[6:9]
	v_mfma_f32_16x16x32_bf16 v[10:13], v[164:167], v[246:249], v[10:13]
	v_mfma_f32_16x16x32_bf16 v[10:13], v[168:171], v[250:253], v[10:13]
	v_mfma_f32_16x16x32_bf16 v[14:17], v[160:163], v[250:253], v[14:17]
	v_mfma_f32_16x16x32_bf16 v[14:17], v[156:159], v[246:249], v[14:17]
	s_waitcnt vmcnt(0)
	s_barrier
	s_add_i32 s49, s49, 1
; #define PG8_STAGE(bufoff, gbase, voff) do { _Pragma("unroll") for (int _i = 0; _i < 2; ++_i) \
;         __builtin_amdgcn_global_load_lds((const unsigned*)((const char*)(gbase) + (voff)[_i]), (PG8_LAS unsigned*)(lds + (bufoff) + ldsw + _i * 8192), 16, 0, 0); } while (0)
; #define PG8_LDA(dst, b, h) do { _Pragma("unroll") for (int m = 0; m < 4; ++m) _Pragma("unroll") for (int k = 0; k < 2; ++k) dst[m][k] = *(const PG8_LAS bf16x8*)(lds + PG8_SA(b, h) + aoff + m * 2048 + k * 1024); } while (0)
; #define PG8_LDB(dst, b, h) do { _Pragma("unroll") for (int n = 0; n < 2; ++n) _Pragma("unroll") for (int k = 0; k < 2; ++k) dst[n][k] = *(const PG8_LAS bf16x8*)(lds + PG8_SB(b, h) + boff + n * 2048 + k * 1024); } while (0)
; #define PG8_MMA(ai, bj, At, Bt) do { __builtin_amdgcn_s_setprio(1); _Pragma("unroll") for (int m = 0; m < 4; ++m) _Pragma("unroll") for (int n = 0; n < 2; ++n) _Pragma("unroll") for (int k = 0; k < 2; ++k) \
;         acc[ai][bj][m][n] = __builtin_amdgcn_mfma_f32_16x16x32_bf16(Bt[n][k], At[m][k], acc[ai][bj][m][n], 0, 0, 0); __builtin_amdgcn_s_setprio(0); } while (0)
; #define PG8_WAIT_V(n) asm volatile("s_waitcnt vmcnt(" #n ")" ::: "memory")
; #define PG8_WAIT_L(n) asm volatile("s_waitcnt lgkmcnt(" #n ")" ::: "memory")
; #define PG8_BAR __builtin_amdgcn_s_barrier()
; #define PG8_SCHED __builtin_amdgcn_sched_barrier(0)
; template <class Epi, class Sched, bool ALIGN_EPI>
; __device__ __forceinline__ void gemm_phase(PG8_LAS unsigned char* lds, const Gemm g, const Sched& S, const Epi& E) {
;     ...
;             PG8_LDB(B0, 0, 0); PG8_LDB(B1, 0, 1); PG8_SCHED; PG8_LDA(At, 0, 0); PG8_STAGE(PG8_SA(1, 1), a1 + hstepA, voffA);
;             PG8_WAIT_V(8); PG8_WAIT_L(0); PG8_BAR; PG8_MMA(0, 0, At, B0); PG8_MMA(0, 1, At, B1); PG8_BAR; PG8_SCHED;
;             PG8_LDA(At, 0, 1); PG8_STAGE(PG8_SB(0, 0), b2, voffB); PG8_STAGE(PG8_SB(0, 1), b2 + hstepB, voffB); PG8_STAGE(PG8_SA(0, 0), a2, voffA);
;             PG8_WAIT_V(8); PG8_WAIT_L(0); PG8_BAR; PG8_MMA(1, 0, At, B0); PG8_MMA(1, 1, At, B1); PG8_BAR; PG8_SCHED;
.Lp8k_A_loop:
	ds_read_b128 v[190:193], v155 offset:0
	ds_read_b128 v[194:197], v155 offset:1024
	ds_read_b128 v[198:201], v155 offset:2048
	s_add_i32 m0, s2, 0x18000
	s_nop 0
	global_load_lds_dwordx4 v134, s[28:29]
	ds_read_b128 v[202:205], v155 offset:3072
	ds_read_b128 v[206:209], v155 offset:4096
	ds_read_b128 v[210:213], v155 offset:5120
	s_add_i32 m0, s2, 0x1a000
	s_nop 0
	global_load_lds_dwordx4 v130, s[28:29]
	ds_read_b128 v[214:217], v155 offset:6144
	ds_read_b128 v[218:221], v155 offset:7168
	ds_read_b128 v[156:159], v153 offset:0
	s_add_u32 s30, s28, 0x20000
	s_addc_u32 s31, s29, 0
	s_add_i32 m0, s2, 0x19000
	s_nop 0
	global_load_lds_dwordx4 v134, s[30:31]
	ds_read_b128 v[160:163], v153 offset:1024
	ds_read_b128 v[164:167], v153 offset:2048
	ds_read_b128 v[168:171], v153 offset:3072
	s_add_i32 m0, s2, 0x1b000
	s_nop 0
	global_load_lds_dwordx4 v130, s[30:31]
	ds_read_b128 v[174:177], v153 offset:16384
	ds_read_b128 v[178:181], v153 offset:17408
	ds_read_b128 v[182:185], v153 offset:18432
	s_add_u32 s30, s28, 0x80000
	s_addc_u32 s31, s29, 0
	s_add_i32 m0, s2, 0x1c000
	s_nop 0
	global_load_lds_dwordx4 v134, s[30:31]
	ds_read_b128 v[186:189], v153 offset:19456
	ds_read_b128 v[222:225], v155 offset:16384
	ds_read_b128 v[226:229], v155 offset:17408
	s_add_i32 m0, s2, 0x1e000
	s_nop 0
	global_load_lds_dwordx4 v130, s[30:31]
	ds_read_b128 v[230:233], v155 offset:18432
	ds_read_b128 v[234:237], v155 offset:19456
	ds_read_b128 v[238:241], v155 offset:20480
	s_add_u32 s30, s28, 0xa0000
	s_addc_u32 s31, s29, 0
	s_add_i32 m0, s2, 0x1d000
	s_nop 0
	global_load_lds_dwordx4 v134, s[30:31]
	ds_read_b128 v[242:245], v155 offset:21504
	ds_read_b128 v[246:249], v155 offset:22528
	ds_read_b128 v[250:253], v155 offset:23552
	s_add_i32 m0, s2, 0x1f000
	s_nop 0
	global_load_lds_dwordx4 v130, s[30:31]
	s_add_u32 s28, s28, 0x80
	s_addc_u32 s29, s29, 0
	s_waitcnt vmcnt(8) lgkmcnt(0)
	s_barrier
	v_mfma_f32_16x16x32_bf16 v[126:129], v[156:159], v[190:193], v[126:129]
	v_mfma_f32_16x16x32_bf16 v[126:129], v[160:163], v[194:197], v[126:129]
	v_mfma_f32_16x16x32_bf16 v[122:125], v[168:171], v[194:197], v[122:125]
	v_mfma_f32_16x16x32_bf16 v[122:125], v[164:167], v[190:193], v[122:125]
	v_mfma_f32_16x16x32_bf16 v[118:121], v[174:177], v[190:193], v[118:121]
	v_mfma_f32_16x16x32_bf16 v[118:121], v[178:181], v[194:197], v[118:121]
	v_mfma_f32_16x16x32_bf16 v[114:117], v[186:189], v[194:197], v[114:117]
	v_mfma_f32_16x16x32_bf16 v[114:117], v[182:185], v[190:193], v[114:117]
	v_mfma_f32_16x16x32_bf16 v[98:101], v[182:185], v[198:201], v[98:101]
	v_mfma_f32_16x16x32_bf16 v[98:101], v[186:189], v[202:205], v[98:101]
	v_mfma_f32_16x16x32_bf16 v[102:105], v[178:181], v[202:205], v[102:105]
	v_mfma_f32_16x16x32_bf16 v[102:105], v[174:177], v[198:201], v[102:105]
	v_mfma_f32_16x16x32_bf16 v[106:109], v[164:167], v[198:201], v[106:109]
	v_mfma_f32_16x16x32_bf16 v[106:109], v[168:171], v[202:205], v[106:109]
	v_mfma_f32_16x16x32_bf16 v[110:113], v[160:163], v[202:205], v[110:113]
	v_mfma_f32_16x16x32_bf16 v[110:113], v[156:159], v[198:201], v[110:113]
	v_mfma_f32_16x16x32_bf16 v[94:97], v[156:159], v[206:209], v[94:97]
	v_mfma_f32_16x16x32_bf16 v[94:97], v[160:163], v[210:213], v[94:97]
	v_mfma_f32_16x16x32_bf16 v[90:93], v[168:171], v[210:213], v[90:93]
	v_mfma_f32_16x16x32_bf16 v[90:93], v[164:167], v[206:209], v[90:93]
	v_mfma_f32_16x16x32_bf16 v[86:89], v[174:177], v[206:209], v[86:89]
	v_mfma_f32_16x16x32_bf16 v[86:89], v[178:181], v[210:213], v[86:89]
	v_mfma_f32_16x16x32_bf16 v[82:85], v[186:189], v[210:213], v[82:85]
	v_mfma_f32_16x16x32_bf16 v[82:85], v[182:185], v[206:209], v[82:85]
	v_mfma_f32_16x16x32_bf16 v[66:69], v[182:185], v[214:217], v[66:69]
	v_mfma_f32_16x16x32_bf16 v[66:69], v[186:189], v[218:221], v[66:69]
	v_mfma_f32_16x16x32_bf16 v[70:73], v[178:181], v[218:221], v[70:73]
	v_mfma_f32_16x16x32_bf16 v[70:73], v[174:177], v[214:217], v[70:73]
	v_mfma_f32_16x16x32_bf16 v[74:77], v[164:167], v[214:217], v[74:77]
	v_mfma_f32_16x16x32_bf16 v[74:77], v[168:171], v[218:221], v[74:77]
	v_mfma_f32_16x16x32_bf16 v[78:81], v[160:163], v[218:221], v[78:81]
	v_mfma_f32_16x16x32_bf16 v[78:81], v[156:159], v[214:217], v[78:81]
	v_mfma_f32_16x16x32_bf16 v[62:65], v[156:159], v[222:225], v[62:65]
	v_mfma_f32_16x16x32_bf16 v[62:65], v[160:163], v[226:229], v[62:65]
	v_mfma_f32_16x16x32_bf16 v[58:61], v[168:171], v[226:229], v[58:61]
	v_mfma_f32_16x16x32_bf16 v[58:61], v[164:167], v[222:225], v[58:61]
	v_mfma_f32_16x16x32_bf16 v[54:57], v[174:177], v[222:225], v[54:57]
	v_mfma_f32_16x16x32_bf16 v[54:57], v[178:181], v[226:229], v[54:57]
	v_mfma_f32_16x16x32_bf16 v[50:53], v[186:189], v[226:229], v[50:53]
	v_mfma_f32_16x16x32_bf16 v[50:53], v[182:185], v[222:225], v[50:53]
	v_mfma_f32_16x16x32_bf16 v[34:37], v[182:185], v[230:233], v[34:37]
	v_mfma_f32_16x16x32_bf16 v[34:37], v[186:189], v[234:237], v[34:37]
	v_mfma_f32_16x16x32_bf16 v[38:41], v[178:181], v[234:237], v[38:41]
	v_mfma_f32_16x16x32_bf16 v[38:41], v[174:177], v[230:233], v[38:41]
	v_mfma_f32_16x16x32_bf16 v[42:45], v[164:167], v[230:233], v[42:45]
	v_mfma_f32_16x16x32_bf16 v[42:45], v[168:171], v[234:237], v[42:45]
	v_mfma_f32_16x16x32_bf16 v[46:49], v[160:163], v[234:237], v[46:49]
	v_mfma_f32_16x16x32_bf16 v[46:49], v[156:159], v[230:233], v[46:49]
	v_mfma_f32_16x16x32_bf16 v[30:33], v[156:159], v[238:241], v[30:33]
	v_mfma_f32_16x16x32_bf16 v[30:33], v[160:163], v[242:245], v[30:33]
	v_mfma_f32_16x16x32_bf16 v[26:29], v[168:171], v[242:245], v[26:29]
	v_mfma_f32_16x16x32_bf16 v[26:29], v[164:167], v[238:241], v[26:29]
	v_mfma_f32_16x16x32_bf16 v[22:25], v[174:177], v[238:241], v[22:25]
	v_mfma_f32_16x16x32_bf16 v[22:25], v[178:181], v[242:245], v[22:25]
	v_mfma_f32_16x16x32_bf16 v[18:21], v[186:189], v[242:245], v[18:21]
	v_mfma_f32_16x16x32_bf16 v[18:21], v[182:185], v[238:241], v[18:21]
	v_mfma_f32_16x16x32_bf16 v[2:5], v[182:185], v[246:249], v[2:5]
	v_mfma_f32_16x16x32_bf16 v[2:5], v[186:189], v[250:253], v[2:5]
	v_mfma_f32_16x16x32_bf16 v[6:9], v[178:181], v[250:253], v[6:9]
	v_mfma_f32_16x16x32_bf16 v[6:9], v[174:177], v[246:249], v[6:9]
	v_mfma_f32_16x16x32_bf16 v[10:13], v[164:167], v[246:249], v[10:13]
	v_mfma_f32_16x16x32_bf16 v[10:13], v[168:171], v[250:253], v[10:13]
	v_mfma_f32_16x16x32_bf16 v[14:17], v[160:163], v[250:253], v[14:17]
	v_mfma_f32_16x16x32_bf16 v[14:17], v[156:159], v[246:249], v[14:17]
	s_waitcnt vmcnt(0)
	s_barrier
; #define PG8_STAGE(bufoff, gbase, voff) do { _Pragma("unroll") for (int _i = 0; _i < 2; ++_i) \
;         __builtin_amdgcn_global_load_lds((const unsigned*)((const char*)(gbase) + (voff)[_i]), (PG8_LAS unsigned*)(lds + (bufoff) + ldsw + _i * 8192), 16, 0, 0); } while (0)
; #define PG8_LDA(dst, b, h) do { _Pragma("unroll") for (int m = 0; m < 4; ++m) _Pragma("unroll") for (int k = 0; k < 2; ++k) dst[m][k] = *(const PG8_LAS bf16x8*)(lds + PG8_SA(b, h) + aoff + m * 2048 + k * 1024); } while (0)
; #define PG8_LDB(dst, b, h) do { _Pragma("unroll") for (int n = 0; n < 2; ++n) _Pragma("unroll") for (int k = 0; k < 2; ++k) dst[n][k] = *(const PG8_LAS bf16x8*)(lds + PG8_SB(b, h) + boff + n * 2048 + k * 1024); } while (0)
; #define PG8_MMA(ai, bj, At, Bt) do { __builtin_amdgcn_s_setprio(1); _Pragma("unroll") for (int m = 0; m < 4; ++m) _Pragma("unroll") for (int n = 0; n < 2; ++n) _Pragma("unroll") for (int k = 0; k < 2; ++k) \
;         acc[ai][bj][m][n] = __builtin_amdgcn_mfma_f32_16x16x32_bf16(Bt[n][k], At[m][k], acc[ai][bj][m][n], 0, 0, 0); __builtin_amdgcn_s_setprio(0); } while (0)
; #define PG8_WAIT_V(n) asm volatile("s_waitcnt vmcnt(" #n ")" ::: "memory")
; #define PG8_WAIT_L(n) asm volatile("s_waitcnt lgkmcnt(" #n ")" ::: "memory")
; #define PG8_BAR __builtin_amdgcn_s_barrier()
; #define PG8_SCHED __builtin_amdgcn_sched_barrier(0)
; template <class Epi, class Sched, bool ALIGN_EPI>
; __device__ __forceinline__ void gemm_phase(PG8_LAS unsigned char* lds, const Gemm g, const Sched& S, const Epi& E) {
;     ...
;             PG8_LDB(B0, 1, 0); PG8_LDB(B1, 1, 1); PG8_SCHED; PG8_LDA(At, 1, 0); PG8_STAGE(PG8_SA(0, 1), a2 + hstepA, voffA);
;             PG8_WAIT_V(8); PG8_WAIT_L(0); PG8_BAR; PG8_MMA(0, 0, At, B0); PG8_MMA(0, 1, At, B1); PG8_BAR; PG8_SCHED;
;             PG8_LDA(At, 1, 1); PG8_STAGE(PG8_SB(1, 0), b3, voffB); PG8_STAGE(PG8_SB(1, 1), b3 + hstepB, voffB); PG8_STAGE(PG8_SA(1, 0), a3, voffA);
;             PG8_WAIT_V(8); PG8_WAIT_L(0); PG8_BAR; PG8_MMA(1, 0, At, B0); PG8_MMA(1, 1, At, B1); PG8_BAR; PG8_SCHED;
	ds_read_b128 v[190:193], v155 offset:32768
	ds_read_b128 v[194:197], v155 offset:33792
	ds_read_b128 v[198:201], v155 offset:34816
	s_cmp_eq_u32 s49, 15
	s_cselect_b32 s28, s50, s28
	s_cselect_b32 s29, s51, s29
	s_add_i32 m0, s2, 0x10000
	s_nop 0
	global_load_lds_dwordx4 v134, s[28:29]
	ds_read_b128 v[202:205], v155 offset:35840
	ds_read_b128 v[206:209], v155 offset:36864
	ds_read_b128 v[210:213], v155 offset:37888
	s_add_i32 m0, s2, 0x12000
	s_nop 0
	global_load_lds_dwordx4 v130, s[28:29]
	ds_read_b128 v[214:217], v155 offset:38912
	ds_read_b128 v[218:221], v155 offset:39936
	ds_read_b128 v[156:159], v153 offset:32768
	s_add_u32 s30, s28, 0x20000
	s_addc_u32 s31, s29, 0
	s_add_i32 m0, s2, 0x11000
	s_nop 0
	global_load_lds_dwordx4 v134, s[30:31]
	ds_read_b128 v[160:163], v153 offset:33792
	ds_read_b128 v[164:167], v153 offset:34816
	ds_read_b128 v[168:171], v153 offset:35840
	s_add_i32 m0, s2, 0x13000
	s_nop 0
	global_load_lds_dwordx4 v130, s[30:31]
	ds_read_b128 v[174:177], v153 offset:49152
	ds_read_b128 v[178:181], v153 offset:50176
	ds_read_b128 v[182:185], v153 offset:51200
	s_add_u32 s30, s28, 0x80000
	s_addc_u32 s31, s29, 0
	s_add_i32 m0, s2, 0x14000
	s_nop 0
	global_load_lds_dwordx4 v134, s[30:31]
	ds_read_b128 v[186:189], v153 offset:52224
	ds_read_b128 v[222:225], v155 offset:49152
	ds_read_b128 v[226:229], v155 offset:50176
	s_add_i32 m0, s2, 0x16000
	s_nop 0
	global_load_lds_dwordx4 v130, s[30:31]
	ds_read_b128 v[230:233], v155 offset:51200
	ds_read_b128 v[234:237], v155 offset:52224
	ds_read_b128 v[238:241], v155 offset:53248
	s_add_u32 s30, s28, 0xa0000
	s_addc_u32 s31, s29, 0
	s_add_i32 m0, s2, 0x15000
	s_nop 0
	global_load_lds_dwordx4 v134, s[30:31]
	ds_read_b128 v[242:245], v155 offset:54272
	ds_read_b128 v[246:249], v155 offset:55296
	ds_read_b128 v[250:253], v155 offset:56320
	s_add_i32 m0, s2, 0x17000
	s_nop 0
	global_load_lds_dwordx4 v130, s[30:31]
	s_add_u32 s28, s28, 0x80
	s_addc_u32 s29, s29, 0
	s_waitcnt vmcnt(8) lgkmcnt(0)
	s_barrier
	v_mfma_f32_16x16x32_bf16 v[126:129], v[156:159], v[190:193], v[126:129]
	v_mfma_f32_16x16x32_bf16 v[126:129], v[160:163], v[194:197], v[126:129]
	v_mfma_f32_16x16x32_bf16 v[122:125], v[168:171], v[194:197], v[122:125]
	v_mfma_f32_16x16x32_bf16 v[122:125], v[164:167], v[190:193], v[122:125]
	v_mfma_f32_16x16x32_bf16 v[118:121], v[174:177], v[190:193], v[118:121]
	v_mfma_f32_16x16x32_bf16 v[118:121], v[178:181], v[194:197], v[118:121]
	v_mfma_f32_16x16x32_bf16 v[114:117], v[186:189], v[194:197], v[114:117]
	v_mfma_f32_16x16x32_bf16 v[114:117], v[182:185], v[190:193], v[114:117]
	v_mfma_f32_16x16x32_bf16 v[98:101], v[182:185], v[198:201], v[98:101]
	v_mfma_f32_16x16x32_bf16 v[98:101], v[186:189], v[202:205], v[98:101]
	v_mfma_f32_16x16x32_bf16 v[102:105], v[178:181], v[202:205], v[102:105]
	v_mfma_f32_16x16x32_bf16 v[102:105], v[174:177], v[198:201], v[102:105]
	v_mfma_f32_16x16x32_bf16 v[106:109], v[164:167], v[198:201], v[106:109]
	v_mfma_f32_16x16x32_bf16 v[106:109], v[168:171], v[202:205], v[106:109]
	v_mfma_f32_16x16x32_bf16 v[110:113], v[160:163], v[202:205], v[110:113]
	v_mfma_f32_16x16x32_bf16 v[110:113], v[156:159], v[198:201], v[110:113]
	v_mfma_f32_16x16x32_bf16 v[94:97], v[156:159], v[206:209], v[94:97]
	v_mfma_f32_16x16x32_bf16 v[94:97], v[160:163], v[210:213], v[94:97]
	v_mfma_f32_16x16x32_bf16 v[90:93], v[168:171], v[210:213], v[90:93]
	v_mfma_f32_16x16x32_bf16 v[90:93], v[164:167], v[206:209], v[90:93]
	v_mfma_f32_16x16x32_bf16 v[86:89], v[174:177], v[206:209], v[86:89]
	v_mfma_f32_16x16x32_bf16 v[86:89], v[178:181], v[210:213], v[86:89]
	v_mfma_f32_16x16x32_bf16 v[82:85], v[186:189], v[210:213], v[82:85]
	v_mfma_f32_16x16x32_bf16 v[82:85], v[182:185], v[206:209], v[82:85]
	v_mfma_f32_16x16x32_bf16 v[66:69], v[182:185], v[214:217], v[66:69]
	v_mfma_f32_16x16x32_bf16 v[66:69], v[186:189], v[218:221], v[66:69]
	v_mfma_f32_16x16x32_bf16 v[70:73], v[178:181], v[218:221], v[70:73]
	v_mfma_f32_16x16x32_bf16 v[70:73], v[174:177], v[214:217], v[70:73]
	v_mfma_f32_16x16x32_bf16 v[74:77], v[164:167], v[214:217], v[74:77]
	v_mfma_f32_16x16x32_bf16 v[74:77], v[168:171], v[218:221], v[74:77]
	v_mfma_f32_16x16x32_bf16 v[78:81], v[160:163], v[218:221], v[78:81]
	v_mfma_f32_16x16x32_bf16 v[78:81], v[156:159], v[214:217], v[78:81]
	v_mfma_f32_16x16x32_bf16 v[62:65], v[156:159], v[222:225], v[62:65]
	v_mfma_f32_16x16x32_bf16 v[62:65], v[160:163], v[226:229], v[62:65]
	v_mfma_f32_16x16x32_bf16 v[58:61], v[168:171], v[226:229], v[58:61]
	v_mfma_f32_16x16x32_bf16 v[58:61], v[164:167], v[222:225], v[58:61]
	v_mfma_f32_16x16x32_bf16 v[54:57], v[174:177], v[222:225], v[54:57]
	v_mfma_f32_16x16x32_bf16 v[54:57], v[178:181], v[226:229], v[54:57]
	v_mfma_f32_16x16x32_bf16 v[50:53], v[186:189], v[226:229], v[50:53]
	v_mfma_f32_16x16x32_bf16 v[50:53], v[182:185], v[222:225], v[50:53]
	v_mfma_f32_16x16x32_bf16 v[34:37], v[182:185], v[230:233], v[34:37]
	v_mfma_f32_16x16x32_bf16 v[34:37], v[186:189], v[234:237], v[34:37]
	v_mfma_f32_16x16x32_bf16 v[38:41], v[178:181], v[234:237], v[38:41]
	v_mfma_f32_16x16x32_bf16 v[38:41], v[174:177], v[230:233], v[38:41]
	v_mfma_f32_16x16x32_bf16 v[42:45], v[164:167], v[230:233], v[42:45]
	v_mfma_f32_16x16x32_bf16 v[42:45], v[168:171], v[234:237], v[42:45]
	v_mfma_f32_16x16x32_bf16 v[46:49], v[160:163], v[234:237], v[46:49]
	v_mfma_f32_16x16x32_bf16 v[46:49], v[156:159], v[230:233], v[46:49]
	v_mfma_f32_16x16x32_bf16 v[30:33], v[156:159], v[238:241], v[30:33]
	v_mfma_f32_16x16x32_bf16 v[30:33], v[160:163], v[242:245], v[30:33]
	v_mfma_f32_16x16x32_bf16 v[26:29], v[168:171], v[242:245], v[26:29]
	v_mfma_f32_16x16x32_bf16 v[26:29], v[164:167], v[238:241], v[26:29]
	v_mfma_f32_16x16x32_bf16 v[22:25], v[174:177], v[238:241], v[22:25]
	v_mfma_f32_16x16x32_bf16 v[22:25], v[178:181], v[242:245], v[22:25]
	v_mfma_f32_16x16x32_bf16 v[18:21], v[186:189], v[242:245], v[18:21]
	v_mfma_f32_16x16x32_bf16 v[18:21], v[182:185], v[238:241], v[18:21]
	v_mfma_f32_16x16x32_bf16 v[2:5], v[182:185], v[246:249], v[2:5]
	v_mfma_f32_16x16x32_bf16 v[2:5], v[186:189], v[250:253], v[2:5]
	v_mfma_f32_16x16x32_bf16 v[6:9], v[178:181], v[250:253], v[6:9]
	v_mfma_f32_16x16x32_bf16 v[6:9], v[174:177], v[246:249], v[6:9]
	v_mfma_f32_16x16x32_bf16 v[10:13], v[164:167], v[246:249], v[10:13]
	v_mfma_f32_16x16x32_bf16 v[10:13], v[168:171], v[250:253], v[10:13]
	v_mfma_f32_16x16x32_bf16 v[14:17], v[160:163], v[250:253], v[14:17]
	v_mfma_f32_16x16x32_bf16 v[14:17], v[156:159], v[246:249], v[14:17]
	s_waitcnt vmcnt(0)
	s_barrier
; #define PG8_STAGE(bufoff, gbase, voff) do { _Pragma("unroll") for (int _i = 0; _i < 2; ++_i) \
;         __builtin_amdgcn_global_load_lds((const unsigned*)((const char*)(gbase) + (voff)[_i]), (PG8_LAS unsigned*)(lds + (bufoff) + ldsw + _i * 8192), 16, 0, 0); } while (0)
; #define PG8_LDA(dst, b, h) do { _Pragma("unroll") for (int m = 0; m < 4; ++m) _Pragma("unroll") for (int k = 0; k < 2; ++k) dst[m][k] = *(const PG8_LAS bf16x8*)(lds + PG8_SA(b, h) + aoff + m * 2048 + k * 1024); } while (0)
; #define PG8_LDB(dst, b, h) do { _Pragma("unroll") for (int n = 0; n < 2; ++n) _Pragma("unroll") for (int k = 0; k < 2; ++k) dst[n][k] = *(const PG8_LAS bf16x8*)(lds + PG8_SB(b, h) + boff + n * 2048 + k * 1024); } while (0)
; #define PG8_WAIT_V(n) asm volatile("s_waitcnt vmcnt(" #n ")" ::: "memory")
; #define PG8_WAIT_L(n) asm volatile("s_waitcnt lgkmcnt(" #n ")" ::: "memory")
; #define PG8_BAR __builtin_amdgcn_s_barrier()
; #define PG8_SCHED __builtin_amdgcn_sched_barrier(0)
; template <class Epi, class Sched, bool ALIGN_EPI>
; __device__ __forceinline__ void gemm_phase(PG8_LAS unsigned char* lds, const Gemm g, const Sched& S, const Epi& E) {
;     ...
;             const char* a2 = last ? nA : cA + (size_t)(t + 2) * kstepA; const char* b2 = last ? nB : cB + (size_t)(t + 2) * kstep;
;             const char* a3 = a2 + kstepA; const char* b3 = b2 + kstep;
;             PG8_LDB(B0, 0, 0); PG8_LDB(B1, 0, 1); PG8_SCHED; PG8_LDA(At, 0, 0); PG8_STAGE(PG8_SA(1, 1), a1 + hstepA, voffA);
;             PG8_WAIT_V(8); PG8_WAIT_L(0); PG8_BAR; PG8_MMA(0, 0, At, B0); PG8_MMA(0, 1, At, B1); PG8_BAR; PG8_SCHED;
;             PG8_LDA(At, 0, 1); PG8_STAGE(PG8_SB(0, 0), b2, voffB); PG8_STAGE(PG8_SB(0, 1), b2 + hstepB, voffB); PG8_STAGE(PG8_SA(0, 0), a2, voffA);
;             PG8_WAIT_V(8); PG8_WAIT_L(0); PG8_BAR; PG8_MMA(1, 0, At, B0); PG8_MMA(1, 1, At, B1); PG8_BAR; PG8_SCHED;
;             PG8_LDB(B0, 1, 0); PG8_LDB(B1, 1, 1); PG8_SCHED; PG8_LDA(At, 1, 0); PG8_STAGE(PG8_SA(0, 1), a2 + hstepA, voffA);
;             PG8_WAIT_V(8); PG8_WAIT_L(0); PG8_BAR; PG8_MMA(0, 0, At, B0); PG8_MMA(0, 1, At, B1); PG8_BAR; PG8_SCHED;
;             PG8_LDA(At, 1, 1); PG8_STAGE(PG8_SB(1, 0), b3, voffB); PG8_STAGE(PG8_SB(1, 1), b3 + hstepB, voffB); PG8_STAGE(PG8_SA(1, 0), a3, voffA);
;             PG8_WAIT_V(8); PG8_WAIT_L(0); PG8_BAR; PG8_MMA(1, 0, At, B0); PG8_MMA(1, 1, At, B1); PG8_BAR; PG8_SCHED;
;         }
	s_add_i32 s49, s49, 1
	s_cmp_lt_u32 s49, 16
	s_cbranch_scc1 .Lp8k_A_loop
	ds_read_b128 v[190:193], v155 offset:0
	ds_read_b128 v[194:197], v155 offset:1024
	ds_read_b128 v[198:201], v155 offset:2048
	s_add_i32 m0, s2, 0x18000
	s_nop 0
	global_load_lds_dwordx4 v134, s[28:29]
	ds_read_b128 v[202:205], v155 offset:3072
	ds_read_b128 v[206:209], v155 offset:4096
	ds_read_b128 v[210:213], v155 offset:5120
	s_add_i32 m0, s2, 0x1a000
	s_nop 0
	global_load_lds_dwordx4 v130, s[28:29]
	ds_read_b128 v[214:217], v155 offset:6144
	ds_read_b128 v[218:221], v155 offset:7168
	ds_read_b128 v[164:167], v153 offset:2048
	s_add_u32 s30, s28, 0x20000
	s_addc_u32 s31, s29, 0
	s_add_i32 m0, s2, 0x19000
	s_nop 0
	global_load_lds_dwordx4 v134, s[30:31]
	ds_read_b128 v[168:171], v153 offset:3072
	ds_read_b128 v[174:177], v153 offset:16384
	ds_read_b128 v[178:181], v153 offset:17408
	s_add_i32 m0, s2, 0x1b000
	s_nop 0
	global_load_lds_dwordx4 v130, s[30:31]
	ds_read_b128 v[182:185], v153 offset:18432
	ds_read_b128 v[186:189], v153 offset:19456
	ds_read_b128 v[222:225], v155 offset:16384
	s_add_u32 s30, s28, 0x80000
	s_addc_u32 s31, s29, 0
	s_add_i32 m0, s2, 0x1c000
	s_nop 0
	global_load_lds_dwordx4 v134, s[30:31]
	ds_read_b128 v[226:229], v155 offset:17408
	ds_read_b128 v[230:233], v155 offset:18432
	ds_read_b128 v[234:237], v155 offset:19456
	s_add_i32 m0, s2, 0x1e000
	s_nop 0
	global_load_lds_dwordx4 v130, s[30:31]
	ds_read_b128 v[238:241], v155 offset:20480
	ds_read_b128 v[242:245], v155 offset:21504
	ds_read_b128 v[246:249], v155 offset:22528
	s_add_u32 s30, s28, 0xa0000
	s_addc_u32 s31, s29, 0
	s_add_i32 m0, s2, 0x1d000
	s_nop 0
	global_load_lds_dwordx4 v134, s[30:31]
	ds_read_b128 v[250:253], v155 offset:23552
	s_add_i32 m0, s2, 0x1f000
	s_nop 0
	global_load_lds_dwordx4 v130, s[30:31]
	s_add_u32 s28, s28, 0x80
	s_addc_u32 s29, s29, 0
	s_branch .Lp8k_done
.Lp8k_B_init:
	s_setprio 1
	s_sub_u32 s28, s28, 0xa0000
	s_subb_u32 s29, s29, 0
	s_sub_u32 s50, s22, 0x20000
	s_subb_u32 s51, s23, 0
	s_cmp_eq_u32 s42, 1
	s_cbranch_scc1 .Lp8k_B_nobar
	s_barrier
.Lp8k_B_nobar:
	ds_read_b128 v[190:193], v155 offset:0
	ds_read_b128 v[194:197], v155 offset:1024
	ds_read_b128 v[198:201], v155 offset:2048
	s_add_i32 m0, s2, 0xa000
	s_nop 0
	global_load_lds_dwordx4 v132, s[28:29]
	ds_read_b128 v[202:205], v155 offset:3072
	ds_read_b128 v[206:209], v155 offset:4096
	ds_read_b128 v[210:213], v155 offset:5120
	s_add_u32 s30, s28, 0x20000
	s_addc_u32 s31, s29, 0
	s_add_i32 m0, s2, 0xb000
	s_nop 0
	global_load_lds_dwordx4 v132, s[30:31]
	ds_read_b128 v[214:217], v155 offset:6144
	ds_read_b128 v[218:221], v155 offset:7168
	ds_read_b128 v[156:159], v153 offset:0
	s_add_u32 s30, s28, 0x80000
	s_addc_u32 s31, s29, 0
	s_add_i32 m0, s2, 0xe000
	s_nop 0
	global_load_lds_dwordx4 v132, s[30:31]
	ds_read_b128 v[160:163], v153 offset:1024
	ds_read_b128 v[164:167], v153 offset:2048
	ds_read_b128 v[168:171], v153 offset:3072
	s_add_u32 s30, s28, 0xa0000
	s_addc_u32 s31, s29, 0
	s_add_i32 m0, s2, 0xf000
	s_nop 0
	global_load_lds_dwordx4 v132, s[30:31]
	ds_read_b128 v[174:177], v153 offset:16384
	ds_read_b128 v[178:181], v153 offset:17408
	ds_read_b128 v[182:185], v153 offset:18432
	s_add_u32 s34, s28, 0x80
	s_addc_u32 s35, s29, 0
	s_cmp_eq_u32 s49, 15
	s_cselect_b32 s34, s50, s34
	s_cselect_b32 s35, s51, s35
	s_add_i32 m0, s2, 0x0
	s_nop 0
	global_load_lds_dwordx4 v136, s[34:35]
	ds_read_b128 v[186:189], v153 offset:19456
	ds_read_b128 v[222:225], v155 offset:16384
	ds_read_b128 v[226:229], v155 offset:17408
	s_add_u32 s30, s34, 0x20000
	s_addc_u32 s31, s35, 0
	s_add_i32 m0, s2, 0x1000
	s_nop 0
	global_load_lds_dwordx4 v136, s[30:31]
	ds_read_b128 v[230:233], v155 offset:18432
	ds_read_b128 v[234:237], v155 offset:19456
	ds_read_b128 v[238:241], v155 offset:20480
	s_add_u32 s30, s34, 0x80000
	s_addc_u32 s31, s35, 0
	s_add_i32 m0, s2, 0x4000
	s_nop 0
	global_load_lds_dwordx4 v136, s[30:31]
	ds_read_b128 v[242:245], v155 offset:21504
	ds_read_b128 v[246:249], v155 offset:22528
	ds_read_b128 v[250:253], v155 offset:23552
	s_add_u32 s30, s34, 0xa0000
	s_addc_u32 s31, s35, 0
	s_add_i32 m0, s2, 0x5000
	s_nop 0
	global_load_lds_dwordx4 v136, s[30:31]
	s_add_u32 s28, s28, 0x80
	s_addc_u32 s29, s29, 0
	s_waitcnt vmcnt(8) lgkmcnt(0)
	s_barrier
; #define PG8_STAGE(bufoff, gbase, voff) do { _Pragma("unroll") for (int _i = 0; _i < 2; ++_i) \
;         __builtin_amdgcn_global_load_lds((const unsigned*)((const char*)(gbase) + (voff)[_i]), (PG8_LAS unsigned*)(lds + (bufoff) + ldsw + _i * 8192), 16, 0, 0); } while (0)
; #define PG8_LDA(dst, b, h) do { _Pragma("unroll") for (int m = 0; m < 4; ++m) _Pragma("unroll") for (int k = 0; k < 2; ++k) dst[m][k] = *(const PG8_LAS bf16x8*)(lds + PG8_SA(b, h) + aoff + m * 2048 + k * 1024); } while (0)
; #define PG8_LDB(dst, b, h) do { _Pragma("unroll") for (int n = 0; n < 2; ++n) _Pragma("unroll") for (int k = 0; k < 2; ++k) dst[n][k] = *(const PG8_LAS bf16x8*)(lds + PG8_SB(b, h) + boff + n * 2048 + k * 1024); } while (0)
; #define PG8_MMA(ai, bj, At, Bt) do { __builtin_amdgcn_s_setprio(1); _Pragma("unroll") for (int m = 0; m < 4; ++m) _Pragma("unroll") for (int n = 0; n < 2; ++n) _Pragma("unroll") for (int k = 0; k < 2; ++k) \
;         acc[ai][bj][m][n] = __builtin_amdgcn_mfma_f32_16x16x32_bf16(Bt[n][k], At[m][k], acc[ai][bj][m][n], 0, 0, 0); __builtin_amdgcn_s_setprio(0); } while (0)
; #define PG8_WAIT_V(n) asm volatile("s_waitcnt vmcnt(" #n ")" ::: "memory")
; template <class Epi, class Sched, bool ALIGN_EPI>
; __device__ __forceinline__ void gemm_phase(PG8_LAS unsigned char* lds, const Gemm g, const Sched& S, const Epi& E) {
;     ...
;             PG8_LDB(B0, 0, 0); PG8_LDB(B1, 0, 1); PG8_SCHED; PG8_LDA(At, 0, 0); PG8_STAGE(PG8_SA(1, 1), a1 + hstepA, voffA);
;             PG8_WAIT_V(8); PG8_WAIT_L(0); PG8_BAR; PG8_MMA(0, 0, At, B0); PG8_MMA(0, 1, At, B1); PG8_BAR; PG8_SCHED;
;             PG8_LDA(At, 0, 1); PG8_STAGE(PG8_SB(0, 0), b2, voffB); PG8_STAGE(PG8_SB(0, 1), b2 + hstepB, voffB); PG8_STAGE(PG8_SA(0, 0), a2, voffA);
;             PG8_WAIT_V(8); PG8_WAIT_L(0); PG8_BAR; PG8_MMA(1, 0, At, B0); PG8_MMA(1, 1, At, B1); PG8_BAR; PG8_SCHED;
;             PG8_LDB(B0, 1, 0); PG8_LDB(B1, 1, 1); PG8_SCHED; PG8_LDA(At, 1, 0); PG8_STAGE(PG8_SA(0, 1), a2 + hstepA, voffA);
;             PG8_WAIT_V(8); PG8_WAIT_L(0); PG8_BAR; PG8_MMA(0, 0, At, B0); PG8_MMA(0, 1, At, B1); PG8_BAR; PG8_SCHED;
;             PG8_LDA(At, 1, 1); PG8_STAGE(PG8_SB(1, 0), b3, voffB); PG8_STAGE(PG8_SB(1, 1), b3 + hstepB, voffB); PG8_STAGE(PG8_SA(1, 0), a3, voffA);
;             PG8_WAIT_V(8); PG8_WAIT_L(0); PG8_BAR; PG8_MMA(1, 0, At, B0); PG8_MMA(1, 1, At, B1); PG8_BAR; PG8_SCHED;
	v_mfma_f32_16x16x32_bf16 v[126:129], v[156:159], v[190:193], 0
	v_mfma_f32_16x16x32_bf16 v[126:129], v[160:163], v[194:197], v[126:129]
	v_mfma_f32_16x16x32_bf16 v[122:125], v[168:171], v[194:197], 0
	v_mfma_f32_16x16x32_bf16 v[122:125], v[164:167], v[190:193], v[122:125]
	v_mfma_f32_16x16x32_bf16 v[118:121], v[174:177], v[190:193], 0
	v_mfma_f32_16x16x32_bf16 v[118:121], v[178:181], v[194:197], v[118:121]
	v_mfma_f32_16x16x32_bf16 v[114:117], v[186:189], v[194:197], 0
	v_mfma_f32_16x16x32_bf16 v[114:117], v[182:185], v[190:193], v[114:117]
	v_mfma_f32_16x16x32_bf16 v[98:101], v[182:185], v[198:201], 0
	v_mfma_f32_16x16x32_bf16 v[98:101], v[186:189], v[202:205], v[98:101]
	v_mfma_f32_16x16x32_bf16 v[102:105], v[178:181], v[202:205], 0
	v_mfma_f32_16x16x32_bf16 v[102:105], v[174:177], v[198:201], v[102:105]
	v_mfma_f32_16x16x32_bf16 v[106:109], v[164:167], v[198:201], 0
	v_mfma_f32_16x16x32_bf16 v[106:109], v[168:171], v[202:205], v[106:109]
	v_mfma_f32_16x16x32_bf16 v[110:113], v[160:163], v[202:205], 0
	v_mfma_f32_16x16x32_bf16 v[110:113], v[156:159], v[198:201], v[110:113]
	v_mfma_f32_16x16x32_bf16 v[94:97], v[156:159], v[206:209], 0
	v_mfma_f32_16x16x32_bf16 v[94:97], v[160:163], v[210:213], v[94:97]
	v_mfma_f32_16x16x32_bf16 v[90:93], v[168:171], v[210:213], 0
	v_mfma_f32_16x16x32_bf16 v[90:93], v[164:167], v[206:209], v[90:93]
	v_mfma_f32_16x16x32_bf16 v[86:89], v[174:177], v[206:209], 0
	v_mfma_f32_16x16x32_bf16 v[86:89], v[178:181], v[210:213], v[86:89]
	v_mfma_f32_16x16x32_bf16 v[82:85], v[186:189], v[210:213], 0
	v_mfma_f32_16x16x32_bf16 v[82:85], v[182:185], v[206:209], v[82:85]
	v_mfma_f32_16x16x32_bf16 v[66:69], v[182:185], v[214:217], 0
	v_mfma_f32_16x16x32_bf16 v[66:69], v[186:189], v[218:221], v[66:69]
	v_mfma_f32_16x16x32_bf16 v[70:73], v[178:181], v[218:221], 0
	v_mfma_f32_16x16x32_bf16 v[70:73], v[174:177], v[214:217], v[70:73]
	v_mfma_f32_16x16x32_bf16 v[74:77], v[164:167], v[214:217], 0
	v_mfma_f32_16x16x32_bf16 v[74:77], v[168:171], v[218:221], v[74:77]
	v_mfma_f32_16x16x32_bf16 v[78:81], v[160:163], v[218:221], 0
	v_mfma_f32_16x16x32_bf16 v[78:81], v[156:159], v[214:217], v[78:81]
	v_mfma_f32_16x16x32_bf16 v[62:65], v[156:159], v[222:225], 0
	v_mfma_f32_16x16x32_bf16 v[62:65], v[160:163], v[226:229], v[62:65]
	v_mfma_f32_16x16x32_bf16 v[58:61], v[168:171], v[226:229], 0
	v_mfma_f32_16x16x32_bf16 v[58:61], v[164:167], v[222:225], v[58:61]
	v_mfma_f32_16x16x32_bf16 v[54:57], v[174:177], v[222:225], 0
	v_mfma_f32_16x16x32_bf16 v[54:57], v[178:181], v[226:229], v[54:57]
	v_mfma_f32_16x16x32_bf16 v[50:53], v[186:189], v[226:229], 0
	v_mfma_f32_16x16x32_bf16 v[50:53], v[182:185], v[222:225], v[50:53]
	v_mfma_f32_16x16x32_bf16 v[34:37], v[182:185], v[230:233], 0
	v_mfma_f32_16x16x32_bf16 v[34:37], v[186:189], v[234:237], v[34:37]
	v_mfma_f32_16x16x32_bf16 v[38:41], v[178:181], v[234:237], 0
	v_mfma_f32_16x16x32_bf16 v[38:41], v[174:177], v[230:233], v[38:41]
	v_mfma_f32_16x16x32_bf16 v[42:45], v[164:167], v[230:233], 0
	v_mfma_f32_16x16x32_bf16 v[42:45], v[168:171], v[234:237], v[42:45]
	v_mfma_f32_16x16x32_bf16 v[46:49], v[160:163], v[234:237], 0
	v_mfma_f32_16x16x32_bf16 v[46:49], v[156:159], v[230:233], v[46:49]
	v_mfma_f32_16x16x32_bf16 v[30:33], v[156:159], v[238:241], 0
	v_mfma_f32_16x16x32_bf16 v[30:33], v[160:163], v[242:245], v[30:33]
	v_mfma_f32_16x16x32_bf16 v[26:29], v[168:171], v[242:245], 0
	v_mfma_f32_16x16x32_bf16 v[26:29], v[164:167], v[238:241], v[26:29]
	v_mfma_f32_16x16x32_bf16 v[22:25], v[174:177], v[238:241], 0
	v_mfma_f32_16x16x32_bf16 v[22:25], v[178:181], v[242:245], v[22:25]
	v_mfma_f32_16x16x32_bf16 v[18:21], v[186:189], v[242:245], 0
	v_mfma_f32_16x16x32_bf16 v[18:21], v[182:185], v[238:241], v[18:21]
	v_mfma_f32_16x16x32_bf16 v[2:5], v[182:185], v[246:249], 0
	v_mfma_f32_16x16x32_bf16 v[2:5], v[186:189], v[250:253], v[2:5]
	v_mfma_f32_16x16x32_bf16 v[6:9], v[178:181], v[250:253], 0
	v_mfma_f32_16x16x32_bf16 v[6:9], v[174:177], v[246:249], v[6:9]
	v_mfma_f32_16x16x32_bf16 v[10:13], v[164:167], v[246:249], 0
	v_mfma_f32_16x16x32_bf16 v[10:13], v[168:171], v[250:253], v[10:13]
	v_mfma_f32_16x16x32_bf16 v[14:17], v[160:163], v[250:253], 0
	v_mfma_f32_16x16x32_bf16 v[14:17], v[156:159], v[246:249], v[14:17]
	s_waitcnt vmcnt(0)
	s_barrier
	ds_read_b128 v[190:193], v155 offset:32768
	ds_read_b128 v[194:197], v155 offset:33792
	ds_read_b128 v[198:201], v155 offset:34816
	s_cmp_eq_u32 s49, 15
	s_cselect_b32 s28, s50, s28
	s_cselect_b32 s29, s51, s29
	s_add_i32 m0, s2, 0x2000
	s_nop 0
	global_load_lds_dwordx4 v132, s[28:29]
	ds_read_b128 v[202:205], v155 offset:35840
	ds_read_b128 v[206:209], v155 offset:36864
	ds_read_b128 v[210:213], v155 offset:37888
	s_add_u32 s30, s28, 0x20000
	s_addc_u32 s31, s29, 0
	s_add_i32 m0, s2, 0x3000
	s_nop 0
	global_load_lds_dwordx4 v132, s[30:31]
	ds_read_b128 v[214:217], v155 offset:38912
	ds_read_b128 v[218:221], v155 offset:39936
	ds_read_b128 v[156:159], v153 offset:32768
	s_add_u32 s30, s28, 0x80000
	s_addc_u32 s31, s29, 0
	s_add_i32 m0, s2, 0x6000
	s_nop 0
	global_load_lds_dwordx4 v132, s[30:31]
	ds_read_b128 v[160:163], v153 offset:33792
	ds_read_b128 v[164:167], v153 offset:34816
	ds_read_b128 v[168:171], v153 offset:35840
	s_add_u32 s30, s28, 0xa0000
	s_addc_u32 s31, s29, 0
	s_add_i32 m0, s2, 0x7000
	s_nop 0
	global_load_lds_dwordx4 v132, s[30:31]
	ds_read_b128 v[174:177], v153 offset:49152
	ds_read_b128 v[178:181], v153 offset:50176
	ds_read_b128 v[182:185], v153 offset:51200
	s_add_u32 s34, s28, 0x80
	s_addc_u32 s35, s29, 0
	s_add_i32 m0, s2, 0x8000
	s_nop 0
	global_load_lds_dwordx4 v136, s[34:35]
	ds_read_b128 v[186:189], v153 offset:52224
	ds_read_b128 v[222:225], v155 offset:49152
	ds_read_b128 v[226:229], v155 offset:50176
	s_add_u32 s30, s34, 0x20000
	s_addc_u32 s31, s35, 0
	s_add_i32 m0, s2, 0x9000
	s_nop 0
	global_load_lds_dwordx4 v136, s[30:31]
	ds_read_b128 v[230:233], v155 offset:51200
	ds_read_b128 v[234:237], v155 offset:52224
	ds_read_b128 v[238:241], v155 offset:53248
	s_add_u32 s30, s34, 0x80000
	s_addc_u32 s31, s35, 0
	s_add_i32 m0, s2, 0xc000
	s_nop 0
	global_load_lds_dwordx4 v136, s[30:31]
	ds_read_b128 v[242:245], v155 offset:54272
	ds_read_b128 v[246:249], v155 offset:55296
	ds_read_b128 v[250:253], v155 offset:56320
	s_add_u32 s30, s34, 0xa0000
	s_addc_u32 s31, s35, 0
	s_add_i32 m0, s2, 0xd000
	s_nop 0
	global_load_lds_dwordx4 v136, s[30:31]
	s_add_u32 s28, s28, 0x80
	s_addc_u32 s29, s29, 0
	s_waitcnt vmcnt(8) lgkmcnt(0)
	s_barrier
; #define PG8_STAGE(bufoff, gbase, voff) do { _Pragma("unroll") for (int _i = 0; _i < 2; ++_i) \
;         __builtin_amdgcn_global_load_lds((const unsigned*)((const char*)(gbase) + (voff)[_i]), (PG8_LAS unsigned*)(lds + (bufoff) + ldsw + _i * 8192), 16, 0, 0); } while (0)
; #define PG8_LDA(dst, b, h) do { _Pragma("unroll") for (int m = 0; m < 4; ++m) _Pragma("unroll") for (int k = 0; k < 2; ++k) dst[m][k] = *(const PG8_LAS bf16x8*)(lds + PG8_SA(b, h) + aoff + m * 2048 + k * 1024); } while (0)
; #define PG8_LDB(dst, b, h) do { _Pragma("unroll") for (int n = 0; n < 2; ++n) _Pragma("unroll") for (int k = 0; k < 2; ++k) dst[n][k] = *(const PG8_LAS bf16x8*)(lds + PG8_SB(b, h) + boff + n * 2048 + k * 1024); } while (0)
; #define PG8_MMA(ai, bj, At, Bt) do { __builtin_amdgcn_s_setprio(1); _Pragma("unroll") for (int m = 0; m < 4; ++m) _Pragma("unroll") for (int n = 0; n < 2; ++n) _Pragma("unroll") for (int k = 0; k < 2; ++k) \
;         acc[ai][bj][m][n] = __builtin_amdgcn_mfma_f32_16x16x32_bf16(Bt[n][k], At[m][k], acc[ai][bj][m][n], 0, 0, 0); __builtin_amdgcn_s_setprio(0); } while (0)
; #define PG8_WAIT_V(n) asm volatile("s_waitcnt vmcnt(" #n ")" ::: "memory")
; #define PG8_WAIT_L(n) asm volatile("s_waitcnt lgkmcnt(" #n ")" ::: "memory")
; #define PG8_BAR __builtin_amdgcn_s_barrier()
; #define PG8_SCHED __builtin_amdgcn_sched_barrier(0)
; template <class Epi, class Sched, bool ALIGN_EPI>
; __device__ __forceinline__ void gemm_phase(PG8_LAS unsigned char* lds, const Gemm g, const Sched& S, const Epi& E) {
;     ...
;             PG8_LDB(B0, 1, 0); PG8_LDB(B1, 1, 1); PG8_SCHED; PG8_LDA(At, 1, 0); PG8_STAGE(PG8_SA(0, 1), a2 + hstepA, voffA);
;             PG8_WAIT_V(8); PG8_WAIT_L(0); PG8_BAR; PG8_MMA(0, 0, At, B0); PG8_MMA(0, 1, At, B1); PG8_BAR; PG8_SCHED;
;             PG8_LDA(At, 1, 1); PG8_STAGE(PG8_SB(1, 0), b3, voffB); PG8_STAGE(PG8_SB(1, 1), b3 + hstepB, voffB); PG8_STAGE(PG8_SA(1, 0), a3, voffA);
;             PG8_WAIT_V(8); PG8_WAIT_L(0); PG8_BAR; PG8_MMA(1, 0, At, B0); PG8_MMA(1, 1, At, B1); PG8_BAR; PG8_SCHED;
	v_mfma_f32_16x16x32_bf16 v[126:129], v[156:159], v[190:193], v[126:129]
	v_mfma_f32_16x16x32_bf16 v[126:129], v[160:163], v[194:197], v[126:129]
	v_mfma_f32_16x16x32_bf16 v[122:125], v[168:171], v[194:197], v[122:125]
	v_mfma_f32_16x16x32_bf16 v[122:125], v[164:167], v[190:193], v[122:125]
	v_mfma_f32_16x16x32_bf16 v[118:121], v[174:177], v[190:193], v[118:121]
	v_mfma_f32_16x16x32_bf16 v[118:121], v[178:181], v[194:197], v[118:121]
	v_mfma_f32_16x16x32_bf16 v[114:117], v[186:189], v[194:197], v[114:117]
	v_mfma_f32_16x16x32_bf16 v[114:117], v[182:185], v[190:193], v[114:117]
	v_mfma_f32_16x16x32_bf16 v[98:101], v[182:185], v[198:201], v[98:101]
	v_mfma_f32_16x16x32_bf16 v[98:101], v[186:189], v[202:205], v[98:101]
	v_mfma_f32_16x16x32_bf16 v[102:105], v[178:181], v[202:205], v[102:105]
	v_mfma_f32_16x16x32_bf16 v[102:105], v[174:177], v[198:201], v[102:105]
	v_mfma_f32_16x16x32_bf16 v[106:109], v[164:167], v[198:201], v[106:109]
	v_mfma_f32_16x16x32_bf16 v[106:109], v[168:171], v[202:205], v[106:109]
	v_mfma_f32_16x16x32_bf16 v[110:113], v[160:163], v[202:205], v[110:113]
	v_mfma_f32_16x16x32_bf16 v[110:113], v[156:159], v[198:201], v[110:113]
	v_mfma_f32_16x16x32_bf16 v[94:97], v[156:159], v[206:209], v[94:97]
	v_mfma_f32_16x16x32_bf16 v[94:97], v[160:163], v[210:213], v[94:97]
	v_mfma_f32_16x16x32_bf16 v[90:93], v[168:171], v[210:213], v[90:93]
	v_mfma_f32_16x16x32_bf16 v[90:93], v[164:167], v[206:209], v[90:93]
	v_mfma_f32_16x16x32_bf16 v[86:89], v[174:177], v[206:209], v[86:89]
	v_mfma_f32_16x16x32_bf16 v[86:89], v[178:181], v[210:213], v[86:89]
	v_mfma_f32_16x16x32_bf16 v[82:85], v[186:189], v[210:213], v[82:85]
	v_mfma_f32_16x16x32_bf16 v[82:85], v[182:185], v[206:209], v[82:85]
	v_mfma_f32_16x16x32_bf16 v[66:69], v[182:185], v[214:217], v[66:69]
	v_mfma_f32_16x16x32_bf16 v[66:69], v[186:189], v[218:221], v[66:69]
	v_mfma_f32_16x16x32_bf16 v[70:73], v[178:181], v[218:221], v[70:73]
	v_mfma_f32_16x16x32_bf16 v[70:73], v[174:177], v[214:217], v[70:73]
	v_mfma_f32_16x16x32_bf16 v[74:77], v[164:167], v[214:217], v[74:77]
	v_mfma_f32_16x16x32_bf16 v[74:77], v[168:171], v[218:221], v[74:77]
	v_mfma_f32_16x16x32_bf16 v[78:81], v[160:163], v[218:221], v[78:81]
	v_mfma_f32_16x16x32_bf16 v[78:81], v[156:159], v[214:217], v[78:81]
	v_mfma_f32_16x16x32_bf16 v[62:65], v[156:159], v[222:225], v[62:65]
	v_mfma_f32_16x16x32_bf16 v[62:65], v[160:163], v[226:229], v[62:65]
	v_mfma_f32_16x16x32_bf16 v[58:61], v[168:171], v[226:229], v[58:61]
	v_mfma_f32_16x16x32_bf16 v[58:61], v[164:167], v[222:225], v[58:61]
	v_mfma_f32_16x16x32_bf16 v[54:57], v[174:177], v[222:225], v[54:57]
	v_mfma_f32_16x16x32_bf16 v[54:57], v[178:181], v[226:229], v[54:57]
	v_mfma_f32_16x16x32_bf16 v[50:53], v[186:189], v[226:229], v[50:53]
	v_mfma_f32_16x16x32_bf16 v[50:53], v[182:185], v[222:225], v[50:53]
	v_mfma_f32_16x16x32_bf16 v[34:37], v[182:185], v[230:233], v[34:37]
	v_mfma_f32_16x16x32_bf16 v[34:37], v[186:189], v[234:237], v[34:37]
	v_mfma_f32_16x16x32_bf16 v[38:41], v[178:181], v[234:237], v[38:41]
	v_mfma_f32_16x16x32_bf16 v[38:41], v[174:177], v[230:233], v[38:41]
	v_mfma_f32_16x16x32_bf16 v[42:45], v[164:167], v[230:233], v[42:45]
	v_mfma_f32_16x16x32_bf16 v[42:45], v[168:171], v[234:237], v[42:45]
	v_mfma_f32_16x16x32_bf16 v[46:49], v[160:163], v[234:237], v[46:49]
	v_mfma_f32_16x16x32_bf16 v[46:49], v[156:159], v[230:233], v[46:49]
	v_mfma_f32_16x16x32_bf16 v[30:33], v[156:159], v[238:241], v[30:33]
	v_mfma_f32_16x16x32_bf16 v[30:33], v[160:163], v[242:245], v[30:33]
	v_mfma_f32_16x16x32_bf16 v[26:29], v[168:171], v[242:245], v[26:29]
	v_mfma_f32_16x16x32_bf16 v[26:29], v[164:167], v[238:241], v[26:29]
	v_mfma_f32_16x16x32_bf16 v[22:25], v[174:177], v[238:241], v[22:25]
	v_mfma_f32_16x16x32_bf16 v[22:25], v[178:181], v[242:245], v[22:25]
	v_mfma_f32_16x16x32_bf16 v[18:21], v[186:189], v[242:245], v[18:21]
	v_mfma_f32_16x16x32_bf16 v[18:21], v[182:185], v[238:241], v[18:21]
	v_mfma_f32_16x16x32_bf16 v[2:5], v[182:185], v[246:249], v[2:5]
	v_mfma_f32_16x16x32_bf16 v[2:5], v[186:189], v[250:253], v[2:5]
	v_mfma_f32_16x16x32_bf16 v[6:9], v[178:181], v[250:253], v[6:9]
	v_mfma_f32_16x16x32_bf16 v[6:9], v[174:177], v[246:249], v[6:9]
	v_mfma_f32_16x16x32_bf16 v[10:13], v[164:167], v[246:249], v[10:13]
	v_mfma_f32_16x16x32_bf16 v[10:13], v[168:171], v[250:253], v[10:13]
	v_mfma_f32_16x16x32_bf16 v[14:17], v[160:163], v[250:253], v[14:17]
	v_mfma_f32_16x16x32_bf16 v[14:17], v[156:159], v[246:249], v[14:17]
	s_waitcnt vmcnt(0)
	s_barrier
	s_add_i32 s49, s49, 1
; #define PG8_STAGE(bufoff, gbase, voff) do { _Pragma("unroll") for (int _i = 0; _i < 2; ++_i) \
;         __builtin_amdgcn_global_load_lds((const unsigned*)((const char*)(gbase) + (voff)[_i]), (PG8_LAS unsigned*)(lds + (bufoff) + ldsw + _i * 8192), 16, 0, 0); } while (0)
; #define PG8_LDA(dst, b, h) do { _Pragma("unroll") for (int m = 0; m < 4; ++m) _Pragma("unroll") for (int k = 0; k < 2; ++k) dst[m][k] = *(const PG8_LAS bf16x8*)(lds + PG8_SA(b, h) + aoff + m * 2048 + k * 1024); } while (0)
; #define PG8_LDB(dst, b, h) do { _Pragma("unroll") for (int n = 0; n < 2; ++n) _Pragma("unroll") for (int k = 0; k < 2; ++k) dst[n][k] = *(const PG8_LAS bf16x8*)(lds + PG8_SB(b, h) + boff + n * 2048 + k * 1024); } while (0)
; #define PG8_MMA(ai, bj, At, Bt) do { __builtin_amdgcn_s_setprio(1); _Pragma("unroll") for (int m = 0; m < 4; ++m) _Pragma("unroll") for (int n = 0; n < 2; ++n) _Pragma("unroll") for (int k = 0; k < 2; ++k) \
;         acc[ai][bj][m][n] = __builtin_amdgcn_mfma_f32_16x16x32_bf16(Bt[n][k], At[m][k], acc[ai][bj][m][n], 0, 0, 0); __builtin_amdgcn_s_setprio(0); } while (0)
; #define PG8_WAIT_V(n) asm volatile("s_waitcnt vmcnt(" #n ")" ::: "memory")
; #define PG8_WAIT_L(n) asm volatile("s_waitcnt lgkmcnt(" #n ")" ::: "memory")
; #define PG8_BAR __builtin_amdgcn_s_barrier()
; #define PG8_SCHED __builtin_amdgcn_sched_barrier(0)
; template <class Epi, class Sched, bool ALIGN_EPI>
; __device__ __forceinline__ void gemm_phase(PG8_LAS unsigned char* lds, const Gemm g, const Sched& S, const Epi& E) {
;     ...
;             PG8_LDB(B0, 0, 0); PG8_LDB(B1, 0, 1); PG8_SCHED; PG8_LDA(At, 0, 0); PG8_STAGE(PG8_SA(1, 1), a1 + hstepA, voffA);
;             PG8_WAIT_V(8); PG8_WAIT_L(0); PG8_BAR; PG8_MMA(0, 0, At, B0); PG8_MMA(0, 1, At, B1); PG8_BAR; PG8_SCHED;
;             PG8_LDA(At, 0, 1); PG8_STAGE(PG8_SB(0, 0), b2, voffB); PG8_STAGE(PG8_SB(0, 1), b2 + hstepB, voffB); PG8_STAGE(PG8_SA(0, 0), a2, voffA);
;             PG8_WAIT_V(8); PG8_WAIT_L(0); PG8_BAR; PG8_MMA(1, 0, At, B0); PG8_MMA(1, 1, At, B1); PG8_BAR; PG8_SCHED;
.Lp8k_B_loop:
	ds_read_b128 v[190:193], v155 offset:0
	ds_read_b128 v[194:197], v155 offset:1024
	ds_read_b128 v[198:201], v155 offset:2048
	s_add_i32 m0, s2, 0xa000
	s_nop 0
	global_load_lds_dwordx4 v132, s[28:29]
	ds_read_b128 v[202:205], v155 offset:3072
	ds_read_b128 v[206:209], v155 offset:4096
	ds_read_b128 v[210:213], v155 offset:5120
	s_add_u32 s30, s28, 0x20000
	s_addc_u32 s31, s29, 0
	s_add_i32 m0, s2, 0xb000
	s_nop 0
	global_load_lds_dwordx4 v132, s[30:31]
	ds_read_b128 v[214:217], v155 offset:6144
	ds_read_b128 v[218:221], v155 offset:7168
	ds_read_b128 v[156:159], v153 offset:0
	s_add_u32 s30, s28, 0x80000
	s_addc_u32 s31, s29, 0
	s_add_i32 m0, s2, 0xe000
	s_nop 0
	global_load_lds_dwordx4 v132, s[30:31]
	ds_read_b128 v[160:163], v153 offset:1024
	ds_read_b128 v[164:167], v153 offset:2048
	ds_read_b128 v[168:171], v153 offset:3072
	s_add_u32 s30, s28, 0xa0000
	s_addc_u32 s31, s29, 0
	s_add_i32 m0, s2, 0xf000
	s_nop 0
	global_load_lds_dwordx4 v132, s[30:31]
	ds_read_b128 v[174:177], v153 offset:16384
	ds_read_b128 v[178:181], v153 offset:17408
	ds_read_b128 v[182:185], v153 offset:18432
	s_add_u32 s34, s28, 0x80
	s_addc_u32 s35, s29, 0
	s_cmp_eq_u32 s49, 15
	s_cselect_b32 s34, s50, s34
	s_cselect_b32 s35, s51, s35
	s_add_i32 m0, s2, 0x0
	s_nop 0
	global_load_lds_dwordx4 v136, s[34:35]
	ds_read_b128 v[186:189], v153 offset:19456
	ds_read_b128 v[222:225], v155 offset:16384
	ds_read_b128 v[226:229], v155 offset:17408
	s_add_u32 s30, s34, 0x20000
	s_addc_u32 s31, s35, 0
	s_add_i32 m0, s2, 0x1000
	s_nop 0
	global_load_lds_dwordx4 v136, s[30:31]
	ds_read_b128 v[230:233], v155 offset:18432
	ds_read_b128 v[234:237], v155 offset:19456
	ds_read_b128 v[238:241], v155 offset:20480
	s_add_u32 s30, s34, 0x80000
	s_addc_u32 s31, s35, 0
	s_add_i32 m0, s2, 0x4000
	s_nop 0
	global_load_lds_dwordx4 v136, s[30:31]
	ds_read_b128 v[242:245], v155 offset:21504
	ds_read_b128 v[246:249], v155 offset:22528
	ds_read_b128 v[250:253], v155 offset:23552
	s_add_u32 s30, s34, 0xa0000
	s_addc_u32 s31, s35, 0
	s_add_i32 m0, s2, 0x5000
	s_nop 0
	global_load_lds_dwordx4 v136, s[30:31]
	s_add_u32 s28, s28, 0x80
	s_addc_u32 s29, s29, 0
	s_waitcnt vmcnt(8) lgkmcnt(0)
	s_barrier
	v_mfma_f32_16x16x32_bf16 v[126:129], v[156:159], v[190:193], v[126:129]
	v_mfma_f32_16x16x32_bf16 v[126:129], v[160:163], v[194:197], v[126:129]
	v_mfma_f32_16x16x32_bf16 v[122:125], v[168:171], v[194:197], v[122:125]
	v_mfma_f32_16x16x32_bf16 v[122:125], v[164:167], v[190:193], v[122:125]
	v_mfma_f32_16x16x32_bf16 v[118:121], v[174:177], v[190:193], v[118:121]
	v_mfma_f32_16x16x32_bf16 v[118:121], v[178:181], v[194:197], v[118:121]
	v_mfma_f32_16x16x32_bf16 v[114:117], v[186:189], v[194:197], v[114:117]
	v_mfma_f32_16x16x32_bf16 v[114:117], v[182:185], v[190:193], v[114:117]
	v_mfma_f32_16x16x32_bf16 v[98:101], v[182:185], v[198:201], v[98:101]
	v_mfma_f32_16x16x32_bf16 v[98:101], v[186:189], v[202:205], v[98:101]
	v_mfma_f32_16x16x32_bf16 v[102:105], v[178:181], v[202:205], v[102:105]
	v_mfma_f32_16x16x32_bf16 v[102:105], v[174:177], v[198:201], v[102:105]
	v_mfma_f32_16x16x32_bf16 v[106:109], v[164:167], v[198:201], v[106:109]
	v_mfma_f32_16x16x32_bf16 v[106:109], v[168:171], v[202:205], v[106:109]
	v_mfma_f32_16x16x32_bf16 v[110:113], v[160:163], v[202:205], v[110:113]
	v_mfma_f32_16x16x32_bf16 v[110:113], v[156:159], v[198:201], v[110:113]
	v_mfma_f32_16x16x32_bf16 v[94:97], v[156:159], v[206:209], v[94:97]
	v_mfma_f32_16x16x32_bf16 v[94:97], v[160:163], v[210:213], v[94:97]
	v_mfma_f32_16x16x32_bf16 v[90:93], v[168:171], v[210:213], v[90:93]
	v_mfma_f32_16x16x32_bf16 v[90:93], v[164:167], v[206:209], v[90:93]
	v_mfma_f32_16x16x32_bf16 v[86:89], v[174:177], v[206:209], v[86:89]
	v_mfma_f32_16x16x32_bf16 v[86:89], v[178:181], v[210:213], v[86:89]
	v_mfma_f32_16x16x32_bf16 v[82:85], v[186:189], v[210:213], v[82:85]
	v_mfma_f32_16x16x32_bf16 v[82:85], v[182:185], v[206:209], v[82:85]
	v_mfma_f32_16x16x32_bf16 v[66:69], v[182:185], v[214:217], v[66:69]
	v_mfma_f32_16x16x32_bf16 v[66:69], v[186:189], v[218:221], v[66:69]
	v_mfma_f32_16x16x32_bf16 v[70:73], v[178:181], v[218:221], v[70:73]
	v_mfma_f32_16x16x32_bf16 v[70:73], v[174:177], v[214:217], v[70:73]
	v_mfma_f32_16x16x32_bf16 v[74:77], v[164:167], v[214:217], v[74:77]
	v_mfma_f32_16x16x32_bf16 v[74:77], v[168:171], v[218:221], v[74:77]
	v_mfma_f32_16x16x32_bf16 v[78:81], v[160:163], v[218:221], v[78:81]
	v_mfma_f32_16x16x32_bf16 v[78:81], v[156:159], v[214:217], v[78:81]
	v_mfma_f32_16x16x32_bf16 v[62:65], v[156:159], v[222:225], v[62:65]
	v_mfma_f32_16x16x32_bf16 v[62:65], v[160:163], v[226:229], v[62:65]
	v_mfma_f32_16x16x32_bf16 v[58:61], v[168:171], v[226:229], v[58:61]
	v_mfma_f32_16x16x32_bf16 v[58:61], v[164:167], v[222:225], v[58:61]
	v_mfma_f32_16x16x32_bf16 v[54:57], v[174:177], v[222:225], v[54:57]
	v_mfma_f32_16x16x32_bf16 v[54:57], v[178:181], v[226:229], v[54:57]
	v_mfma_f32_16x16x32_bf16 v[50:53], v[186:189], v[226:229], v[50:53]
	v_mfma_f32_16x16x32_bf16 v[50:53], v[182:185], v[222:225], v[50:53]
	v_mfma_f32_16x16x32_bf16 v[34:37], v[182:185], v[230:233], v[34:37]
	v_mfma_f32_16x16x32_bf16 v[34:37], v[186:189], v[234:237], v[34:37]
	v_mfma_f32_16x16x32_bf16 v[38:41], v[178:181], v[234:237], v[38:41]
	v_mfma_f32_16x16x32_bf16 v[38:41], v[174:177], v[230:233], v[38:41]
	v_mfma_f32_16x16x32_bf16 v[42:45], v[164:167], v[230:233], v[42:45]
	v_mfma_f32_16x16x32_bf16 v[42:45], v[168:171], v[234:237], v[42:45]
	v_mfma_f32_16x16x32_bf16 v[46:49], v[160:163], v[234:237], v[46:49]
	v_mfma_f32_16x16x32_bf16 v[46:49], v[156:159], v[230:233], v[46:49]
	v_mfma_f32_16x16x32_bf16 v[30:33], v[156:159], v[238:241], v[30:33]
	v_mfma_f32_16x16x32_bf16 v[30:33], v[160:163], v[242:245], v[30:33]
	v_mfma_f32_16x16x32_bf16 v[26:29], v[168:171], v[242:245], v[26:29]
	v_mfma_f32_16x16x32_bf16 v[26:29], v[164:167], v[238:241], v[26:29]
	v_mfma_f32_16x16x32_bf16 v[22:25], v[174:177], v[238:241], v[22:25]
	v_mfma_f32_16x16x32_bf16 v[22:25], v[178:181], v[242:245], v[22:25]
	v_mfma_f32_16x16x32_bf16 v[18:21], v[186:189], v[242:245], v[18:21]
	v_mfma_f32_16x16x32_bf16 v[18:21], v[182:185], v[238:241], v[18:21]
	v_mfma_f32_16x16x32_bf16 v[2:5], v[182:185], v[246:249], v[2:5]
	v_mfma_f32_16x16x32_bf16 v[2:5], v[186:189], v[250:253], v[2:5]
	v_mfma_f32_16x16x32_bf16 v[6:9], v[178:181], v[250:253], v[6:9]
	v_mfma_f32_16x16x32_bf16 v[6:9], v[174:177], v[246:249], v[6:9]
	v_mfma_f32_16x16x32_bf16 v[10:13], v[164:167], v[246:249], v[10:13]
	v_mfma_f32_16x16x32_bf16 v[10:13], v[168:171], v[250:253], v[10:13]
	v_mfma_f32_16x16x32_bf16 v[14:17], v[160:163], v[250:253], v[14:17]
	v_mfma_f32_16x16x32_bf16 v[14:17], v[156:159], v[246:249], v[14:17]
	s_waitcnt vmcnt(0)
	s_barrier
; #define PG8_STAGE(bufoff, gbase, voff) do { _Pragma("unroll") for (int _i = 0; _i < 2; ++_i) \
;         __builtin_amdgcn_global_load_lds((const unsigned*)((const char*)(gbase) + (voff)[_i]), (PG8_LAS unsigned*)(lds + (bufoff) + ldsw + _i * 8192), 16, 0, 0); } while (0)
; #define PG8_LDA(dst, b, h) do { _Pragma("unroll") for (int m = 0; m < 4; ++m) _Pragma("unroll") for (int k = 0; k < 2; ++k) dst[m][k] = *(const PG8_LAS bf16x8*)(lds + PG8_SA(b, h) + aoff + m * 2048 + k * 1024); } while (0)
; #define PG8_LDB(dst, b, h) do { _Pragma("unroll") for (int n = 0; n < 2; ++n) _Pragma("unroll") for (int k = 0; k < 2; ++k) dst[n][k] = *(const PG8_LAS bf16x8*)(lds + PG8_SB(b, h) + boff + n * 2048 + k * 1024); } while (0)
; #define PG8_MMA(ai, bj, At, Bt) do { __builtin_amdgcn_s_setprio(1); _Pragma("unroll") for (int m = 0; m < 4; ++m) _Pragma("unroll") for (int n = 0; n < 2; ++n) _Pragma("unroll") for (int k = 0; k < 2; ++k) \
;         acc[ai][bj][m][n] = __builtin_amdgcn_mfma_f32_16x16x32_bf16(Bt[n][k], At[m][k], acc[ai][bj][m][n], 0, 0, 0); __builtin_amdgcn_s_setprio(0); } while (0)
; #define PG8_WAIT_V(n) asm volatile("s_waitcnt vmcnt(" #n ")" ::: "memory")
; #define PG8_WAIT_L(n) asm volatile("s_waitcnt lgkmcnt(" #n ")" ::: "memory")
; #define PG8_BAR __builtin_amdgcn_s_barrier()
; #define PG8_SCHED __builtin_amdgcn_sched_barrier(0)
; template <class Epi, class Sched, bool ALIGN_EPI>
; __device__ __forceinline__ void gemm_phase(PG8_LAS unsigned char* lds, const Gemm g, const Sched& S, const Epi& E) {
;     ...
;             PG8_LDB(B0, 1, 0); PG8_LDB(B1, 1, 1); PG8_SCHED; PG8_LDA(At, 1, 0); PG8_STAGE(PG8_SA(0, 1), a2 + hstepA, voffA);
;             PG8_WAIT_V(8); PG8_WAIT_L(0); PG8_BAR; PG8_MMA(0, 0, At, B0); PG8_MMA(0, 1, At, B1); PG8_BAR; PG8_SCHED;
;             PG8_LDA(At, 1, 1); PG8_STAGE(PG8_SB(1, 0), b3, voffB); PG8_STAGE(PG8_SB(1, 1), b3 + hstepB, voffB); PG8_STAGE(PG8_SA(1, 0), a3, voffA);
;             PG8_WAIT_V(8); PG8_WAIT_L(0); PG8_BAR; PG8_MMA(1, 0, At, B0); PG8_MMA(1, 1, At, B1); PG8_BAR; PG8_SCHED;
;         }
	ds_read_b128 v[190:193], v155 offset:32768
	ds_read_b128 v[194:197], v155 offset:33792
	ds_read_b128 v[198:201], v155 offset:34816
	s_cmp_eq_u32 s49, 15
	s_cselect_b32 s28, s50, s28
	s_cselect_b32 s29, s51, s29
	s_add_i32 m0, s2, 0x2000
	s_nop 0
	global_load_lds_dwordx4 v132, s[28:29]
	ds_read_b128 v[202:205], v155 offset:35840
	ds_read_b128 v[206:209], v155 offset:36864
	ds_read_b128 v[210:213], v155 offset:37888
	s_add_u32 s30, s28, 0x20000
	s_addc_u32 s31, s29, 0
	s_add_i32 m0, s2, 0x3000
	s_nop 0
	global_load_lds_dwordx4 v132, s[30:31]
	ds_read_b128 v[214:217], v155 offset:38912
	ds_read_b128 v[218:221], v155 offset:39936
	ds_read_b128 v[156:159], v153 offset:32768
	s_add_u32 s30, s28, 0x80000
	s_addc_u32 s31, s29, 0
	s_add_i32 m0, s2, 0x6000
	s_nop 0
	global_load_lds_dwordx4 v132, s[30:31]
	ds_read_b128 v[160:163], v153 offset:33792
	ds_read_b128 v[164:167], v153 offset:34816
	ds_read_b128 v[168:171], v153 offset:35840
	s_add_u32 s30, s28, 0xa0000
	s_addc_u32 s31, s29, 0
	s_add_i32 m0, s2, 0x7000
	s_nop 0
	global_load_lds_dwordx4 v132, s[30:31]
	ds_read_b128 v[174:177], v153 offset:49152
	ds_read_b128 v[178:181], v153 offset:50176
	ds_read_b128 v[182:185], v153 offset:51200
	s_add_u32 s34, s28, 0x80
	s_addc_u32 s35, s29, 0
	s_add_i32 m0, s2, 0x8000
	s_nop 0
	global_load_lds_dwordx4 v136, s[34:35]
	ds_read_b128 v[186:189], v153 offset:52224
	ds_read_b128 v[222:225], v155 offset:49152
	ds_read_b128 v[226:229], v155 offset:50176
	s_add_u32 s30, s34, 0x20000
	s_addc_u32 s31, s35, 0
	s_add_i32 m0, s2, 0x9000
	s_nop 0
	global_load_lds_dwordx4 v136, s[30:31]
	ds_read_b128 v[230:233], v155 offset:51200
	ds_read_b128 v[234:237], v155 offset:52224
	ds_read_b128 v[238:241], v155 offset:53248
	s_add_u32 s30, s34, 0x80000
	s_addc_u32 s31, s35, 0
	s_add_i32 m0, s2, 0xc000
	s_nop 0
	global_load_lds_dwordx4 v136, s[30:31]
	ds_read_b128 v[242:245], v155 offset:54272
	ds_read_b128 v[246:249], v155 offset:55296
	ds_read_b128 v[250:253], v155 offset:56320
	s_add_u32 s30, s34, 0xa0000
	s_addc_u32 s31, s35, 0
	s_add_i32 m0, s2, 0xd000
	s_nop 0
	global_load_lds_dwordx4 v136, s[30:31]
	s_add_u32 s28, s28, 0x80
	s_addc_u32 s29, s29, 0
	s_waitcnt vmcnt(8) lgkmcnt(0)
	s_barrier
	v_mfma_f32_16x16x32_bf16 v[126:129], v[156:159], v[190:193], v[126:129]
	v_mfma_f32_16x16x32_bf16 v[126:129], v[160:163], v[194:197], v[126:129]
	v_mfma_f32_16x16x32_bf16 v[122:125], v[168:171], v[194:197], v[122:125]
	v_mfma_f32_16x16x32_bf16 v[122:125], v[164:167], v[190:193], v[122:125]
	v_mfma_f32_16x16x32_bf16 v[118:121], v[174:177], v[190:193], v[118:121]
	v_mfma_f32_16x16x32_bf16 v[118:121], v[178:181], v[194:197], v[118:121]
	v_mfma_f32_16x16x32_bf16 v[114:117], v[186:189], v[194:197], v[114:117]
	v_mfma_f32_16x16x32_bf16 v[114:117], v[182:185], v[190:193], v[114:117]
	v_mfma_f32_16x16x32_bf16 v[98:101], v[182:185], v[198:201], v[98:101]
	v_mfma_f32_16x16x32_bf16 v[98:101], v[186:189], v[202:205], v[98:101]
	v_mfma_f32_16x16x32_bf16 v[102:105], v[178:181], v[202:205], v[102:105]
	v_mfma_f32_16x16x32_bf16 v[102:105], v[174:177], v[198:201], v[102:105]
	v_mfma_f32_16x16x32_bf16 v[106:109], v[164:167], v[198:201], v[106:109]
	v_mfma_f32_16x16x32_bf16 v[106:109], v[168:171], v[202:205], v[106:109]
	v_mfma_f32_16x16x32_bf16 v[110:113], v[160:163], v[202:205], v[110:113]
	v_mfma_f32_16x16x32_bf16 v[110:113], v[156:159], v[198:201], v[110:113]
	v_mfma_f32_16x16x32_bf16 v[94:97], v[156:159], v[206:209], v[94:97]
	v_mfma_f32_16x16x32_bf16 v[94:97], v[160:163], v[210:213], v[94:97]
	v_mfma_f32_16x16x32_bf16 v[90:93], v[168:171], v[210:213], v[90:93]
	v_mfma_f32_16x16x32_bf16 v[90:93], v[164:167], v[206:209], v[90:93]
	v_mfma_f32_16x16x32_bf16 v[86:89], v[174:177], v[206:209], v[86:89]
	v_mfma_f32_16x16x32_bf16 v[86:89], v[178:181], v[210:213], v[86:89]
	v_mfma_f32_16x16x32_bf16 v[82:85], v[186:189], v[210:213], v[82:85]
	v_mfma_f32_16x16x32_bf16 v[82:85], v[182:185], v[206:209], v[82:85]
	v_mfma_f32_16x16x32_bf16 v[66:69], v[182:185], v[214:217], v[66:69]
	v_mfma_f32_16x16x32_bf16 v[66:69], v[186:189], v[218:221], v[66:69]
	v_mfma_f32_16x16x32_bf16 v[70:73], v[178:181], v[218:221], v[70:73]
	v_mfma_f32_16x16x32_bf16 v[70:73], v[174:177], v[214:217], v[70:73]
	v_mfma_f32_16x16x32_bf16 v[74:77], v[164:167], v[214:217], v[74:77]
	v_mfma_f32_16x16x32_bf16 v[74:77], v[168:171], v[218:221], v[74:77]
	v_mfma_f32_16x16x32_bf16 v[78:81], v[160:163], v[218:221], v[78:81]
	v_mfma_f32_16x16x32_bf16 v[78:81], v[156:159], v[214:217], v[78:81]
	v_mfma_f32_16x16x32_bf16 v[62:65], v[156:159], v[222:225], v[62:65]
	v_mfma_f32_16x16x32_bf16 v[62:65], v[160:163], v[226:229], v[62:65]
	v_mfma_f32_16x16x32_bf16 v[58:61], v[168:171], v[226:229], v[58:61]
	v_mfma_f32_16x16x32_bf16 v[58:61], v[164:167], v[222:225], v[58:61]
	v_mfma_f32_16x16x32_bf16 v[54:57], v[174:177], v[222:225], v[54:57]
	v_mfma_f32_16x16x32_bf16 v[54:57], v[178:181], v[226:229], v[54:57]
	v_mfma_f32_16x16x32_bf16 v[50:53], v[186:189], v[226:229], v[50:53]
	v_mfma_f32_16x16x32_bf16 v[50:53], v[182:185], v[222:225], v[50:53]
	v_mfma_f32_16x16x32_bf16 v[34:37], v[182:185], v[230:233], v[34:37]
	v_mfma_f32_16x16x32_bf16 v[34:37], v[186:189], v[234:237], v[34:37]
	v_mfma_f32_16x16x32_bf16 v[38:41], v[178:181], v[234:237], v[38:41]
	v_mfma_f32_16x16x32_bf16 v[38:41], v[174:177], v[230:233], v[38:41]
	v_mfma_f32_16x16x32_bf16 v[42:45], v[164:167], v[230:233], v[42:45]
	v_mfma_f32_16x16x32_bf16 v[42:45], v[168:171], v[234:237], v[42:45]
	v_mfma_f32_16x16x32_bf16 v[46:49], v[160:163], v[234:237], v[46:49]
	v_mfma_f32_16x16x32_bf16 v[46:49], v[156:159], v[230:233], v[46:49]
	v_mfma_f32_16x16x32_bf16 v[30:33], v[156:159], v[238:241], v[30:33]
	v_mfma_f32_16x16x32_bf16 v[30:33], v[160:163], v[242:245], v[30:33]
	v_mfma_f32_16x16x32_bf16 v[26:29], v[168:171], v[242:245], v[26:29]
	v_mfma_f32_16x16x32_bf16 v[26:29], v[164:167], v[238:241], v[26:29]
	v_mfma_f32_16x16x32_bf16 v[22:25], v[174:177], v[238:241], v[22:25]
	v_mfma_f32_16x16x32_bf16 v[22:25], v[178:181], v[242:245], v[22:25]
	v_mfma_f32_16x16x32_bf16 v[18:21], v[186:189], v[242:245], v[18:21]
	v_mfma_f32_16x16x32_bf16 v[18:21], v[182:185], v[238:241], v[18:21]
	v_mfma_f32_16x16x32_bf16 v[2:5], v[182:185], v[246:249], v[2:5]
	v_mfma_f32_16x16x32_bf16 v[2:5], v[186:189], v[250:253], v[2:5]
	v_mfma_f32_16x16x32_bf16 v[6:9], v[178:181], v[250:253], v[6:9]
	v_mfma_f32_16x16x32_bf16 v[6:9], v[174:177], v[246:249], v[6:9]
	v_mfma_f32_16x16x32_bf16 v[10:13], v[164:167], v[246:249], v[10:13]
	v_mfma_f32_16x16x32_bf16 v[10:13], v[168:171], v[250:253], v[10:13]
	v_mfma_f32_16x16x32_bf16 v[14:17], v[160:163], v[250:253], v[14:17]
	v_mfma_f32_16x16x32_bf16 v[14:17], v[156:159], v[246:249], v[14:17]
	s_waitcnt vmcnt(0)
	s_add_i32 s49, s49, 1
	s_cmp_lt_u32 s49, 16
	s_cbranch_scc0 .Lp8k_B_exit
	s_barrier
	s_branch .Lp8k_B_loop
.Lp8k_B_exit:
.Lp8k_done:
	s_setprio 0

;     __host__ __device__ bool next(int i, Unit& u) const { const int L = i * G + c; if (L >= n) return false; u.pm = L; u.pn = L >> 2; return true; }
; #define PG8_STAGE(bufoff, gbase, voff) do { _Pragma("unroll") for (int _i = 0; _i < 2; ++_i) \
;         __builtin_amdgcn_global_load_lds((const unsigned*)((const char*)(gbase) + (voff)[_i]), (PG8_LAS unsigned*)(lds + (bufoff) + ldsw + _i * 8192), 16, 0, 0); } while (0)
; #define PG8_LDA(dst, b, h) do { _Pragma("unroll") for (int m = 0; m < 4; ++m) _Pragma("unroll") for (int k = 0; k < 2; ++k) dst[m][k] = *(const PG8_LAS bf16x8*)(lds + PG8_SA(b, h) + aoff + m * 2048 + k * 1024); } while (0)
; #define PG8_LDB(dst, b, h) do { _Pragma("unroll") for (int n = 0; n < 2; ++n) _Pragma("unroll") for (int k = 0; k < 2; ++k) dst[n][k] = *(const PG8_LAS bf16x8*)(lds + PG8_SB(b, h) + boff + n * 2048 + k * 1024); } while (0)
; #define PG8_WAIT_V(n) asm volatile("s_waitcnt vmcnt(" #n ")" ::: "memory")
; template <class Epi, class Sched, bool ALIGN_EPI>
; __device__ __forceinline__ void gemm_phase(PG8_LAS unsigned char* lds, const Gemm g, const Sched& S, const Epi& E) {
;     ...
;         const bool has_next = S.next(ui + 1, nxt);
;         const size_t tail_ = has_next ? 0 : tailoff; const char* nA = (has_next ? (const char*)g.A + (size_t)nxt.pm * tstepA : cA) + (has_next ? 0 : tailoffA); const char* nB = (has_next ? (const char*)g.Bt + (size_t)nxt.pn * tstepB : cB) + tail_;
;         for (int t = 0; t < nt; t += 2) {
;             if constexpr (Epi::MIDK) { if (t == (nt >> 1)) E.midk(acc, cur, wr, fr); }
;             const bool last = (t == nt - 2);
;             const char* a1 = cA + (size_t)(t + 1) * kstepA;
;             const char* a2 = last ? nA : cA + (size_t)(t + 2) * kstepA; const char* b2 = last ? nB : cB + (size_t)(t + 2) * kstep;
;             const char* a3 = a2 + kstepA; const char* b3 = b2 + kstep;
;             PG8_LDB(B0, 0, 0); PG8_LDB(B1, 0, 1); PG8_SCHED; PG8_LDA(At, 0, 0); PG8_STAGE(PG8_SA(1, 1), a1 + hstepA, voffA);
;             PG8_WAIT_V(8); PG8_WAIT_L(0); PG8_BAR; PG8_MMA(0, 0, At, B0); PG8_MMA(0, 1, At, B1); PG8_BAR; PG8_SCHED;
;             PG8_LDA(At, 0, 1); PG8_STAGE(PG8_SB(0, 0), b2, voffB); PG8_STAGE(PG8_SB(0, 1), b2 + hstepB, voffB); PG8_STAGE(PG8_SA(0, 0), a2, voffA);
;             PG8_WAIT_V(8); PG8_WAIT_L(0); PG8_BAR; PG8_MMA(1, 0, At, B0); PG8_MMA(1, 1, At, B1); PG8_BAR; PG8_SCHED;
.LBB0_947:
	s_add_u32 s6, s6, s30
	s_addc_u32 s7, s7, s31
	s_add_u32 s24, s34, s24
	s_addc_u32 s25, s35, s25
	s_add_u32 s57, s28, 0x100
	s_addc_u32 s58, s29, 0
	s_mov_b32 s59, -2
	s_and_b32 s60, s37, 0xfff
	s_mov_b32 s57, 0
	s_cmp_lt_u32 s37, 0x1000
	s_cbranch_scc0 .Lp9k_B_init
	s_setprio 0
	s_add_u32 s28, s28, 0x80
	s_addc_u32 s29, s29, 0
	s_mov_b64 s[58:59], s[24:25]
	ds_read_b128 v[194:197], v157 offset:0
	ds_read_b128 v[198:201], v157 offset:1024
	ds_read_b128 v[202:205], v157 offset:2048
	s_add_i32 m0, s60, 0x18000
	s_nop 0
	global_load_lds_dwordx4 v132, s[28:29]
	ds_read_b128 v[206:209], v157 offset:3072
	ds_read_b128 v[210:213], v157 offset:4096
	ds_read_b128 v[214:217], v157 offset:5120
	s_add_i32 m0, s60, 0x1a000
	s_nop 0
	global_load_lds_dwordx4 v136, s[28:29]
	ds_read_b128 v[218:221], v157 offset:6144
	ds_read_b128 v[222:225], v157 offset:7168
	ds_read_b128 v[158:161], v155 offset:0
	s_add_u32 s30, s28, 0x58000
	s_addc_u32 s31, s29, 0
	s_add_i32 m0, s60, 0x19000
	s_nop 0
	global_load_lds_dwordx4 v132, s[30:31]
	ds_read_b128 v[162:165], v155 offset:1024
	ds_read_b128 v[166:169], v155 offset:2048
	ds_read_b128 v[174:177], v155 offset:3072
	s_add_i32 m0, s60, 0x1b000
	s_nop 0
	global_load_lds_dwordx4 v136, s[30:31]
	ds_read_b128 v[178:181], v155 offset:16384
	ds_read_b128 v[182:185], v155 offset:17408
	ds_read_b128 v[186:189], v155 offset:18432
	s_add_u32 s30, s28, 0x160000
	s_addc_u32 s31, s29, 0
	s_add_i32 m0, s60, 0x1c000
	s_nop 0
	global_load_lds_dwordx4 v132, s[30:31]
	ds_read_b128 v[190:193], v155 offset:19456
	ds_read_b128 v[226:229], v157 offset:16384
	ds_read_b128 v[230:233], v157 offset:17408
	s_add_i32 m0, s60, 0x1e000
	s_nop 0
	global_load_lds_dwordx4 v136, s[30:31]
	ds_read_b128 v[234:237], v157 offset:18432
	ds_read_b128 v[238:241], v157 offset:19456
	ds_read_b128 v[242:245], v157 offset:20480
	s_add_u32 s30, s28, 0x1b8000
	s_addc_u32 s31, s29, 0
	s_add_i32 m0, s60, 0x1d000
	s_nop 0
	global_load_lds_dwordx4 v132, s[30:31]
	ds_read_b128 v[246:249], v157 offset:21504
	ds_read_b128 v[250:253], v157 offset:22528
	ds_read_b128 v[142:145], v157 offset:23552
	s_add_i32 m0, s60, 0x1f000
	s_nop 0
	global_load_lds_dwordx4 v136, s[30:31]
	s_add_u32 s28, s28, 0x80
	s_addc_u32 s29, s29, 0
	s_waitcnt vmcnt(8) lgkmcnt(0)
	s_barrier
	v_mfma_f32_16x16x32_bf16 v[126:129], v[158:161], v[194:197], 0
	v_mfma_f32_16x16x32_bf16 v[126:129], v[162:165], v[198:201], v[126:129]
	v_mfma_f32_16x16x32_bf16 v[122:125], v[174:177], v[198:201], 0
	v_mfma_f32_16x16x32_bf16 v[122:125], v[166:169], v[194:197], v[122:125]
	v_mfma_f32_16x16x32_bf16 v[114:117], v[178:181], v[194:197], 0
	v_mfma_f32_16x16x32_bf16 v[114:117], v[182:185], v[198:201], v[114:117]
	v_mfma_f32_16x16x32_bf16 v[106:109], v[190:193], v[198:201], 0
	v_mfma_f32_16x16x32_bf16 v[106:109], v[186:189], v[194:197], v[106:109]
	v_mfma_f32_16x16x32_bf16 v[90:93], v[186:189], v[202:205], 0
	v_mfma_f32_16x16x32_bf16 v[90:93], v[190:193], v[206:209], v[90:93]
	v_mfma_f32_16x16x32_bf16 v[98:101], v[182:185], v[206:209], 0
	v_mfma_f32_16x16x32_bf16 v[98:101], v[178:181], v[202:205], v[98:101]
	v_mfma_f32_16x16x32_bf16 v[110:113], v[166:169], v[202:205], 0
	v_mfma_f32_16x16x32_bf16 v[110:113], v[174:177], v[206:209], v[110:113]
	v_mfma_f32_16x16x32_bf16 v[118:121], v[162:165], v[206:209], 0
	v_mfma_f32_16x16x32_bf16 v[118:121], v[158:161], v[202:205], v[118:121]
	v_mfma_f32_16x16x32_bf16 v[102:105], v[158:161], v[210:213], 0
	v_mfma_f32_16x16x32_bf16 v[102:105], v[162:165], v[214:217], v[102:105]
	v_mfma_f32_16x16x32_bf16 v[94:97], v[174:177], v[214:217], 0
	v_mfma_f32_16x16x32_bf16 v[94:97], v[166:169], v[210:213], v[94:97]
	v_mfma_f32_16x16x32_bf16 v[82:85], v[178:181], v[210:213], 0
	v_mfma_f32_16x16x32_bf16 v[82:85], v[182:185], v[214:217], v[82:85]
	v_mfma_f32_16x16x32_bf16 v[74:77], v[190:193], v[214:217], 0
	v_mfma_f32_16x16x32_bf16 v[74:77], v[186:189], v[210:213], v[74:77]
	v_mfma_f32_16x16x32_bf16 v[66:69], v[186:189], v[218:221], 0
	v_mfma_f32_16x16x32_bf16 v[66:69], v[190:193], v[222:225], v[66:69]
	v_mfma_f32_16x16x32_bf16 v[70:73], v[182:185], v[222:225], 0
	v_mfma_f32_16x16x32_bf16 v[70:73], v[178:181], v[218:221], v[70:73]
	v_mfma_f32_16x16x32_bf16 v[78:81], v[166:169], v[218:221], 0
	v_mfma_f32_16x16x32_bf16 v[78:81], v[174:177], v[222:225], v[78:81]
	v_mfma_f32_16x16x32_bf16 v[86:89], v[162:165], v[222:225], 0
	v_mfma_f32_16x16x32_bf16 v[86:89], v[158:161], v[218:221], v[86:89]
	v_mfma_f32_16x16x32_bf16 v[62:65], v[158:161], v[226:229], 0
	v_mfma_f32_16x16x32_bf16 v[62:65], v[162:165], v[230:233], v[62:65]
	v_mfma_f32_16x16x32_bf16 v[58:61], v[174:177], v[230:233], 0
	v_mfma_f32_16x16x32_bf16 v[58:61], v[166:169], v[226:229], v[58:61]
	v_mfma_f32_16x16x32_bf16 v[50:53], v[178:181], v[226:229], 0
	v_mfma_f32_16x16x32_bf16 v[50:53], v[182:185], v[230:233], v[50:53]
	v_mfma_f32_16x16x32_bf16 v[42:45], v[190:193], v[230:233], 0
	v_mfma_f32_16x16x32_bf16 v[42:45], v[186:189], v[226:229], v[42:45]
	v_mfma_f32_16x16x32_bf16 v[26:29], v[186:189], v[234:237], 0
	v_mfma_f32_16x16x32_bf16 v[26:29], v[190:193], v[238:241], v[26:29]
	v_mfma_f32_16x16x32_bf16 v[34:37], v[182:185], v[238:241], 0
	v_mfma_f32_16x16x32_bf16 v[34:37], v[178:181], v[234:237], v[34:37]
	v_mfma_f32_16x16x32_bf16 v[46:49], v[166:169], v[234:237], 0
	v_mfma_f32_16x16x32_bf16 v[46:49], v[174:177], v[238:241], v[46:49]
	v_mfma_f32_16x16x32_bf16 v[54:57], v[162:165], v[238:241], 0
	v_mfma_f32_16x16x32_bf16 v[54:57], v[158:161], v[234:237], v[54:57]
	v_mfma_f32_16x16x32_bf16 v[38:41], v[158:161], v[242:245], 0
	v_mfma_f32_16x16x32_bf16 v[38:41], v[162:165], v[246:249], v[38:41]
	v_mfma_f32_16x16x32_bf16 v[30:33], v[174:177], v[246:249], 0
	v_mfma_f32_16x16x32_bf16 v[30:33], v[166:169], v[242:245], v[30:33]
	v_mfma_f32_16x16x32_bf16 v[18:21], v[178:181], v[242:245], 0
	v_mfma_f32_16x16x32_bf16 v[18:21], v[182:185], v[246:249], v[18:21]
	v_mfma_f32_16x16x32_bf16 v[10:13], v[190:193], v[246:249], 0
	v_mfma_f32_16x16x32_bf16 v[10:13], v[186:189], v[242:245], v[10:13]
	v_mfma_f32_16x16x32_bf16 v[2:5], v[186:189], v[250:253], 0
	v_mfma_f32_16x16x32_bf16 v[2:5], v[190:193], v[142:145], v[2:5]
	v_mfma_f32_16x16x32_bf16 v[6:9], v[182:185], v[142:145], 0
	v_mfma_f32_16x16x32_bf16 v[6:9], v[178:181], v[250:253], v[6:9]
	v_mfma_f32_16x16x32_bf16 v[14:17], v[166:169], v[250:253], 0
	v_mfma_f32_16x16x32_bf16 v[14:17], v[174:177], v[142:145], v[14:17]
	v_mfma_f32_16x16x32_bf16 v[22:25], v[162:165], v[142:145], 0
	v_mfma_f32_16x16x32_bf16 v[22:25], v[158:161], v[250:253], v[22:25]
	s_waitcnt vmcnt(0)
	s_barrier
; #define PG8_STAGE(bufoff, gbase, voff) do { _Pragma("unroll") for (int _i = 0; _i < 2; ++_i) \
;         __builtin_amdgcn_global_load_lds((const unsigned*)((const char*)(gbase) + (voff)[_i]), (PG8_LAS unsigned*)(lds + (bufoff) + ldsw + _i * 8192), 16, 0, 0); } while (0)
; #define PG8_LDA(dst, b, h) do { _Pragma("unroll") for (int m = 0; m < 4; ++m) _Pragma("unroll") for (int k = 0; k < 2; ++k) dst[m][k] = *(const PG8_LAS bf16x8*)(lds + PG8_SA(b, h) + aoff + m * 2048 + k * 1024); } while (0)
; #define PG8_LDB(dst, b, h) do { _Pragma("unroll") for (int n = 0; n < 2; ++n) _Pragma("unroll") for (int k = 0; k < 2; ++k) dst[n][k] = *(const PG8_LAS bf16x8*)(lds + PG8_SB(b, h) + boff + n * 2048 + k * 1024); } while (0)
; #define PG8_MMA(ai, bj, At, Bt) do { __builtin_amdgcn_s_setprio(1); _Pragma("unroll") for (int m = 0; m < 4; ++m) _Pragma("unroll") for (int n = 0; n < 2; ++n) _Pragma("unroll") for (int k = 0; k < 2; ++k) \
;         acc[ai][bj][m][n] = __builtin_amdgcn_mfma_f32_16x16x32_bf16(Bt[n][k], At[m][k], acc[ai][bj][m][n], 0, 0, 0); __builtin_amdgcn_s_setprio(0); } while (0)
; #define PG8_WAIT_V(n) asm volatile("s_waitcnt vmcnt(" #n ")" ::: "memory")
; #define PG8_WAIT_L(n) asm volatile("s_waitcnt lgkmcnt(" #n ")" ::: "memory")
; #define PG8_BAR __builtin_amdgcn_s_barrier()
; #define PG8_SCHED __builtin_amdgcn_sched_barrier(0)
; template <class Epi, class Sched, bool ALIGN_EPI>
; __device__ __forceinline__ void gemm_phase(PG8_LAS unsigned char* lds, const Gemm g, const Sched& S, const Epi& E) {
;     ...
;             PG8_LDB(B0, 1, 0); PG8_LDB(B1, 1, 1); PG8_SCHED; PG8_LDA(At, 1, 0); PG8_STAGE(PG8_SA(0, 1), a2 + hstepA, voffA);
;             PG8_WAIT_V(8); PG8_WAIT_L(0); PG8_BAR; PG8_MMA(0, 0, At, B0); PG8_MMA(0, 1, At, B1); PG8_BAR; PG8_SCHED;
;             PG8_LDA(At, 1, 1); PG8_STAGE(PG8_SB(1, 0), b3, voffB); PG8_STAGE(PG8_SB(1, 1), b3 + hstepB, voffB); PG8_STAGE(PG8_SA(1, 0), a3, voffA);
;             PG8_WAIT_V(8); PG8_WAIT_L(0); PG8_BAR; PG8_MMA(1, 0, At, B0); PG8_MMA(1, 1, At, B1); PG8_BAR; PG8_SCHED;
	ds_read_b128 v[194:197], v157 offset:32768
	ds_read_b128 v[198:201], v157 offset:33792
	ds_read_b128 v[202:205], v157 offset:34816
	s_cmp_eq_u32 s57, 43
	s_cselect_b32 s28, s58, s28
	s_cselect_b32 s29, s59, s29
	s_add_i32 m0, s60, 0x10000
	s_nop 0
	global_load_lds_dwordx4 v132, s[28:29]
	ds_read_b128 v[206:209], v157 offset:35840
	ds_read_b128 v[210:213], v157 offset:36864
	ds_read_b128 v[214:217], v157 offset:37888
	s_add_i32 m0, s60, 0x12000
	s_nop 0
	global_load_lds_dwordx4 v136, s[28:29]
	ds_read_b128 v[218:221], v157 offset:38912
	ds_read_b128 v[222:225], v157 offset:39936
	ds_read_b128 v[158:161], v155 offset:32768
	s_add_u32 s30, s28, 0x58000
	s_addc_u32 s31, s29, 0
	s_add_i32 m0, s60, 0x11000
	s_nop 0
	global_load_lds_dwordx4 v132, s[30:31]
	ds_read_b128 v[162:165], v155 offset:33792
	ds_read_b128 v[166:169], v155 offset:34816
	ds_read_b128 v[174:177], v155 offset:35840
	s_add_i32 m0, s60, 0x13000
	s_nop 0
	global_load_lds_dwordx4 v136, s[30:31]
	ds_read_b128 v[178:181], v155 offset:49152
	ds_read_b128 v[182:185], v155 offset:50176
	ds_read_b128 v[186:189], v155 offset:51200
	s_add_u32 s30, s28, 0x160000
	s_addc_u32 s31, s29, 0
	s_add_i32 m0, s60, 0x14000
	s_nop 0
	global_load_lds_dwordx4 v132, s[30:31]
	ds_read_b128 v[190:193], v155 offset:52224
	ds_read_b128 v[226:229], v157 offset:49152
	ds_read_b128 v[230:233], v157 offset:50176
	s_add_i32 m0, s60, 0x16000
	s_nop 0
	global_load_lds_dwordx4 v136, s[30:31]
	ds_read_b128 v[234:237], v157 offset:51200
	ds_read_b128 v[238:241], v157 offset:52224
	ds_read_b128 v[242:245], v157 offset:53248
	s_add_u32 s30, s28, 0x1b8000
	s_addc_u32 s31, s29, 0
	s_add_i32 m0, s60, 0x15000
	s_nop 0
	global_load_lds_dwordx4 v132, s[30:31]
	ds_read_b128 v[246:249], v157 offset:54272
	ds_read_b128 v[250:253], v157 offset:55296
	ds_read_b128 v[142:145], v157 offset:56320
	s_add_i32 m0, s60, 0x17000
	s_nop 0
	global_load_lds_dwordx4 v136, s[30:31]
	s_add_u32 s28, s28, 0x80
	s_addc_u32 s29, s29, 0
	s_waitcnt vmcnt(8) lgkmcnt(0)
	s_barrier
	v_mfma_f32_16x16x32_bf16 v[126:129], v[158:161], v[194:197], v[126:129]
	v_mfma_f32_16x16x32_bf16 v[126:129], v[162:165], v[198:201], v[126:129]
	v_mfma_f32_16x16x32_bf16 v[122:125], v[174:177], v[198:201], v[122:125]
	v_mfma_f32_16x16x32_bf16 v[122:125], v[166:169], v[194:197], v[122:125]
	v_mfma_f32_16x16x32_bf16 v[114:117], v[178:181], v[194:197], v[114:117]
	v_mfma_f32_16x16x32_bf16 v[114:117], v[182:185], v[198:201], v[114:117]
	v_mfma_f32_16x16x32_bf16 v[106:109], v[190:193], v[198:201], v[106:109]
	v_mfma_f32_16x16x32_bf16 v[106:109], v[186:189], v[194:197], v[106:109]
	v_mfma_f32_16x16x32_bf16 v[90:93], v[186:189], v[202:205], v[90:93]
	v_mfma_f32_16x16x32_bf16 v[90:93], v[190:193], v[206:209], v[90:93]
	v_mfma_f32_16x16x32_bf16 v[98:101], v[182:185], v[206:209], v[98:101]
	v_mfma_f32_16x16x32_bf16 v[98:101], v[178:181], v[202:205], v[98:101]
	v_mfma_f32_16x16x32_bf16 v[110:113], v[166:169], v[202:205], v[110:113]
	v_mfma_f32_16x16x32_bf16 v[110:113], v[174:177], v[206:209], v[110:113]
	v_mfma_f32_16x16x32_bf16 v[118:121], v[162:165], v[206:209], v[118:121]
	v_mfma_f32_16x16x32_bf16 v[118:121], v[158:161], v[202:205], v[118:121]
	v_mfma_f32_16x16x32_bf16 v[102:105], v[158:161], v[210:213], v[102:105]
	v_mfma_f32_16x16x32_bf16 v[102:105], v[162:165], v[214:217], v[102:105]
	v_mfma_f32_16x16x32_bf16 v[94:97], v[174:177], v[214:217], v[94:97]
	v_mfma_f32_16x16x32_bf16 v[94:97], v[166:169], v[210:213], v[94:97]
	v_mfma_f32_16x16x32_bf16 v[82:85], v[178:181], v[210:213], v[82:85]
	v_mfma_f32_16x16x32_bf16 v[82:85], v[182:185], v[214:217], v[82:85]
	v_mfma_f32_16x16x32_bf16 v[74:77], v[190:193], v[214:217], v[74:77]
	v_mfma_f32_16x16x32_bf16 v[74:77], v[186:189], v[210:213], v[74:77]
	v_mfma_f32_16x16x32_bf16 v[66:69], v[186:189], v[218:221], v[66:69]
	v_mfma_f32_16x16x32_bf16 v[66:69], v[190:193], v[222:225], v[66:69]
	v_mfma_f32_16x16x32_bf16 v[70:73], v[182:185], v[222:225], v[70:73]
	v_mfma_f32_16x16x32_bf16 v[70:73], v[178:181], v[218:221], v[70:73]
	v_mfma_f32_16x16x32_bf16 v[78:81], v[166:169], v[218:221], v[78:81]
	v_mfma_f32_16x16x32_bf16 v[78:81], v[174:177], v[222:225], v[78:81]
	v_mfma_f32_16x16x32_bf16 v[86:89], v[162:165], v[222:225], v[86:89]
	v_mfma_f32_16x16x32_bf16 v[86:89], v[158:161], v[218:221], v[86:89]
	v_mfma_f32_16x16x32_bf16 v[62:65], v[158:161], v[226:229], v[62:65]
	v_mfma_f32_16x16x32_bf16 v[62:65], v[162:165], v[230:233], v[62:65]
	v_mfma_f32_16x16x32_bf16 v[58:61], v[174:177], v[230:233], v[58:61]
	v_mfma_f32_16x16x32_bf16 v[58:61], v[166:169], v[226:229], v[58:61]
	v_mfma_f32_16x16x32_bf16 v[50:53], v[178:181], v[226:229], v[50:53]
	v_mfma_f32_16x16x32_bf16 v[50:53], v[182:185], v[230:233], v[50:53]
	v_mfma_f32_16x16x32_bf16 v[42:45], v[190:193], v[230:233], v[42:45]
	v_mfma_f32_16x16x32_bf16 v[42:45], v[186:189], v[226:229], v[42:45]
	v_mfma_f32_16x16x32_bf16 v[26:29], v[186:189], v[234:237], v[26:29]
	v_mfma_f32_16x16x32_bf16 v[26:29], v[190:193], v[238:241], v[26:29]
	v_mfma_f32_16x16x32_bf16 v[34:37], v[182:185], v[238:241], v[34:37]
	v_mfma_f32_16x16x32_bf16 v[34:37], v[178:181], v[234:237], v[34:37]
	v_mfma_f32_16x16x32_bf16 v[46:49], v[166:169], v[234:237], v[46:49]
	v_mfma_f32_16x16x32_bf16 v[46:49], v[174:177], v[238:241], v[46:49]
	v_mfma_f32_16x16x32_bf16 v[54:57], v[162:165], v[238:241], v[54:57]
	v_mfma_f32_16x16x32_bf16 v[54:57], v[158:161], v[234:237], v[54:57]
	v_mfma_f32_16x16x32_bf16 v[38:41], v[158:161], v[242:245], v[38:41]
	v_mfma_f32_16x16x32_bf16 v[38:41], v[162:165], v[246:249], v[38:41]
	v_mfma_f32_16x16x32_bf16 v[30:33], v[174:177], v[246:249], v[30:33]
	v_mfma_f32_16x16x32_bf16 v[30:33], v[166:169], v[242:245], v[30:33]
	v_mfma_f32_16x16x32_bf16 v[18:21], v[178:181], v[242:245], v[18:21]
	v_mfma_f32_16x16x32_bf16 v[18:21], v[182:185], v[246:249], v[18:21]
	v_mfma_f32_16x16x32_bf16 v[10:13], v[190:193], v[246:249], v[10:13]
	v_mfma_f32_16x16x32_bf16 v[10:13], v[186:189], v[242:245], v[10:13]
	v_mfma_f32_16x16x32_bf16 v[2:5], v[186:189], v[250:253], v[2:5]
	v_mfma_f32_16x16x32_bf16 v[2:5], v[190:193], v[142:145], v[2:5]
	v_mfma_f32_16x16x32_bf16 v[6:9], v[182:185], v[142:145], v[6:9]
	v_mfma_f32_16x16x32_bf16 v[6:9], v[178:181], v[250:253], v[6:9]
	v_mfma_f32_16x16x32_bf16 v[14:17], v[166:169], v[250:253], v[14:17]
	v_mfma_f32_16x16x32_bf16 v[14:17], v[174:177], v[142:145], v[14:17]
	v_mfma_f32_16x16x32_bf16 v[22:25], v[162:165], v[142:145], v[22:25]
	v_mfma_f32_16x16x32_bf16 v[22:25], v[158:161], v[250:253], v[22:25]
	s_waitcnt vmcnt(0)
	s_barrier
	s_add_i32 s57, s57, 1
; #define PG8_STAGE(bufoff, gbase, voff) do { _Pragma("unroll") for (int _i = 0; _i < 2; ++_i) \
;         __builtin_amdgcn_global_load_lds((const unsigned*)((const char*)(gbase) + (voff)[_i]), (PG8_LAS unsigned*)(lds + (bufoff) + ldsw + _i * 8192), 16, 0, 0); } while (0)
; #define PG8_LDA(dst, b, h) do { _Pragma("unroll") for (int m = 0; m < 4; ++m) _Pragma("unroll") for (int k = 0; k < 2; ++k) dst[m][k] = *(const PG8_LAS bf16x8*)(lds + PG8_SA(b, h) + aoff + m * 2048 + k * 1024); } while (0)
; #define PG8_LDB(dst, b, h) do { _Pragma("unroll") for (int n = 0; n < 2; ++n) _Pragma("unroll") for (int k = 0; k < 2; ++k) dst[n][k] = *(const PG8_LAS bf16x8*)(lds + PG8_SB(b, h) + boff + n * 2048 + k * 1024); } while (0)
; #define PG8_MMA(ai, bj, At, Bt) do { __builtin_amdgcn_s_setprio(1); _Pragma("unroll") for (int m = 0; m < 4; ++m) _Pragma("unroll") for (int n = 0; n < 2; ++n) _Pragma("unroll") for (int k = 0; k < 2; ++k) \
;         acc[ai][bj][m][n] = __builtin_amdgcn_mfma_f32_16x16x32_bf16(Bt[n][k], At[m][k], acc[ai][bj][m][n], 0, 0, 0); __builtin_amdgcn_s_setprio(0); } while (0)
; #define PG8_WAIT_V(n) asm volatile("s_waitcnt vmcnt(" #n ")" ::: "memory")
; #define PG8_WAIT_L(n) asm volatile("s_waitcnt lgkmcnt(" #n ")" ::: "memory")
; #define PG8_BAR __builtin_amdgcn_s_barrier()
; #define PG8_SCHED __builtin_amdgcn_sched_barrier(0)
; template <class Epi, class Sched, bool ALIGN_EPI>
; __device__ __forceinline__ void gemm_phase(PG8_LAS unsigned char* lds, const Gemm g, const Sched& S, const Epi& E) {
;     ...
;             PG8_LDB(B0, 0, 0); PG8_LDB(B1, 0, 1); PG8_SCHED; PG8_LDA(At, 0, 0); PG8_STAGE(PG8_SA(1, 1), a1 + hstepA, voffA);
;             PG8_WAIT_V(8); PG8_WAIT_L(0); PG8_BAR; PG8_MMA(0, 0, At, B0); PG8_MMA(0, 1, At, B1); PG8_BAR; PG8_SCHED;
;             PG8_LDA(At, 0, 1); PG8_STAGE(PG8_SB(0, 0), b2, voffB); PG8_STAGE(PG8_SB(0, 1), b2 + hstepB, voffB); PG8_STAGE(PG8_SA(0, 0), a2, voffA);
;             PG8_WAIT_V(8); PG8_WAIT_L(0); PG8_BAR; PG8_MMA(1, 0, At, B0); PG8_MMA(1, 1, At, B1); PG8_BAR; PG8_SCHED;
.Lp9k_A_loop:
	ds_read_b128 v[194:197], v157 offset:0
	ds_read_b128 v[198:201], v157 offset:1024
	ds_read_b128 v[202:205], v157 offset:2048
	s_add_i32 m0, s60, 0x18000
	s_nop 0
	global_load_lds_dwordx4 v132, s[28:29]
	ds_read_b128 v[206:209], v157 offset:3072
	ds_read_b128 v[210:213], v157 offset:4096
	ds_read_b128 v[214:217], v157 offset:5120
	s_add_i32 m0, s60, 0x1a000
	s_nop 0
	global_load_lds_dwordx4 v136, s[28:29]
	ds_read_b128 v[218:221], v157 offset:6144
	ds_read_b128 v[222:225], v157 offset:7168
	ds_read_b128 v[158:161], v155 offset:0
	s_add_u32 s30, s28, 0x58000
	s_addc_u32 s31, s29, 0
	s_add_i32 m0, s60, 0x19000
	s_nop 0
	global_load_lds_dwordx4 v132, s[30:31]
	ds_read_b128 v[162:165], v155 offset:1024
	ds_read_b128 v[166:169], v155 offset:2048
	ds_read_b128 v[174:177], v155 offset:3072
	s_add_i32 m0, s60, 0x1b000
	s_nop 0
	global_load_lds_dwordx4 v136, s[30:31]
	ds_read_b128 v[178:181], v155 offset:16384
	ds_read_b128 v[182:185], v155 offset:17408
	ds_read_b128 v[186:189], v155 offset:18432
	s_add_u32 s30, s28, 0x160000
	s_addc_u32 s31, s29, 0
	s_add_i32 m0, s60, 0x1c000
	s_nop 0
	global_load_lds_dwordx4 v132, s[30:31]
	ds_read_b128 v[190:193], v155 offset:19456
	ds_read_b128 v[226:229], v157 offset:16384
	ds_read_b128 v[230:233], v157 offset:17408
	s_add_i32 m0, s60, 0x1e000
	s_nop 0
	global_load_lds_dwordx4 v136, s[30:31]
	ds_read_b128 v[234:237], v157 offset:18432
	ds_read_b128 v[238:241], v157 offset:19456
	ds_read_b128 v[242:245], v157 offset:20480
	s_add_u32 s30, s28, 0x1b8000
	s_addc_u32 s31, s29, 0
	s_add_i32 m0, s60, 0x1d000
	s_nop 0
	global_load_lds_dwordx4 v132, s[30:31]
	ds_read_b128 v[246:249], v157 offset:21504
	ds_read_b128 v[250:253], v157 offset:22528
	ds_read_b128 v[142:145], v157 offset:23552
	s_add_i32 m0, s60, 0x1f000
	s_nop 0
	global_load_lds_dwordx4 v136, s[30:31]
	s_add_u32 s28, s28, 0x80
	s_addc_u32 s29, s29, 0
	s_waitcnt vmcnt(8) lgkmcnt(0)
	s_barrier
	v_mfma_f32_16x16x32_bf16 v[126:129], v[158:161], v[194:197], v[126:129]
	v_mfma_f32_16x16x32_bf16 v[126:129], v[162:165], v[198:201], v[126:129]
	v_mfma_f32_16x16x32_bf16 v[122:125], v[174:177], v[198:201], v[122:125]
	v_mfma_f32_16x16x32_bf16 v[122:125], v[166:169], v[194:197], v[122:125]
	v_mfma_f32_16x16x32_bf16 v[114:117], v[178:181], v[194:197], v[114:117]
	v_mfma_f32_16x16x32_bf16 v[114:117], v[182:185], v[198:201], v[114:117]
	v_mfma_f32_16x16x32_bf16 v[106:109], v[190:193], v[198:201], v[106:109]
	v_mfma_f32_16x16x32_bf16 v[106:109], v[186:189], v[194:197], v[106:109]
	v_mfma_f32_16x16x32_bf16 v[90:93], v[186:189], v[202:205], v[90:93]
	v_mfma_f32_16x16x32_bf16 v[90:93], v[190:193], v[206:209], v[90:93]
	v_mfma_f32_16x16x32_bf16 v[98:101], v[182:185], v[206:209], v[98:101]
	v_mfma_f32_16x16x32_bf16 v[98:101], v[178:181], v[202:205], v[98:101]
	v_mfma_f32_16x16x32_bf16 v[110:113], v[166:169], v[202:205], v[110:113]
	v_mfma_f32_16x16x32_bf16 v[110:113], v[174:177], v[206:209], v[110:113]
	v_mfma_f32_16x16x32_bf16 v[118:121], v[162:165], v[206:209], v[118:121]
	v_mfma_f32_16x16x32_bf16 v[118:121], v[158:161], v[202:205], v[118:121]
	v_mfma_f32_16x16x32_bf16 v[102:105], v[158:161], v[210:213], v[102:105]
	v_mfma_f32_16x16x32_bf16 v[102:105], v[162:165], v[214:217], v[102:105]
	v_mfma_f32_16x16x32_bf16 v[94:97], v[174:177], v[214:217], v[94:97]
	v_mfma_f32_16x16x32_bf16 v[94:97], v[166:169], v[210:213], v[94:97]
	v_mfma_f32_16x16x32_bf16 v[82:85], v[178:181], v[210:213], v[82:85]
	v_mfma_f32_16x16x32_bf16 v[82:85], v[182:185], v[214:217], v[82:85]
	v_mfma_f32_16x16x32_bf16 v[74:77], v[190:193], v[214:217], v[74:77]
	v_mfma_f32_16x16x32_bf16 v[74:77], v[186:189], v[210:213], v[74:77]
	v_mfma_f32_16x16x32_bf16 v[66:69], v[186:189], v[218:221], v[66:69]
	v_mfma_f32_16x16x32_bf16 v[66:69], v[190:193], v[222:225], v[66:69]
	v_mfma_f32_16x16x32_bf16 v[70:73], v[182:185], v[222:225], v[70:73]
	v_mfma_f32_16x16x32_bf16 v[70:73], v[178:181], v[218:221], v[70:73]
	v_mfma_f32_16x16x32_bf16 v[78:81], v[166:169], v[218:221], v[78:81]
	v_mfma_f32_16x16x32_bf16 v[78:81], v[174:177], v[222:225], v[78:81]
	v_mfma_f32_16x16x32_bf16 v[86:89], v[162:165], v[222:225], v[86:89]
	v_mfma_f32_16x16x32_bf16 v[86:89], v[158:161], v[218:221], v[86:89]
	v_mfma_f32_16x16x32_bf16 v[62:65], v[158:161], v[226:229], v[62:65]
	v_mfma_f32_16x16x32_bf16 v[62:65], v[162:165], v[230:233], v[62:65]
	v_mfma_f32_16x16x32_bf16 v[58:61], v[174:177], v[230:233], v[58:61]
	v_mfma_f32_16x16x32_bf16 v[58:61], v[166:169], v[226:229], v[58:61]
	v_mfma_f32_16x16x32_bf16 v[50:53], v[178:181], v[226:229], v[50:53]
	v_mfma_f32_16x16x32_bf16 v[50:53], v[182:185], v[230:233], v[50:53]
	v_mfma_f32_16x16x32_bf16 v[42:45], v[190:193], v[230:233], v[42:45]
	v_mfma_f32_16x16x32_bf16 v[42:45], v[186:189], v[226:229], v[42:45]
	v_mfma_f32_16x16x32_bf16 v[26:29], v[186:189], v[234:237], v[26:29]
	v_mfma_f32_16x16x32_bf16 v[26:29], v[190:193], v[238:241], v[26:29]
	v_mfma_f32_16x16x32_bf16 v[34:37], v[182:185], v[238:241], v[34:37]
	v_mfma_f32_16x16x32_bf16 v[34:37], v[178:181], v[234:237], v[34:37]
	v_mfma_f32_16x16x32_bf16 v[46:49], v[166:169], v[234:237], v[46:49]
	v_mfma_f32_16x16x32_bf16 v[46:49], v[174:177], v[238:241], v[46:49]
	v_mfma_f32_16x16x32_bf16 v[54:57], v[162:165], v[238:241], v[54:57]
	v_mfma_f32_16x16x32_bf16 v[54:57], v[158:161], v[234:237], v[54:57]
	v_mfma_f32_16x16x32_bf16 v[38:41], v[158:161], v[242:245], v[38:41]
	v_mfma_f32_16x16x32_bf16 v[38:41], v[162:165], v[246:249], v[38:41]
	v_mfma_f32_16x16x32_bf16 v[30:33], v[174:177], v[246:249], v[30:33]
	v_mfma_f32_16x16x32_bf16 v[30:33], v[166:169], v[242:245], v[30:33]
	v_mfma_f32_16x16x32_bf16 v[18:21], v[178:181], v[242:245], v[18:21]
	v_mfma_f32_16x16x32_bf16 v[18:21], v[182:185], v[246:249], v[18:21]
	v_mfma_f32_16x16x32_bf16 v[10:13], v[190:193], v[246:249], v[10:13]
	v_mfma_f32_16x16x32_bf16 v[10:13], v[186:189], v[242:245], v[10:13]
	v_mfma_f32_16x16x32_bf16 v[2:5], v[186:189], v[250:253], v[2:5]
	v_mfma_f32_16x16x32_bf16 v[2:5], v[190:193], v[142:145], v[2:5]
	v_mfma_f32_16x16x32_bf16 v[6:9], v[182:185], v[142:145], v[6:9]
	v_mfma_f32_16x16x32_bf16 v[6:9], v[178:181], v[250:253], v[6:9]
	v_mfma_f32_16x16x32_bf16 v[14:17], v[166:169], v[250:253], v[14:17]
	v_mfma_f32_16x16x32_bf16 v[14:17], v[174:177], v[142:145], v[14:17]
	v_mfma_f32_16x16x32_bf16 v[22:25], v[162:165], v[142:145], v[22:25]
	v_mfma_f32_16x16x32_bf16 v[22:25], v[158:161], v[250:253], v[22:25]
	s_waitcnt vmcnt(0)
	s_barrier
; #define PG8_STAGE(bufoff, gbase, voff) do { _Pragma("unroll") for (int _i = 0; _i < 2; ++_i) \
;         __builtin_amdgcn_global_load_lds((const unsigned*)((const char*)(gbase) + (voff)[_i]), (PG8_LAS unsigned*)(lds + (bufoff) + ldsw + _i * 8192), 16, 0, 0); } while (0)
; #define PG8_LDA(dst, b, h) do { _Pragma("unroll") for (int m = 0; m < 4; ++m) _Pragma("unroll") for (int k = 0; k < 2; ++k) dst[m][k] = *(const PG8_LAS bf16x8*)(lds + PG8_SA(b, h) + aoff + m * 2048 + k * 1024); } while (0)
; #define PG8_LDB(dst, b, h) do { _Pragma("unroll") for (int n = 0; n < 2; ++n) _Pragma("unroll") for (int k = 0; k < 2; ++k) dst[n][k] = *(const PG8_LAS bf16x8*)(lds + PG8_SB(b, h) + boff + n * 2048 + k * 1024); } while (0)
; template <class Epi, class Sched, bool ALIGN_EPI>
; __device__ __forceinline__ void gemm_phase(PG8_LAS unsigned char* lds, const Gemm g, const Sched& S, const Epi& E) {
;     ...
;         for (int t = 0; t < nt; t += 2) {
;             if constexpr (Epi::MIDK) { if (t == (nt >> 1)) E.midk(acc, cur, wr, fr); }
;             const bool last = (t == nt - 2);
;             const char* a1 = cA + (size_t)(t + 1) * kstepA;
;             const char* a2 = last ? nA : cA + (size_t)(t + 2) * kstepA; const char* b2 = last ? nB : cB + (size_t)(t + 2) * kstep;
;             const char* a3 = a2 + kstepA; const char* b3 = b2 + kstep;
;             PG8_LDB(B0, 0, 0); PG8_LDB(B1, 0, 1); PG8_SCHED; PG8_LDA(At, 0, 0); PG8_STAGE(PG8_SA(1, 1), a1 + hstepA, voffA);
;             PG8_WAIT_V(8); PG8_WAIT_L(0); PG8_BAR; PG8_MMA(0, 0, At, B0); PG8_MMA(0, 1, At, B1); PG8_BAR; PG8_SCHED;
;             PG8_LDA(At, 0, 1); PG8_STAGE(PG8_SB(0, 0), b2, voffB); PG8_STAGE(PG8_SB(0, 1), b2 + hstepB, voffB); PG8_STAGE(PG8_SA(0, 0), a2, voffA);
;             PG8_WAIT_V(8); PG8_WAIT_L(0); PG8_BAR; PG8_MMA(1, 0, At, B0); PG8_MMA(1, 1, At, B1); PG8_BAR; PG8_SCHED;
;             PG8_LDB(B0, 1, 0); PG8_LDB(B1, 1, 1); PG8_SCHED; PG8_LDA(At, 1, 0); PG8_STAGE(PG8_SA(0, 1), a2 + hstepA, voffA);
;             PG8_WAIT_V(8); PG8_WAIT_L(0); PG8_BAR; PG8_MMA(0, 0, At, B0); PG8_MMA(0, 1, At, B1); PG8_BAR; PG8_SCHED;
;             PG8_LDA(At, 1, 1); PG8_STAGE(PG8_SB(1, 0), b3, voffB); PG8_STAGE(PG8_SB(1, 1), b3 + hstepB, voffB); PG8_STAGE(PG8_SA(1, 0), a3, voffA);
;             PG8_WAIT_V(8); PG8_WAIT_L(0); PG8_BAR; PG8_MMA(1, 0, At, B0); PG8_MMA(1, 1, At, B1); PG8_BAR; PG8_SCHED;
;         }
	ds_read_b128 v[194:197], v157 offset:32768
	ds_read_b128 v[198:201], v157 offset:33792
	ds_read_b128 v[202:205], v157 offset:34816
	s_cmp_eq_u32 s57, 43
	s_cselect_b32 s28, s58, s28
	s_cselect_b32 s29, s59, s29
	s_add_i32 m0, s60, 0x10000
	s_nop 0
	global_load_lds_dwordx4 v132, s[28:29]
	ds_read_b128 v[206:209], v157 offset:35840
	ds_read_b128 v[210:213], v157 offset:36864
	ds_read_b128 v[214:217], v157 offset:37888
	s_add_i32 m0, s60, 0x12000
	s_nop 0
	global_load_lds_dwordx4 v136, s[28:29]
	ds_read_b128 v[218:221], v157 offset:38912
	ds_read_b128 v[222:225], v157 offset:39936
	ds_read_b128 v[158:161], v155 offset:32768
	s_add_u32 s30, s28, 0x58000
	s_addc_u32 s31, s29, 0
	s_add_i32 m0, s60, 0x11000
	s_nop 0
	global_load_lds_dwordx4 v132, s[30:31]
	ds_read_b128 v[162:165], v155 offset:33792
	ds_read_b128 v[166:169], v155 offset:34816
	ds_read_b128 v[174:177], v155 offset:35840
	s_add_i32 m0, s60, 0x13000
	s_nop 0
	global_load_lds_dwordx4 v136, s[30:31]
	ds_read_b128 v[178:181], v155 offset:49152
	ds_read_b128 v[182:185], v155 offset:50176
	ds_read_b128 v[186:189], v155 offset:51200
	s_add_u32 s30, s28, 0x160000
	s_addc_u32 s31, s29, 0
	s_add_i32 m0, s60, 0x14000
	s_nop 0
	global_load_lds_dwordx4 v132, s[30:31]
	ds_read_b128 v[190:193], v155 offset:52224
	ds_read_b128 v[226:229], v157 offset:49152
	ds_read_b128 v[230:233], v157 offset:50176
	s_add_i32 m0, s60, 0x16000
	s_nop 0
	global_load_lds_dwordx4 v136, s[30:31]
	ds_read_b128 v[234:237], v157 offset:51200
	ds_read_b128 v[238:241], v157 offset:52224
	ds_read_b128 v[242:245], v157 offset:53248
	s_add_u32 s30, s28, 0x1b8000
	s_addc_u32 s31, s29, 0
	s_add_i32 m0, s60, 0x15000
	s_nop 0
	global_load_lds_dwordx4 v132, s[30:31]
	ds_read_b128 v[246:249], v157 offset:54272
	ds_read_b128 v[250:253], v157 offset:55296
	ds_read_b128 v[142:145], v157 offset:56320
	s_add_i32 m0, s60, 0x17000
	s_nop 0
	global_load_lds_dwordx4 v136, s[30:31]
	s_add_u32 s28, s28, 0x80
	s_addc_u32 s29, s29, 0
	s_waitcnt vmcnt(8) lgkmcnt(0)
	s_barrier
	v_mfma_f32_16x16x32_bf16 v[126:129], v[158:161], v[194:197], v[126:129]
	v_mfma_f32_16x16x32_bf16 v[126:129], v[162:165], v[198:201], v[126:129]
	v_mfma_f32_16x16x32_bf16 v[122:125], v[174:177], v[198:201], v[122:125]
	v_mfma_f32_16x16x32_bf16 v[122:125], v[166:169], v[194:197], v[122:125]
	v_mfma_f32_16x16x32_bf16 v[114:117], v[178:181], v[194:197], v[114:117]
	v_mfma_f32_16x16x32_bf16 v[114:117], v[182:185], v[198:201], v[114:117]
	v_mfma_f32_16x16x32_bf16 v[106:109], v[190:193], v[198:201], v[106:109]
	v_mfma_f32_16x16x32_bf16 v[106:109], v[186:189], v[194:197], v[106:109]
	v_mfma_f32_16x16x32_bf16 v[90:93], v[186:189], v[202:205], v[90:93]
	v_mfma_f32_16x16x32_bf16 v[90:93], v[190:193], v[206:209], v[90:93]
	v_mfma_f32_16x16x32_bf16 v[98:101], v[182:185], v[206:209], v[98:101]
	v_mfma_f32_16x16x32_bf16 v[98:101], v[178:181], v[202:205], v[98:101]
	v_mfma_f32_16x16x32_bf16 v[110:113], v[166:169], v[202:205], v[110:113]
	v_mfma_f32_16x16x32_bf16 v[110:113], v[174:177], v[206:209], v[110:113]
	v_mfma_f32_16x16x32_bf16 v[118:121], v[162:165], v[206:209], v[118:121]
	v_mfma_f32_16x16x32_bf16 v[118:121], v[158:161], v[202:205], v[118:121]
	v_mfma_f32_16x16x32_bf16 v[102:105], v[158:161], v[210:213], v[102:105]
	v_mfma_f32_16x16x32_bf16 v[102:105], v[162:165], v[214:217], v[102:105]
	v_mfma_f32_16x16x32_bf16 v[94:97], v[174:177], v[214:217], v[94:97]
	v_mfma_f32_16x16x32_bf16 v[94:97], v[166:169], v[210:213], v[94:97]
	v_mfma_f32_16x16x32_bf16 v[82:85], v[178:181], v[210:213], v[82:85]
	v_mfma_f32_16x16x32_bf16 v[82:85], v[182:185], v[214:217], v[82:85]
	v_mfma_f32_16x16x32_bf16 v[74:77], v[190:193], v[214:217], v[74:77]
	v_mfma_f32_16x16x32_bf16 v[74:77], v[186:189], v[210:213], v[74:77]
	v_mfma_f32_16x16x32_bf16 v[66:69], v[186:189], v[218:221], v[66:69]
	v_mfma_f32_16x16x32_bf16 v[66:69], v[190:193], v[222:225], v[66:69]
	v_mfma_f32_16x16x32_bf16 v[70:73], v[182:185], v[222:225], v[70:73]
	v_mfma_f32_16x16x32_bf16 v[70:73], v[178:181], v[218:221], v[70:73]
	v_mfma_f32_16x16x32_bf16 v[78:81], v[166:169], v[218:221], v[78:81]
	v_mfma_f32_16x16x32_bf16 v[78:81], v[174:177], v[222:225], v[78:81]
	v_mfma_f32_16x16x32_bf16 v[86:89], v[162:165], v[222:225], v[86:89]
	v_mfma_f32_16x16x32_bf16 v[86:89], v[158:161], v[218:221], v[86:89]
	v_mfma_f32_16x16x32_bf16 v[62:65], v[158:161], v[226:229], v[62:65]
	v_mfma_f32_16x16x32_bf16 v[62:65], v[162:165], v[230:233], v[62:65]
	v_mfma_f32_16x16x32_bf16 v[58:61], v[174:177], v[230:233], v[58:61]
	v_mfma_f32_16x16x32_bf16 v[58:61], v[166:169], v[226:229], v[58:61]
	v_mfma_f32_16x16x32_bf16 v[50:53], v[178:181], v[226:229], v[50:53]
	v_mfma_f32_16x16x32_bf16 v[50:53], v[182:185], v[230:233], v[50:53]
	v_mfma_f32_16x16x32_bf16 v[42:45], v[190:193], v[230:233], v[42:45]
	v_mfma_f32_16x16x32_bf16 v[42:45], v[186:189], v[226:229], v[42:45]
	v_mfma_f32_16x16x32_bf16 v[26:29], v[186:189], v[234:237], v[26:29]
	v_mfma_f32_16x16x32_bf16 v[26:29], v[190:193], v[238:241], v[26:29]
	v_mfma_f32_16x16x32_bf16 v[34:37], v[182:185], v[238:241], v[34:37]
	v_mfma_f32_16x16x32_bf16 v[34:37], v[178:181], v[234:237], v[34:37]
	v_mfma_f32_16x16x32_bf16 v[46:49], v[166:169], v[234:237], v[46:49]
	v_mfma_f32_16x16x32_bf16 v[46:49], v[174:177], v[238:241], v[46:49]
	v_mfma_f32_16x16x32_bf16 v[54:57], v[162:165], v[238:241], v[54:57]
	v_mfma_f32_16x16x32_bf16 v[54:57], v[158:161], v[234:237], v[54:57]
	v_mfma_f32_16x16x32_bf16 v[38:41], v[158:161], v[242:245], v[38:41]
	v_mfma_f32_16x16x32_bf16 v[38:41], v[162:165], v[246:249], v[38:41]
	v_mfma_f32_16x16x32_bf16 v[30:33], v[174:177], v[246:249], v[30:33]
	v_mfma_f32_16x16x32_bf16 v[30:33], v[166:169], v[242:245], v[30:33]
	v_mfma_f32_16x16x32_bf16 v[18:21], v[178:181], v[242:245], v[18:21]
	v_mfma_f32_16x16x32_bf16 v[18:21], v[182:185], v[246:249], v[18:21]
	v_mfma_f32_16x16x32_bf16 v[10:13], v[190:193], v[246:249], v[10:13]
	v_mfma_f32_16x16x32_bf16 v[10:13], v[186:189], v[242:245], v[10:13]
	v_mfma_f32_16x16x32_bf16 v[2:5], v[186:189], v[250:253], v[2:5]
	v_mfma_f32_16x16x32_bf16 v[2:5], v[190:193], v[142:145], v[2:5]
	v_mfma_f32_16x16x32_bf16 v[6:9], v[182:185], v[142:145], v[6:9]
	v_mfma_f32_16x16x32_bf16 v[6:9], v[178:181], v[250:253], v[6:9]
	v_mfma_f32_16x16x32_bf16 v[14:17], v[166:169], v[250:253], v[14:17]
	v_mfma_f32_16x16x32_bf16 v[14:17], v[174:177], v[142:145], v[14:17]
	v_mfma_f32_16x16x32_bf16 v[22:25], v[162:165], v[142:145], v[22:25]
	v_mfma_f32_16x16x32_bf16 v[22:25], v[158:161], v[250:253], v[22:25]
	s_waitcnt vmcnt(0)
	s_barrier
	s_add_i32 s57, s57, 1
	s_cmp_lt_u32 s57, 44
	s_cbranch_scc1 .Lp9k_A_loop
	s_branch .Lp9k_done
; #define PG8_STAGE(bufoff, gbase, voff) do { _Pragma("unroll") for (int _i = 0; _i < 2; ++_i) \
;         __builtin_amdgcn_global_load_lds((const unsigned*)((const char*)(gbase) + (voff)[_i]), (PG8_LAS unsigned*)(lds + (bufoff) + ldsw + _i * 8192), 16, 0, 0); } while (0)
; #define PG8_LDA(dst, b, h) do { _Pragma("unroll") for (int m = 0; m < 4; ++m) _Pragma("unroll") for (int k = 0; k < 2; ++k) dst[m][k] = *(const PG8_LAS bf16x8*)(lds + PG8_SA(b, h) + aoff + m * 2048 + k * 1024); } while (0)
; #define PG8_LDB(dst, b, h) do { _Pragma("unroll") for (int n = 0; n < 2; ++n) _Pragma("unroll") for (int k = 0; k < 2; ++k) dst[n][k] = *(const PG8_LAS bf16x8*)(lds + PG8_SB(b, h) + boff + n * 2048 + k * 1024); } while (0)
; template <class Epi, class Sched, bool ALIGN_EPI>
; __device__ __forceinline__ void gemm_phase(PG8_LAS unsigned char* lds, const Gemm g, const Sched& S, const Epi& E) {
;     ...
;         for (int t = 0; t < nt; t += 2) {
;             if constexpr (Epi::MIDK) { if (t == (nt >> 1)) E.midk(acc, cur, wr, fr); }
;             const bool last = (t == nt - 2);
;             const char* a1 = cA + (size_t)(t + 1) * kstepA;
;             const char* a2 = last ? nA : cA + (size_t)(t + 2) * kstepA; const char* b2 = last ? nB : cB + (size_t)(t + 2) * kstep;
;             const char* a3 = a2 + kstepA; const char* b3 = b2 + kstep;
;             PG8_LDB(B0, 0, 0); PG8_LDB(B1, 0, 1); PG8_SCHED; PG8_LDA(At, 0, 0); PG8_STAGE(PG8_SA(1, 1), a1 + hstepA, voffA);
;             PG8_WAIT_V(8); PG8_WAIT_L(0); PG8_BAR; PG8_MMA(0, 0, At, B0); PG8_MMA(0, 1, At, B1); PG8_BAR; PG8_SCHED;
;             PG8_LDA(At, 0, 1); PG8_STAGE(PG8_SB(0, 0), b2, voffB); PG8_STAGE(PG8_SB(0, 1), b2 + hstepB, voffB); PG8_STAGE(PG8_SA(0, 0), a2, voffA);
;             PG8_WAIT_V(8); PG8_WAIT_L(0); PG8_BAR; PG8_MMA(1, 0, At, B0); PG8_MMA(1, 1, At, B1); PG8_BAR; PG8_SCHED;
;             PG8_LDB(B0, 1, 0); PG8_LDB(B1, 1, 1); PG8_SCHED; PG8_LDA(At, 1, 0); PG8_STAGE(PG8_SA(0, 1), a2 + hstepA, voffA);
;             PG8_WAIT_V(8); PG8_WAIT_L(0); PG8_BAR; PG8_MMA(0, 0, At, B0); PG8_MMA(0, 1, At, B1); PG8_BAR; PG8_SCHED;
;             PG8_LDA(At, 1, 1); PG8_STAGE(PG8_SB(1, 0), b3, voffB); PG8_STAGE(PG8_SB(1, 1), b3 + hstepB, voffB); PG8_STAGE(PG8_SA(1, 0), a3, voffA);
;             PG8_WAIT_V(8); PG8_WAIT_L(0); PG8_BAR; PG8_MMA(1, 0, At, B0); PG8_MMA(1, 1, At, B1); PG8_BAR; PG8_SCHED;
;         }
.Lp9k_B_init:
	s_setprio 1
	s_sub_u32 s28, s26, 0x57f80
	s_subb_u32 s29, s27, 0
	s_sub_u32 s58, s6, 0x58000
	s_subb_u32 s59, s7, 0
	ds_read_b128 v[194:197], v157 offset:0
	ds_read_b128 v[198:201], v157 offset:1024
	ds_read_b128 v[202:205], v157 offset:2048
	s_add_i32 m0, s60, 0xa000
	s_nop 0
	global_load_lds_dwordx4 v134, s[28:29]
	ds_read_b128 v[206:209], v157 offset:3072
	ds_read_b128 v[210:213], v157 offset:4096
	ds_read_b128 v[214:217], v157 offset:5120
	s_add_u32 s30, s28, 0x58000
	s_addc_u32 s31, s29, 0
	s_add_i32 m0, s60, 0xb000
	s_nop 0
	global_load_lds_dwordx4 v134, s[30:31]
	ds_read_b128 v[218:221], v157 offset:6144
	ds_read_b128 v[222:225], v157 offset:7168
	ds_read_b128 v[158:161], v155 offset:0
	s_add_u32 s30, s28, 0x160000
	s_addc_u32 s31, s29, 0
	s_add_i32 m0, s60, 0xe000
	s_nop 0
	global_load_lds_dwordx4 v134, s[30:31]
	ds_read_b128 v[162:165], v155 offset:1024
	ds_read_b128 v[166:169], v155 offset:2048
	ds_read_b128 v[174:177], v155 offset:3072
	s_add_u32 s30, s28, 0x1b8000
	s_addc_u32 s31, s29, 0
	s_add_i32 m0, s60, 0xf000
	s_nop 0
	global_load_lds_dwordx4 v134, s[30:31]
	ds_read_b128 v[178:181], v155 offset:16384
	ds_read_b128 v[182:185], v155 offset:17408
	ds_read_b128 v[186:189], v155 offset:18432
	s_add_u32 s34, s28, 0x80
	s_addc_u32 s35, s29, 0
	s_cmp_eq_u32 s57, 43
	s_cselect_b32 s34, s58, s34
	s_cselect_b32 s35, s59, s35
	s_add_i32 m0, s60, 0x0
	s_nop 0
	global_load_lds_dwordx4 v130, s[34:35]
	ds_read_b128 v[190:193], v155 offset:19456
	ds_read_b128 v[226:229], v157 offset:16384
	ds_read_b128 v[230:233], v157 offset:17408
	s_add_u32 s30, s34, 0x58000
	s_addc_u32 s31, s35, 0
	s_add_i32 m0, s60, 0x1000
	s_nop 0
	global_load_lds_dwordx4 v130, s[30:31]
	ds_read_b128 v[234:237], v157 offset:18432
	ds_read_b128 v[238:241], v157 offset:19456
	ds_read_b128 v[242:245], v157 offset:20480
	s_add_u32 s30, s34, 0x160000
	s_addc_u32 s31, s35, 0
	s_add_i32 m0, s60, 0x4000
	s_nop 0
	global_load_lds_dwordx4 v130, s[30:31]
	ds_read_b128 v[246:249], v157 offset:21504
	ds_read_b128 v[250:253], v157 offset:22528
	ds_read_b128 v[142:145], v157 offset:23552
	s_add_u32 s30, s34, 0x1b8000
	s_addc_u32 s31, s35, 0
	s_add_i32 m0, s60, 0x5000
	s_nop 0
	global_load_lds_dwordx4 v130, s[30:31]
	s_add_u32 s28, s28, 0x80
	s_addc_u32 s29, s29, 0
	s_waitcnt vmcnt(8) lgkmcnt(0)
	s_barrier
	v_mfma_f32_16x16x32_bf16 v[126:129], v[158:161], v[194:197], 0
	v_mfma_f32_16x16x32_bf16 v[126:129], v[162:165], v[198:201], v[126:129]
	v_mfma_f32_16x16x32_bf16 v[122:125], v[174:177], v[198:201], 0
	v_mfma_f32_16x16x32_bf16 v[122:125], v[166:169], v[194:197], v[122:125]
	v_mfma_f32_16x16x32_bf16 v[114:117], v[178:181], v[194:197], 0
	v_mfma_f32_16x16x32_bf16 v[114:117], v[182:185], v[198:201], v[114:117]
	v_mfma_f32_16x16x32_bf16 v[106:109], v[190:193], v[198:201], 0
	v_mfma_f32_16x16x32_bf16 v[106:109], v[186:189], v[194:197], v[106:109]
	v_mfma_f32_16x16x32_bf16 v[90:93], v[186:189], v[202:205], 0
	v_mfma_f32_16x16x32_bf16 v[90:93], v[190:193], v[206:209], v[90:93]
	v_mfma_f32_16x16x32_bf16 v[98:101], v[182:185], v[206:209], 0
	v_mfma_f32_16x16x32_bf16 v[98:101], v[178:181], v[202:205], v[98:101]
	v_mfma_f32_16x16x32_bf16 v[110:113], v[166:169], v[202:205], 0
	v_mfma_f32_16x16x32_bf16 v[110:113], v[174:177], v[206:209], v[110:113]
	v_mfma_f32_16x16x32_bf16 v[118:121], v[162:165], v[206:209], 0
	v_mfma_f32_16x16x32_bf16 v[118:121], v[158:161], v[202:205], v[118:121]
	v_mfma_f32_16x16x32_bf16 v[102:105], v[158:161], v[210:213], 0
	v_mfma_f32_16x16x32_bf16 v[102:105], v[162:165], v[214:217], v[102:105]
	v_mfma_f32_16x16x32_bf16 v[94:97], v[174:177], v[214:217], 0
	v_mfma_f32_16x16x32_bf16 v[94:97], v[166:169], v[210:213], v[94:97]
	v_mfma_f32_16x16x32_bf16 v[82:85], v[178:181], v[210:213], 0
	v_mfma_f32_16x16x32_bf16 v[82:85], v[182:185], v[214:217], v[82:85]
	v_mfma_f32_16x16x32_bf16 v[74:77], v[190:193], v[214:217], 0
	v_mfma_f32_16x16x32_bf16 v[74:77], v[186:189], v[210:213], v[74:77]
	v_mfma_f32_16x16x32_bf16 v[66:69], v[186:189], v[218:221], 0
	v_mfma_f32_16x16x32_bf16 v[66:69], v[190:193], v[222:225], v[66:69]
	v_mfma_f32_16x16x32_bf16 v[70:73], v[182:185], v[222:225], 0
	v_mfma_f32_16x16x32_bf16 v[70:73], v[178:181], v[218:221], v[70:73]
	v_mfma_f32_16x16x32_bf16 v[78:81], v[166:169], v[218:221], 0
	v_mfma_f32_16x16x32_bf16 v[78:81], v[174:177], v[222:225], v[78:81]
	v_mfma_f32_16x16x32_bf16 v[86:89], v[162:165], v[222:225], 0
	v_mfma_f32_16x16x32_bf16 v[86:89], v[158:161], v[218:221], v[86:89]
	v_mfma_f32_16x16x32_bf16 v[62:65], v[158:161], v[226:229], 0
	v_mfma_f32_16x16x32_bf16 v[62:65], v[162:165], v[230:233], v[62:65]
	v_mfma_f32_16x16x32_bf16 v[58:61], v[174:177], v[230:233], 0
	v_mfma_f32_16x16x32_bf16 v[58:61], v[166:169], v[226:229], v[58:61]
	v_mfma_f32_16x16x32_bf16 v[50:53], v[178:181], v[226:229], 0
	v_mfma_f32_16x16x32_bf16 v[50:53], v[182:185], v[230:233], v[50:53]
	v_mfma_f32_16x16x32_bf16 v[42:45], v[190:193], v[230:233], 0
	v_mfma_f32_16x16x32_bf16 v[42:45], v[186:189], v[226:229], v[42:45]
	v_mfma_f32_16x16x32_bf16 v[26:29], v[186:189], v[234:237], 0
	v_mfma_f32_16x16x32_bf16 v[26:29], v[190:193], v[238:241], v[26:29]
	v_mfma_f32_16x16x32_bf16 v[34:37], v[182:185], v[238:241], 0
	v_mfma_f32_16x16x32_bf16 v[34:37], v[178:181], v[234:237], v[34:37]
	v_mfma_f32_16x16x32_bf16 v[46:49], v[166:169], v[234:237], 0
	v_mfma_f32_16x16x32_bf16 v[46:49], v[174:177], v[238:241], v[46:49]
	v_mfma_f32_16x16x32_bf16 v[54:57], v[162:165], v[238:241], 0
	v_mfma_f32_16x16x32_bf16 v[54:57], v[158:161], v[234:237], v[54:57]
	v_mfma_f32_16x16x32_bf16 v[38:41], v[158:161], v[242:245], 0
	v_mfma_f32_16x16x32_bf16 v[38:41], v[162:165], v[246:249], v[38:41]
	v_mfma_f32_16x16x32_bf16 v[30:33], v[174:177], v[246:249], 0
	v_mfma_f32_16x16x32_bf16 v[30:33], v[166:169], v[242:245], v[30:33]
	v_mfma_f32_16x16x32_bf16 v[18:21], v[178:181], v[242:245], 0
	v_mfma_f32_16x16x32_bf16 v[18:21], v[182:185], v[246:249], v[18:21]
	v_mfma_f32_16x16x32_bf16 v[10:13], v[190:193], v[246:249], 0
	v_mfma_f32_16x16x32_bf16 v[10:13], v[186:189], v[242:245], v[10:13]
	v_mfma_f32_16x16x32_bf16 v[2:5], v[186:189], v[250:253], 0
	v_mfma_f32_16x16x32_bf16 v[2:5], v[190:193], v[142:145], v[2:5]
	v_mfma_f32_16x16x32_bf16 v[6:9], v[182:185], v[142:145], 0
	v_mfma_f32_16x16x32_bf16 v[6:9], v[178:181], v[250:253], v[6:9]
	v_mfma_f32_16x16x32_bf16 v[14:17], v[166:169], v[250:253], 0
	v_mfma_f32_16x16x32_bf16 v[14:17], v[174:177], v[142:145], v[14:17]
	v_mfma_f32_16x16x32_bf16 v[22:25], v[162:165], v[142:145], 0
	v_mfma_f32_16x16x32_bf16 v[22:25], v[158:161], v[250:253], v[22:25]
	s_waitcnt vmcnt(0)
	s_barrier
; #define PG8_STAGE(bufoff, gbase, voff) do { _Pragma("unroll") for (int _i = 0; _i < 2; ++_i) \
;         __builtin_amdgcn_global_load_lds((const unsigned*)((const char*)(gbase) + (voff)[_i]), (PG8_LAS unsigned*)(lds + (bufoff) + ldsw + _i * 8192), 16, 0, 0); } while (0)
; #define PG8_LDA(dst, b, h) do { _Pragma("unroll") for (int m = 0; m < 4; ++m) _Pragma("unroll") for (int k = 0; k < 2; ++k) dst[m][k] = *(const PG8_LAS bf16x8*)(lds + PG8_SA(b, h) + aoff + m * 2048 + k * 1024); } while (0)
; #define PG8_LDB(dst, b, h) do { _Pragma("unroll") for (int n = 0; n < 2; ++n) _Pragma("unroll") for (int k = 0; k < 2; ++k) dst[n][k] = *(const PG8_LAS bf16x8*)(lds + PG8_SB(b, h) + boff + n * 2048 + k * 1024); } while (0)
; template <class Epi, class Sched, bool ALIGN_EPI>
; __device__ __forceinline__ void gemm_phase(PG8_LAS unsigned char* lds, const Gemm g, const Sched& S, const Epi& E) {
;     ...
;         for (int t = 0; t < nt; t += 2) {
;             if constexpr (Epi::MIDK) { if (t == (nt >> 1)) E.midk(acc, cur, wr, fr); }
;             const bool last = (t == nt - 2);
;             const char* a1 = cA + (size_t)(t + 1) * kstepA;
;             const char* a2 = last ? nA : cA + (size_t)(t + 2) * kstepA; const char* b2 = last ? nB : cB + (size_t)(t + 2) * kstep;
;             const char* a3 = a2 + kstepA; const char* b3 = b2 + kstep;
;             PG8_LDB(B0, 0, 0); PG8_LDB(B1, 0, 1); PG8_SCHED; PG8_LDA(At, 0, 0); PG8_STAGE(PG8_SA(1, 1), a1 + hstepA, voffA);
;             PG8_WAIT_V(8); PG8_WAIT_L(0); PG8_BAR; PG8_MMA(0, 0, At, B0); PG8_MMA(0, 1, At, B1); PG8_BAR; PG8_SCHED;
;             PG8_LDA(At, 0, 1); PG8_STAGE(PG8_SB(0, 0), b2, voffB); PG8_STAGE(PG8_SB(0, 1), b2 + hstepB, voffB); PG8_STAGE(PG8_SA(0, 0), a2, voffA);
;             PG8_WAIT_V(8); PG8_WAIT_L(0); PG8_BAR; PG8_MMA(1, 0, At, B0); PG8_MMA(1, 1, At, B1); PG8_BAR; PG8_SCHED;
;             PG8_LDB(B0, 1, 0); PG8_LDB(B1, 1, 1); PG8_SCHED; PG8_LDA(At, 1, 0); PG8_STAGE(PG8_SA(0, 1), a2 + hstepA, voffA);
;             PG8_WAIT_V(8); PG8_WAIT_L(0); PG8_BAR; PG8_MMA(0, 0, At, B0); PG8_MMA(0, 1, At, B1); PG8_BAR; PG8_SCHED;
;             PG8_LDA(At, 1, 1); PG8_STAGE(PG8_SB(1, 0), b3, voffB); PG8_STAGE(PG8_SB(1, 1), b3 + hstepB, voffB); PG8_STAGE(PG8_SA(1, 0), a3, voffA);
;             PG8_WAIT_V(8); PG8_WAIT_L(0); PG8_BAR; PG8_MMA(1, 0, At, B0); PG8_MMA(1, 1, At, B1); PG8_BAR; PG8_SCHED;
;         }
	ds_read_b128 v[194:197], v157 offset:32768
	ds_read_b128 v[198:201], v157 offset:33792
	ds_read_b128 v[202:205], v157 offset:34816
	s_cmp_eq_u32 s57, 43
	s_cselect_b32 s28, s58, s28
	s_cselect_b32 s29, s59, s29
	s_add_i32 m0, s60, 0x2000
	s_nop 0
	global_load_lds_dwordx4 v134, s[28:29]
	ds_read_b128 v[206:209], v157 offset:35840
	ds_read_b128 v[210:213], v157 offset:36864
	ds_read_b128 v[214:217], v157 offset:37888
	s_add_u32 s30, s28, 0x58000
	s_addc_u32 s31, s29, 0
	s_add_i32 m0, s60, 0x3000
	s_nop 0
	global_load_lds_dwordx4 v134, s[30:31]
	ds_read_b128 v[218:221], v157 offset:38912
	ds_read_b128 v[222:225], v157 offset:39936
	ds_read_b128 v[158:161], v155 offset:32768
	s_add_u32 s30, s28, 0x160000
	s_addc_u32 s31, s29, 0
	s_add_i32 m0, s60, 0x6000
	s_nop 0
	global_load_lds_dwordx4 v134, s[30:31]
	ds_read_b128 v[162:165], v155 offset:33792
	ds_read_b128 v[166:169], v155 offset:34816
	ds_read_b128 v[174:177], v155 offset:35840
	s_add_u32 s30, s28, 0x1b8000
	s_addc_u32 s31, s29, 0
	s_add_i32 m0, s60, 0x7000
	s_nop 0
	global_load_lds_dwordx4 v134, s[30:31]
	ds_read_b128 v[178:181], v155 offset:49152
	ds_read_b128 v[182:185], v155 offset:50176
	ds_read_b128 v[186:189], v155 offset:51200
	s_add_u32 s34, s28, 0x80
	s_addc_u32 s35, s29, 0
	s_add_i32 m0, s60, 0x8000
	s_nop 0
	global_load_lds_dwordx4 v130, s[34:35]
	ds_read_b128 v[190:193], v155 offset:52224
	ds_read_b128 v[226:229], v157 offset:49152
	ds_read_b128 v[230:233], v157 offset:50176
	s_add_u32 s30, s34, 0x58000
	s_addc_u32 s31, s35, 0
	s_add_i32 m0, s60, 0x9000
	s_nop 0
	global_load_lds_dwordx4 v130, s[30:31]
	ds_read_b128 v[234:237], v157 offset:51200
	ds_read_b128 v[238:241], v157 offset:52224
	ds_read_b128 v[242:245], v157 offset:53248
	s_add_u32 s30, s34, 0x160000
	s_addc_u32 s31, s35, 0
	s_add_i32 m0, s60, 0xc000
	s_nop 0
	global_load_lds_dwordx4 v130, s[30:31]
	ds_read_b128 v[246:249], v157 offset:54272
	ds_read_b128 v[250:253], v157 offset:55296
	ds_read_b128 v[142:145], v157 offset:56320
	s_add_u32 s30, s34, 0x1b8000
	s_addc_u32 s31, s35, 0
	s_add_i32 m0, s60, 0xd000
	s_nop 0
	global_load_lds_dwordx4 v130, s[30:31]
	s_add_u32 s28, s28, 0x80
	s_addc_u32 s29, s29, 0
	s_waitcnt vmcnt(8) lgkmcnt(0)
	s_barrier
	v_mfma_f32_16x16x32_bf16 v[126:129], v[158:161], v[194:197], v[126:129]
	v_mfma_f32_16x16x32_bf16 v[126:129], v[162:165], v[198:201], v[126:129]
	v_mfma_f32_16x16x32_bf16 v[122:125], v[174:177], v[198:201], v[122:125]
	v_mfma_f32_16x16x32_bf16 v[122:125], v[166:169], v[194:197], v[122:125]
	v_mfma_f32_16x16x32_bf16 v[114:117], v[178:181], v[194:197], v[114:117]
	v_mfma_f32_16x16x32_bf16 v[114:117], v[182:185], v[198:201], v[114:117]
	v_mfma_f32_16x16x32_bf16 v[106:109], v[190:193], v[198:201], v[106:109]
	v_mfma_f32_16x16x32_bf16 v[106:109], v[186:189], v[194:197], v[106:109]
	v_mfma_f32_16x16x32_bf16 v[90:93], v[186:189], v[202:205], v[90:93]
	v_mfma_f32_16x16x32_bf16 v[90:93], v[190:193], v[206:209], v[90:93]
	v_mfma_f32_16x16x32_bf16 v[98:101], v[182:185], v[206:209], v[98:101]
	v_mfma_f32_16x16x32_bf16 v[98:101], v[178:181], v[202:205], v[98:101]
	v_mfma_f32_16x16x32_bf16 v[110:113], v[166:169], v[202:205], v[110:113]
	v_mfma_f32_16x16x32_bf16 v[110:113], v[174:177], v[206:209], v[110:113]
	v_mfma_f32_16x16x32_bf16 v[118:121], v[162:165], v[206:209], v[118:121]
	v_mfma_f32_16x16x32_bf16 v[118:121], v[158:161], v[202:205], v[118:121]
	v_mfma_f32_16x16x32_bf16 v[102:105], v[158:161], v[210:213], v[102:105]
	v_mfma_f32_16x16x32_bf16 v[102:105], v[162:165], v[214:217], v[102:105]
	v_mfma_f32_16x16x32_bf16 v[94:97], v[174:177], v[214:217], v[94:97]
	v_mfma_f32_16x16x32_bf16 v[94:97], v[166:169], v[210:213], v[94:97]
	v_mfma_f32_16x16x32_bf16 v[82:85], v[178:181], v[210:213], v[82:85]
	v_mfma_f32_16x16x32_bf16 v[82:85], v[182:185], v[214:217], v[82:85]
	v_mfma_f32_16x16x32_bf16 v[74:77], v[190:193], v[214:217], v[74:77]
	v_mfma_f32_16x16x32_bf16 v[74:77], v[186:189], v[210:213], v[74:77]
	v_mfma_f32_16x16x32_bf16 v[66:69], v[186:189], v[218:221], v[66:69]
	v_mfma_f32_16x16x32_bf16 v[66:69], v[190:193], v[222:225], v[66:69]
	v_mfma_f32_16x16x32_bf16 v[70:73], v[182:185], v[222:225], v[70:73]
	v_mfma_f32_16x16x32_bf16 v[70:73], v[178:181], v[218:221], v[70:73]
	v_mfma_f32_16x16x32_bf16 v[78:81], v[166:169], v[218:221], v[78:81]
	v_mfma_f32_16x16x32_bf16 v[78:81], v[174:177], v[222:225], v[78:81]
	v_mfma_f32_16x16x32_bf16 v[86:89], v[162:165], v[222:225], v[86:89]
	v_mfma_f32_16x16x32_bf16 v[86:89], v[158:161], v[218:221], v[86:89]
	v_mfma_f32_16x16x32_bf16 v[62:65], v[158:161], v[226:229], v[62:65]
	v_mfma_f32_16x16x32_bf16 v[62:65], v[162:165], v[230:233], v[62:65]
	v_mfma_f32_16x16x32_bf16 v[58:61], v[174:177], v[230:233], v[58:61]
	v_mfma_f32_16x16x32_bf16 v[58:61], v[166:169], v[226:229], v[58:61]
	v_mfma_f32_16x16x32_bf16 v[50:53], v[178:181], v[226:229], v[50:53]
	v_mfma_f32_16x16x32_bf16 v[50:53], v[182:185], v[230:233], v[50:53]
	v_mfma_f32_16x16x32_bf16 v[42:45], v[190:193], v[230:233], v[42:45]
	v_mfma_f32_16x16x32_bf16 v[42:45], v[186:189], v[226:229], v[42:45]
	v_mfma_f32_16x16x32_bf16 v[26:29], v[186:189], v[234:237], v[26:29]
	v_mfma_f32_16x16x32_bf16 v[26:29], v[190:193], v[238:241], v[26:29]
	v_mfma_f32_16x16x32_bf16 v[34:37], v[182:185], v[238:241], v[34:37]
	v_mfma_f32_16x16x32_bf16 v[34:37], v[178:181], v[234:237], v[34:37]
	v_mfma_f32_16x16x32_bf16 v[46:49], v[166:169], v[234:237], v[46:49]
	v_mfma_f32_16x16x32_bf16 v[46:49], v[174:177], v[238:241], v[46:49]
	v_mfma_f32_16x16x32_bf16 v[54:57], v[162:165], v[238:241], v[54:57]
	v_mfma_f32_16x16x32_bf16 v[54:57], v[158:161], v[234:237], v[54:57]
	v_mfma_f32_16x16x32_bf16 v[38:41], v[158:161], v[242:245], v[38:41]
	v_mfma_f32_16x16x32_bf16 v[38:41], v[162:165], v[246:249], v[38:41]
	v_mfma_f32_16x16x32_bf16 v[30:33], v[174:177], v[246:249], v[30:33]
	v_mfma_f32_16x16x32_bf16 v[30:33], v[166:169], v[242:245], v[30:33]
	v_mfma_f32_16x16x32_bf16 v[18:21], v[178:181], v[242:245], v[18:21]
	v_mfma_f32_16x16x32_bf16 v[18:21], v[182:185], v[246:249], v[18:21]
	v_mfma_f32_16x16x32_bf16 v[10:13], v[190:193], v[246:249], v[10:13]
	v_mfma_f32_16x16x32_bf16 v[10:13], v[186:189], v[242:245], v[10:13]
	v_mfma_f32_16x16x32_bf16 v[2:5], v[186:189], v[250:253], v[2:5]
	v_mfma_f32_16x16x32_bf16 v[2:5], v[190:193], v[142:145], v[2:5]
	v_mfma_f32_16x16x32_bf16 v[6:9], v[182:185], v[142:145], v[6:9]
	v_mfma_f32_16x16x32_bf16 v[6:9], v[178:181], v[250:253], v[6:9]
	v_mfma_f32_16x16x32_bf16 v[14:17], v[166:169], v[250:253], v[14:17]
	v_mfma_f32_16x16x32_bf16 v[14:17], v[174:177], v[142:145], v[14:17]
	v_mfma_f32_16x16x32_bf16 v[22:25], v[162:165], v[142:145], v[22:25]
	v_mfma_f32_16x16x32_bf16 v[22:25], v[158:161], v[250:253], v[22:25]
	s_waitcnt vmcnt(0)
	s_barrier
	s_add_i32 s57, s57, 1
; #define PG8_STAGE(bufoff, gbase, voff) do { _Pragma("unroll") for (int _i = 0; _i < 2; ++_i) \
;         __builtin_amdgcn_global_load_lds((const unsigned*)((const char*)(gbase) + (voff)[_i]), (PG8_LAS unsigned*)(lds + (bufoff) + ldsw + _i * 8192), 16, 0, 0); } while (0)
; #define PG8_LDA(dst, b, h) do { _Pragma("unroll") for (int m = 0; m < 4; ++m) _Pragma("unroll") for (int k = 0; k < 2; ++k) dst[m][k] = *(const PG8_LAS bf16x8*)(lds + PG8_SA(b, h) + aoff + m * 2048 + k * 1024); } while (0)
; #define PG8_LDB(dst, b, h) do { _Pragma("unroll") for (int n = 0; n < 2; ++n) _Pragma("unroll") for (int k = 0; k < 2; ++k) dst[n][k] = *(const PG8_LAS bf16x8*)(lds + PG8_SB(b, h) + boff + n * 2048 + k * 1024); } while (0)
; template <class Epi, class Sched, bool ALIGN_EPI>
; __device__ __forceinline__ void gemm_phase(PG8_LAS unsigned char* lds, const Gemm g, const Sched& S, const Epi& E) {
;     ...
;         for (int t = 0; t < nt; t += 2) {
;             if constexpr (Epi::MIDK) { if (t == (nt >> 1)) E.midk(acc, cur, wr, fr); }
;             const bool last = (t == nt - 2);
;             const char* a1 = cA + (size_t)(t + 1) * kstepA;
;             const char* a2 = last ? nA : cA + (size_t)(t + 2) * kstepA; const char* b2 = last ? nB : cB + (size_t)(t + 2) * kstep;
;             const char* a3 = a2 + kstepA; const char* b3 = b2 + kstep;
;             PG8_LDB(B0, 0, 0); PG8_LDB(B1, 0, 1); PG8_SCHED; PG8_LDA(At, 0, 0); PG8_STAGE(PG8_SA(1, 1), a1 + hstepA, voffA);
;             PG8_WAIT_V(8); PG8_WAIT_L(0); PG8_BAR; PG8_MMA(0, 0, At, B0); PG8_MMA(0, 1, At, B1); PG8_BAR; PG8_SCHED;
;             PG8_LDA(At, 0, 1); PG8_STAGE(PG8_SB(0, 0), b2, voffB); PG8_STAGE(PG8_SB(0, 1), b2 + hstepB, voffB); PG8_STAGE(PG8_SA(0, 0), a2, voffA);
;             PG8_WAIT_V(8); PG8_WAIT_L(0); PG8_BAR; PG8_MMA(1, 0, At, B0); PG8_MMA(1, 1, At, B1); PG8_BAR; PG8_SCHED;
;             PG8_LDB(B0, 1, 0); PG8_LDB(B1, 1, 1); PG8_SCHED; PG8_LDA(At, 1, 0); PG8_STAGE(PG8_SA(0, 1), a2 + hstepA, voffA);
;             PG8_WAIT_V(8); PG8_WAIT_L(0); PG8_BAR; PG8_MMA(0, 0, At, B0); PG8_MMA(0, 1, At, B1); PG8_BAR; PG8_SCHED;
;             PG8_LDA(At, 1, 1); PG8_STAGE(PG8_SB(1, 0), b3, voffB); PG8_STAGE(PG8_SB(1, 1), b3 + hstepB, voffB); PG8_STAGE(PG8_SA(1, 0), a3, voffA);
;             PG8_WAIT_V(8); PG8_WAIT_L(0); PG8_BAR; PG8_MMA(1, 0, At, B0); PG8_MMA(1, 1, At, B1); PG8_BAR; PG8_SCHED;
;         }
.Lp9k_B_loop:
	ds_read_b128 v[194:197], v157 offset:0
	ds_read_b128 v[198:201], v157 offset:1024
	ds_read_b128 v[202:205], v157 offset:2048
	s_add_i32 m0, s60, 0xa000
	s_nop 0
	global_load_lds_dwordx4 v134, s[28:29]
	ds_read_b128 v[206:209], v157 offset:3072
	ds_read_b128 v[210:213], v157 offset:4096
	ds_read_b128 v[214:217], v157 offset:5120
	s_add_u32 s30, s28, 0x58000
	s_addc_u32 s31, s29, 0
	s_add_i32 m0, s60, 0xb000
	s_nop 0
	global_load_lds_dwordx4 v134, s[30:31]
	ds_read_b128 v[218:221], v157 offset:6144
	ds_read_b128 v[222:225], v157 offset:7168
	ds_read_b128 v[158:161], v155 offset:0
	s_add_u32 s30, s28, 0x160000
	s_addc_u32 s31, s29, 0
	s_add_i32 m0, s60, 0xe000
	s_nop 0
	global_load_lds_dwordx4 v134, s[30:31]
	ds_read_b128 v[162:165], v155 offset:1024
	ds_read_b128 v[166:169], v155 offset:2048
	ds_read_b128 v[174:177], v155 offset:3072
	s_add_u32 s30, s28, 0x1b8000
	s_addc_u32 s31, s29, 0
	s_add_i32 m0, s60, 0xf000
	s_nop 0
	global_load_lds_dwordx4 v134, s[30:31]
	ds_read_b128 v[178:181], v155 offset:16384
	ds_read_b128 v[182:185], v155 offset:17408
	ds_read_b128 v[186:189], v155 offset:18432
	s_add_u32 s34, s28, 0x80
	s_addc_u32 s35, s29, 0
	s_cmp_eq_u32 s57, 43
	s_cselect_b32 s34, s58, s34
	s_cselect_b32 s35, s59, s35
	s_add_i32 m0, s60, 0x0
	s_nop 0
	global_load_lds_dwordx4 v130, s[34:35]
	ds_read_b128 v[190:193], v155 offset:19456
	ds_read_b128 v[226:229], v157 offset:16384
	ds_read_b128 v[230:233], v157 offset:17408
	s_add_u32 s30, s34, 0x58000
	s_addc_u32 s31, s35, 0
	s_add_i32 m0, s60, 0x1000
	s_nop 0
	global_load_lds_dwordx4 v130, s[30:31]
	ds_read_b128 v[234:237], v157 offset:18432
	ds_read_b128 v[238:241], v157 offset:19456
	ds_read_b128 v[242:245], v157 offset:20480
	s_add_u32 s30, s34, 0x160000
	s_addc_u32 s31, s35, 0
	s_add_i32 m0, s60, 0x4000
	s_nop 0
	global_load_lds_dwordx4 v130, s[30:31]
	ds_read_b128 v[246:249], v157 offset:21504
	ds_read_b128 v[250:253], v157 offset:22528
	ds_read_b128 v[142:145], v157 offset:23552
	s_add_u32 s30, s34, 0x1b8000
	s_addc_u32 s31, s35, 0
	s_add_i32 m0, s60, 0x5000
	s_nop 0
	global_load_lds_dwordx4 v130, s[30:31]
	s_add_u32 s28, s28, 0x80
	s_addc_u32 s29, s29, 0
	s_waitcnt vmcnt(8) lgkmcnt(0)
	s_barrier
	v_mfma_f32_16x16x32_bf16 v[126:129], v[158:161], v[194:197], v[126:129]
	v_mfma_f32_16x16x32_bf16 v[126:129], v[162:165], v[198:201], v[126:129]
	v_mfma_f32_16x16x32_bf16 v[122:125], v[174:177], v[198:201], v[122:125]
	v_mfma_f32_16x16x32_bf16 v[122:125], v[166:169], v[194:197], v[122:125]
	v_mfma_f32_16x16x32_bf16 v[114:117], v[178:181], v[194:197], v[114:117]
	v_mfma_f32_16x16x32_bf16 v[114:117], v[182:185], v[198:201], v[114:117]
	v_mfma_f32_16x16x32_bf16 v[106:109], v[190:193], v[198:201], v[106:109]
	v_mfma_f32_16x16x32_bf16 v[106:109], v[186:189], v[194:197], v[106:109]
	v_mfma_f32_16x16x32_bf16 v[90:93], v[186:189], v[202:205], v[90:93]
	v_mfma_f32_16x16x32_bf16 v[90:93], v[190:193], v[206:209], v[90:93]
	v_mfma_f32_16x16x32_bf16 v[98:101], v[182:185], v[206:209], v[98:101]
	v_mfma_f32_16x16x32_bf16 v[98:101], v[178:181], v[202:205], v[98:101]
	v_mfma_f32_16x16x32_bf16 v[110:113], v[166:169], v[202:205], v[110:113]
	v_mfma_f32_16x16x32_bf16 v[110:113], v[174:177], v[206:209], v[110:113]
	v_mfma_f32_16x16x32_bf16 v[118:121], v[162:165], v[206:209], v[118:121]
	v_mfma_f32_16x16x32_bf16 v[118:121], v[158:161], v[202:205], v[118:121]
	v_mfma_f32_16x16x32_bf16 v[102:105], v[158:161], v[210:213], v[102:105]
	v_mfma_f32_16x16x32_bf16 v[102:105], v[162:165], v[214:217], v[102:105]
	v_mfma_f32_16x16x32_bf16 v[94:97], v[174:177], v[214:217], v[94:97]
	v_mfma_f32_16x16x32_bf16 v[94:97], v[166:169], v[210:213], v[94:97]
	v_mfma_f32_16x16x32_bf16 v[82:85], v[178:181], v[210:213], v[82:85]
	v_mfma_f32_16x16x32_bf16 v[82:85], v[182:185], v[214:217], v[82:85]
	v_mfma_f32_16x16x32_bf16 v[74:77], v[190:193], v[214:217], v[74:77]
	v_mfma_f32_16x16x32_bf16 v[74:77], v[186:189], v[210:213], v[74:77]
	v_mfma_f32_16x16x32_bf16 v[66:69], v[186:189], v[218:221], v[66:69]
	v_mfma_f32_16x16x32_bf16 v[66:69], v[190:193], v[222:225], v[66:69]
	v_mfma_f32_16x16x32_bf16 v[70:73], v[182:185], v[222:225], v[70:73]
	v_mfma_f32_16x16x32_bf16 v[70:73], v[178:181], v[218:221], v[70:73]
	v_mfma_f32_16x16x32_bf16 v[78:81], v[166:169], v[218:221], v[78:81]
	v_mfma_f32_16x16x32_bf16 v[78:81], v[174:177], v[222:225], v[78:81]
	v_mfma_f32_16x16x32_bf16 v[86:89], v[162:165], v[222:225], v[86:89]
	v_mfma_f32_16x16x32_bf16 v[86:89], v[158:161], v[218:221], v[86:89]
	v_mfma_f32_16x16x32_bf16 v[62:65], v[158:161], v[226:229], v[62:65]
	v_mfma_f32_16x16x32_bf16 v[62:65], v[162:165], v[230:233], v[62:65]
	v_mfma_f32_16x16x32_bf16 v[58:61], v[174:177], v[230:233], v[58:61]
	v_mfma_f32_16x16x32_bf16 v[58:61], v[166:169], v[226:229], v[58:61]
	v_mfma_f32_16x16x32_bf16 v[50:53], v[178:181], v[226:229], v[50:53]
	v_mfma_f32_16x16x32_bf16 v[50:53], v[182:185], v[230:233], v[50:53]
	v_mfma_f32_16x16x32_bf16 v[42:45], v[190:193], v[230:233], v[42:45]
	v_mfma_f32_16x16x32_bf16 v[42:45], v[186:189], v[226:229], v[42:45]
	v_mfma_f32_16x16x32_bf16 v[26:29], v[186:189], v[234:237], v[26:29]
	v_mfma_f32_16x16x32_bf16 v[26:29], v[190:193], v[238:241], v[26:29]
	v_mfma_f32_16x16x32_bf16 v[34:37], v[182:185], v[238:241], v[34:37]
	v_mfma_f32_16x16x32_bf16 v[34:37], v[178:181], v[234:237], v[34:37]
	v_mfma_f32_16x16x32_bf16 v[46:49], v[166:169], v[234:237], v[46:49]
	v_mfma_f32_16x16x32_bf16 v[46:49], v[174:177], v[238:241], v[46:49]
	v_mfma_f32_16x16x32_bf16 v[54:57], v[162:165], v[238:241], v[54:57]
	v_mfma_f32_16x16x32_bf16 v[54:57], v[158:161], v[234:237], v[54:57]
	v_mfma_f32_16x16x32_bf16 v[38:41], v[158:161], v[242:245], v[38:41]
	v_mfma_f32_16x16x32_bf16 v[38:41], v[162:165], v[246:249], v[38:41]
	v_mfma_f32_16x16x32_bf16 v[30:33], v[174:177], v[246:249], v[30:33]
	v_mfma_f32_16x16x32_bf16 v[30:33], v[166:169], v[242:245], v[30:33]
	v_mfma_f32_16x16x32_bf16 v[18:21], v[178:181], v[242:245], v[18:21]
	v_mfma_f32_16x16x32_bf16 v[18:21], v[182:185], v[246:249], v[18:21]
	v_mfma_f32_16x16x32_bf16 v[10:13], v[190:193], v[246:249], v[10:13]
	v_mfma_f32_16x16x32_bf16 v[10:13], v[186:189], v[242:245], v[10:13]
	v_mfma_f32_16x16x32_bf16 v[2:5], v[186:189], v[250:253], v[2:5]
	v_mfma_f32_16x16x32_bf16 v[2:5], v[190:193], v[142:145], v[2:5]
	v_mfma_f32_16x16x32_bf16 v[6:9], v[182:185], v[142:145], v[6:9]
	v_mfma_f32_16x16x32_bf16 v[6:9], v[178:181], v[250:253], v[6:9]
	v_mfma_f32_16x16x32_bf16 v[14:17], v[166:169], v[250:253], v[14:17]
	v_mfma_f32_16x16x32_bf16 v[14:17], v[174:177], v[142:145], v[14:17]
	v_mfma_f32_16x16x32_bf16 v[22:25], v[162:165], v[142:145], v[22:25]
	v_mfma_f32_16x16x32_bf16 v[22:25], v[158:161], v[250:253], v[22:25]
	s_waitcnt vmcnt(0)
	s_barrier
; #define PG8_STAGE(bufoff, gbase, voff) do { _Pragma("unroll") for (int _i = 0; _i < 2; ++_i) \
;         __builtin_amdgcn_global_load_lds((const unsigned*)((const char*)(gbase) + (voff)[_i]), (PG8_LAS unsigned*)(lds + (bufoff) + ldsw + _i * 8192), 16, 0, 0); } while (0)
; #define PG8_LDA(dst, b, h) do { _Pragma("unroll") for (int m = 0; m < 4; ++m) _Pragma("unroll") for (int k = 0; k < 2; ++k) dst[m][k] = *(const PG8_LAS bf16x8*)(lds + PG8_SA(b, h) + aoff + m * 2048 + k * 1024); } while (0)
; #define PG8_WAIT_V(n) asm volatile("s_waitcnt vmcnt(" #n ")" ::: "memory")
; #define PG8_WAIT_L(n) asm volatile("s_waitcnt lgkmcnt(" #n ")" ::: "memory")
; template <class Epi, class Sched, bool ALIGN_EPI>
; __device__ __forceinline__ void gemm_phase(PG8_LAS unsigned char* lds, const Gemm g, const Sched& S, const Epi& E) {
;     ...
;         for (int t = 0; t < nt; t += 2) {
;             if constexpr (Epi::MIDK) { if (t == (nt >> 1)) E.midk(acc, cur, wr, fr); }
;             const bool last = (t == nt - 2);
;             const char* a1 = cA + (size_t)(t + 1) * kstepA;
;             const char* a2 = last ? nA : cA + (size_t)(t + 2) * kstepA; const char* b2 = last ? nB : cB + (size_t)(t + 2) * kstep;
;             const char* a3 = a2 + kstepA; const char* b3 = b2 + kstep;
;             PG8_LDB(B0, 0, 0); PG8_LDB(B1, 0, 1); PG8_SCHED; PG8_LDA(At, 0, 0); PG8_STAGE(PG8_SA(1, 1), a1 + hstepA, voffA);
;             PG8_WAIT_V(8); PG8_WAIT_L(0); PG8_BAR; PG8_MMA(0, 0, At, B0); PG8_MMA(0, 1, At, B1); PG8_BAR; PG8_SCHED;
;             PG8_LDA(At, 0, 1); PG8_STAGE(PG8_SB(0, 0), b2, voffB); PG8_STAGE(PG8_SB(0, 1), b2 + hstepB, voffB); PG8_STAGE(PG8_SA(0, 0), a2, voffA);
;             PG8_WAIT_V(8); PG8_WAIT_L(0); PG8_BAR; PG8_MMA(1, 0, At, B0); PG8_MMA(1, 1, At, B1); PG8_BAR; PG8_SCHED;
;             PG8_LDB(B0, 1, 0); PG8_LDB(B1, 1, 1); PG8_SCHED; PG8_LDA(At, 1, 0); PG8_STAGE(PG8_SA(0, 1), a2 + hstepA, voffA);
;             PG8_WAIT_V(8); PG8_WAIT_L(0); PG8_BAR; PG8_MMA(0, 0, At, B0); PG8_MMA(0, 1, At, B1); PG8_BAR; PG8_SCHED;
;             PG8_LDA(At, 1, 1); PG8_STAGE(PG8_SB(1, 0), b3, voffB); PG8_STAGE(PG8_SB(1, 1), b3 + hstepB, voffB); PG8_STAGE(PG8_SA(1, 0), a3, voffA);
;             PG8_WAIT_V(8); PG8_WAIT_L(0); PG8_BAR; PG8_MMA(1, 0, At, B0); PG8_MMA(1, 1, At, B1); PG8_BAR; PG8_SCHED;
;         }
;         if constexpr (ALIGN_EPI) { if (wr == 0) PG8_BAR; }
	ds_read_b128 v[194:197], v157 offset:32768
	ds_read_b128 v[198:201], v157 offset:33792
	ds_read_b128 v[202:205], v157 offset:34816
	s_cmp_eq_u32 s57, 43
	s_cselect_b32 s28, s58, s28
	s_cselect_b32 s29, s59, s29
	s_add_i32 m0, s60, 0x2000
	s_nop 0
	global_load_lds_dwordx4 v134, s[28:29]
	ds_read_b128 v[206:209], v157 offset:35840
	ds_read_b128 v[210:213], v157 offset:36864
	ds_read_b128 v[214:217], v157 offset:37888
	s_add_u32 s30, s28, 0x58000
	s_addc_u32 s31, s29, 0
	s_add_i32 m0, s60, 0x3000
	s_nop 0
	global_load_lds_dwordx4 v134, s[30:31]
	ds_read_b128 v[218:221], v157 offset:38912
	ds_read_b128 v[222:225], v157 offset:39936
	ds_read_b128 v[158:161], v155 offset:32768
	s_add_u32 s30, s28, 0x160000
	s_addc_u32 s31, s29, 0
	s_add_i32 m0, s60, 0x6000
	s_nop 0
	global_load_lds_dwordx4 v134, s[30:31]
	ds_read_b128 v[162:165], v155 offset:33792
	ds_read_b128 v[166:169], v155 offset:34816
	ds_read_b128 v[174:177], v155 offset:35840
	s_add_u32 s30, s28, 0x1b8000
	s_addc_u32 s31, s29, 0
	s_add_i32 m0, s60, 0x7000
	s_nop 0
	global_load_lds_dwordx4 v134, s[30:31]
	ds_read_b128 v[178:181], v155 offset:49152
	ds_read_b128 v[182:185], v155 offset:50176
	ds_read_b128 v[186:189], v155 offset:51200
	s_add_u32 s34, s28, 0x80
	s_addc_u32 s35, s29, 0
	s_add_i32 m0, s60, 0x8000
	s_nop 0
	global_load_lds_dwordx4 v130, s[34:35]
	ds_read_b128 v[190:193], v155 offset:52224
	ds_read_b128 v[226:229], v157 offset:49152
	ds_read_b128 v[230:233], v157 offset:50176
	s_add_u32 s30, s34, 0x58000
	s_addc_u32 s31, s35, 0
	s_add_i32 m0, s60, 0x9000
	s_nop 0
	global_load_lds_dwordx4 v130, s[30:31]
	ds_read_b128 v[234:237], v157 offset:51200
	ds_read_b128 v[238:241], v157 offset:52224
	ds_read_b128 v[242:245], v157 offset:53248
	s_add_u32 s30, s34, 0x160000
	s_addc_u32 s31, s35, 0
	s_add_i32 m0, s60, 0xc000
	s_nop 0
	global_load_lds_dwordx4 v130, s[30:31]
	ds_read_b128 v[246:249], v157 offset:54272
	ds_read_b128 v[250:253], v157 offset:55296
	ds_read_b128 v[142:145], v157 offset:56320
	s_add_u32 s30, s34, 0x1b8000
	s_addc_u32 s31, s35, 0
	s_add_i32 m0, s60, 0xd000
	s_nop 0
	global_load_lds_dwordx4 v130, s[30:31]
	s_add_u32 s28, s28, 0x80
	s_addc_u32 s29, s29, 0
	s_waitcnt vmcnt(8) lgkmcnt(0)
	s_barrier
	v_mfma_f32_16x16x32_bf16 v[126:129], v[158:161], v[194:197], v[126:129]
	v_mfma_f32_16x16x32_bf16 v[126:129], v[162:165], v[198:201], v[126:129]
	v_mfma_f32_16x16x32_bf16 v[122:125], v[174:177], v[198:201], v[122:125]
	v_mfma_f32_16x16x32_bf16 v[122:125], v[166:169], v[194:197], v[122:125]
	v_mfma_f32_16x16x32_bf16 v[114:117], v[178:181], v[194:197], v[114:117]
	v_mfma_f32_16x16x32_bf16 v[114:117], v[182:185], v[198:201], v[114:117]
	v_mfma_f32_16x16x32_bf16 v[106:109], v[190:193], v[198:201], v[106:109]
	v_mfma_f32_16x16x32_bf16 v[106:109], v[186:189], v[194:197], v[106:109]
	v_mfma_f32_16x16x32_bf16 v[90:93], v[186:189], v[202:205], v[90:93]
	v_mfma_f32_16x16x32_bf16 v[90:93], v[190:193], v[206:209], v[90:93]
	v_mfma_f32_16x16x32_bf16 v[98:101], v[182:185], v[206:209], v[98:101]
	v_mfma_f32_16x16x32_bf16 v[98:101], v[178:181], v[202:205], v[98:101]
	v_mfma_f32_16x16x32_bf16 v[110:113], v[166:169], v[202:205], v[110:113]
	v_mfma_f32_16x16x32_bf16 v[110:113], v[174:177], v[206:209], v[110:113]
	v_mfma_f32_16x16x32_bf16 v[118:121], v[162:165], v[206:209], v[118:121]
	v_mfma_f32_16x16x32_bf16 v[118:121], v[158:161], v[202:205], v[118:121]
	v_mfma_f32_16x16x32_bf16 v[102:105], v[158:161], v[210:213], v[102:105]
	v_mfma_f32_16x16x32_bf16 v[102:105], v[162:165], v[214:217], v[102:105]
	v_mfma_f32_16x16x32_bf16 v[94:97], v[174:177], v[214:217], v[94:97]
	v_mfma_f32_16x16x32_bf16 v[94:97], v[166:169], v[210:213], v[94:97]
	v_mfma_f32_16x16x32_bf16 v[82:85], v[178:181], v[210:213], v[82:85]
	v_mfma_f32_16x16x32_bf16 v[82:85], v[182:185], v[214:217], v[82:85]
	v_mfma_f32_16x16x32_bf16 v[74:77], v[190:193], v[214:217], v[74:77]
	v_mfma_f32_16x16x32_bf16 v[74:77], v[186:189], v[210:213], v[74:77]
	v_mfma_f32_16x16x32_bf16 v[66:69], v[186:189], v[218:221], v[66:69]
	v_mfma_f32_16x16x32_bf16 v[66:69], v[190:193], v[222:225], v[66:69]
	v_mfma_f32_16x16x32_bf16 v[70:73], v[182:185], v[222:225], v[70:73]
	v_mfma_f32_16x16x32_bf16 v[70:73], v[178:181], v[218:221], v[70:73]
	v_mfma_f32_16x16x32_bf16 v[78:81], v[166:169], v[218:221], v[78:81]
	v_mfma_f32_16x16x32_bf16 v[78:81], v[174:177], v[222:225], v[78:81]
	v_mfma_f32_16x16x32_bf16 v[86:89], v[162:165], v[222:225], v[86:89]
	v_mfma_f32_16x16x32_bf16 v[86:89], v[158:161], v[218:221], v[86:89]
	v_mfma_f32_16x16x32_bf16 v[62:65], v[158:161], v[226:229], v[62:65]
	v_mfma_f32_16x16x32_bf16 v[62:65], v[162:165], v[230:233], v[62:65]
	v_mfma_f32_16x16x32_bf16 v[58:61], v[174:177], v[230:233], v[58:61]
	v_mfma_f32_16x16x32_bf16 v[58:61], v[166:169], v[226:229], v[58:61]
	v_mfma_f32_16x16x32_bf16 v[50:53], v[178:181], v[226:229], v[50:53]
	v_mfma_f32_16x16x32_bf16 v[50:53], v[182:185], v[230:233], v[50:53]
	v_mfma_f32_16x16x32_bf16 v[42:45], v[190:193], v[230:233], v[42:45]
	v_mfma_f32_16x16x32_bf16 v[42:45], v[186:189], v[226:229], v[42:45]
	v_mfma_f32_16x16x32_bf16 v[26:29], v[186:189], v[234:237], v[26:29]
	v_mfma_f32_16x16x32_bf16 v[26:29], v[190:193], v[238:241], v[26:29]
	v_mfma_f32_16x16x32_bf16 v[34:37], v[182:185], v[238:241], v[34:37]
	v_mfma_f32_16x16x32_bf16 v[34:37], v[178:181], v[234:237], v[34:37]
	v_mfma_f32_16x16x32_bf16 v[46:49], v[166:169], v[234:237], v[46:49]
	v_mfma_f32_16x16x32_bf16 v[46:49], v[174:177], v[238:241], v[46:49]
	v_mfma_f32_16x16x32_bf16 v[54:57], v[162:165], v[238:241], v[54:57]
	v_mfma_f32_16x16x32_bf16 v[54:57], v[158:161], v[234:237], v[54:57]
	v_mfma_f32_16x16x32_bf16 v[38:41], v[158:161], v[242:245], v[38:41]
	v_mfma_f32_16x16x32_bf16 v[38:41], v[162:165], v[246:249], v[38:41]
	v_mfma_f32_16x16x32_bf16 v[30:33], v[174:177], v[246:249], v[30:33]
	v_mfma_f32_16x16x32_bf16 v[30:33], v[166:169], v[242:245], v[30:33]
	v_mfma_f32_16x16x32_bf16 v[18:21], v[178:181], v[242:245], v[18:21]
	v_mfma_f32_16x16x32_bf16 v[18:21], v[182:185], v[246:249], v[18:21]
	v_mfma_f32_16x16x32_bf16 v[10:13], v[190:193], v[246:249], v[10:13]
	v_mfma_f32_16x16x32_bf16 v[10:13], v[186:189], v[242:245], v[10:13]
	v_mfma_f32_16x16x32_bf16 v[2:5], v[186:189], v[250:253], v[2:5]
	v_mfma_f32_16x16x32_bf16 v[2:5], v[190:193], v[142:145], v[2:5]
	v_mfma_f32_16x16x32_bf16 v[6:9], v[182:185], v[142:145], v[6:9]
	v_mfma_f32_16x16x32_bf16 v[6:9], v[178:181], v[250:253], v[6:9]
	v_mfma_f32_16x16x32_bf16 v[14:17], v[166:169], v[250:253], v[14:17]
	v_mfma_f32_16x16x32_bf16 v[14:17], v[174:177], v[142:145], v[14:17]
	v_mfma_f32_16x16x32_bf16 v[22:25], v[162:165], v[142:145], v[22:25]
	v_mfma_f32_16x16x32_bf16 v[22:25], v[158:161], v[250:253], v[22:25]
	s_waitcnt vmcnt(0)
	s_barrier
	s_add_i32 s57, s57, 1
	s_cmp_lt_u32 s57, 44
	s_cbranch_scc1 .Lp9k_B_loop
.Lp9k_done:
	s_setprio 0
	v_mov_b64_e32 v[142:143], 0x200
	v_mov_b64_e32 v[144:145], 0x1ff
	s_and_b64 vcc, exec, s[14:15]
	s_cbranch_vccz .LBB0_951
	s_barrier
